# v29 + swiglu phases: the pre-epilogue alignment barrier of waves 0-3 moved below the epilogue prologue (bias copies, rstd) so that they work while waves 4-7 finish their last MFMA phase
# speedup vs baseline: 1.0030x; 1.0022x over previous
; #define PG8_STAGE(bufoff, gbase, voff) do { _Pragma("unroll") for (int _i = 0; _i < 2; ++_i) \
;         __builtin_amdgcn_global_load_lds((const unsigned*)((const char*)(gbase) + (voff)[_i]), (LAS unsigned*)(lds + (bufoff) + ldsw + _i * 8192), 16, 0, 0); } while (0)
; #define PG8_LDA(dst, b, h) do { _Pragma("unroll") for (int m = 0; m < 4; ++m) _Pragma("unroll") for (int k = 0; k < 2; ++k) dst[m][k] = *(const LAS bf16x8*)(lds + PG8_SA(b, h) + aoff + m * 2048 + k * 1024); } while (0)
; #define PG8_LDB(dst, b, h) do { _Pragma("unroll") for (int n = 0; n < 2; ++n) _Pragma("unroll") for (int k = 0; k < 2; ++k) dst[n][k] = *(const LAS bf16x8*)(lds + PG8_SB(b, h) + boff + n * 2048 + k * 1024); } while (0)
; #define PG8_MMA(ai, bj, At, Bt) do { __builtin_amdgcn_s_setprio(1); _Pragma("unroll") for (int m = 0; m < 4; ++m) _Pragma("unroll") for (int n = 0; n < 2; ++n) _Pragma("unroll") for (int k = 0; k < 2; ++k) \
;         acc[ai][bj][m][n] = __builtin_amdgcn_mfma_f32_16x16x32_bf16(Bt[n][k], At[m][k], acc[ai][bj][m][n], 0, 0, 0); __builtin_amdgcn_s_setprio(0); } while (0)
; #define PG8_WAIT_V(n) asm volatile("s_waitcnt vmcnt(" #n ")" ::: "memory")
; #define PG8_WAIT_L(n) asm volatile("s_waitcnt lgkmcnt(" #n ")" ::: "memory")
; #define PG8_BAR __builtin_amdgcn_s_barrier()
; #define PG8_SCHED __builtin_amdgcn_sched_barrier(0)
; template <class Epi, class Sched, bool ALIGN_EPI = false, bool SP2 = false>
; __device__ __forceinline__ void gemm_phase(LAS unsigned char* lds, const Gemm g, const Sched& S, const Epi& E) {
;     ...
;             PG8_LDB(B0, 0, 0); PG8_LDB(B1, 0, 1); PG8_SCHED; PG8_LDA(At, 0, 0); PG8_STAGE(PG8_SA(1, 1), a1 + hstep, voffA);
;             PG8_WAIT_V(8); PG8_WAIT_L(0); PG8_BAR; PG8_MMA(0, 0, At, B0); PG8_MMA(0, 1, At, B1); PG8_BAR; PG8_SCHED;
;             PG8_LDA(At, 0, 1); PG8_STAGE(PG8_SB(0, 0), b2, voffB); PG8_STAGE(PG8_SB(0, 1), b2 + hstepB, voffB); PG8_STAGE(PG8_SA(0, 0), a2, voffA);
;             PG8_WAIT_V(8); PG8_WAIT_L(0); PG8_BAR; PG8_MMA(1, 0, At, B0); PG8_MMA(1, 1, At, B1); PG8_BAR; PG8_SCHED;
.LBB0_188:
	ds_read_b128 v[66:69], v174
	ds_read_b128 v[70:73], v174 offset:1024
	ds_read_b128 v[74:77], v174 offset:2048
	ds_read_b128 v[78:81], v174 offset:3072
	ds_read_b128 v[162:165], v175
	ds_read_b128 v[182:185], v175 offset:1024
	ds_read_b128 v[186:189], v175 offset:2048
	ds_read_b128 v[190:193], v175 offset:3072
	s_add_u32 s20, s16, 0xfff80080
	s_addc_u32 s21, s17, -1
	s_cmp_eq_u32 s19, 28
	s_cselect_b32 s53, s3, s21
	s_cselect_b32 s52, s12, s20
	s_cselect_b32 s51, s13, s18
	s_cselect_b32 s50, s14, s15
	s_add_i32 m0, s33, 0xc000
	ds_read_b128 v[194:197], v176
	ds_read_b128 v[198:201], v176 offset:1024
	ds_read_b128 v[202:205], v176 offset:2048
	ds_read_b128 v[206:209], v176 offset:3072
	ds_read_b128 v[210:213], v176 offset:4096
	ds_read_b128 v[214:217], v176 offset:5120
	ds_read_b128 v[218:221], v176 offset:6144
	ds_read_b128 v[222:225], v176 offset:7168
	global_load_lds_dwordx4 v154, s[16:17]
	s_add_i32 m0, s33, 0xe000
	s_nop 0
	global_load_lds_dwordx4 v156, s[16:17]
	s_waitcnt vmcnt(8)
	s_waitcnt lgkmcnt(0)
	s_barrier
	s_waitcnt lgkmcnt(0)
	v_mfma_f32_16x16x32_bf16 v[142:145], v[66:69], v[194:197], v[142:145]
	v_mfma_f32_16x16x32_bf16 v[138:141], v[74:77], v[194:197], v[138:141]
	v_mfma_f32_16x16x32_bf16 v[126:129], v[66:69], v[202:205], v[126:129]
	v_mfma_f32_16x16x32_bf16 v[122:125], v[74:77], v[202:205], v[122:125]
	v_mfma_f32_16x16x32_bf16 v[110:113], v[66:69], v[210:213], v[110:113]
	v_mfma_f32_16x16x32_bf16 v[106:109], v[74:77], v[210:213], v[106:109]
	v_mfma_f32_16x16x32_bf16 v[94:97], v[66:69], v[218:221], v[94:97]
	v_mfma_f32_16x16x32_bf16 v[90:93], v[74:77], v[218:221], v[90:93]
	v_mfma_f32_16x16x32_bf16 v[142:145], v[70:73], v[198:201], v[142:145]
	v_mfma_f32_16x16x32_bf16 v[138:141], v[78:81], v[198:201], v[138:141]
	v_mfma_f32_16x16x32_bf16 v[126:129], v[70:73], v[206:209], v[126:129]
	v_mfma_f32_16x16x32_bf16 v[122:125], v[78:81], v[206:209], v[122:125]
	v_mfma_f32_16x16x32_bf16 v[110:113], v[70:73], v[214:217], v[110:113]
	v_mfma_f32_16x16x32_bf16 v[106:109], v[78:81], v[214:217], v[106:109]
	v_mfma_f32_16x16x32_bf16 v[94:97], v[70:73], v[222:225], v[94:97]
	v_mfma_f32_16x16x32_bf16 v[90:93], v[78:81], v[222:225], v[90:93]
	v_mfma_f32_16x16x32_bf16 v[134:137], v[162:165], v[194:197], v[134:137]
	v_mfma_f32_16x16x32_bf16 v[130:133], v[186:189], v[194:197], v[130:133]
	v_mfma_f32_16x16x32_bf16 v[118:121], v[162:165], v[202:205], v[118:121]
	v_mfma_f32_16x16x32_bf16 v[114:117], v[186:189], v[202:205], v[114:117]
	v_mfma_f32_16x16x32_bf16 v[102:105], v[162:165], v[210:213], v[102:105]
	v_mfma_f32_16x16x32_bf16 v[98:101], v[186:189], v[210:213], v[98:101]
	v_mfma_f32_16x16x32_bf16 v[86:89], v[162:165], v[218:221], v[86:89]
	v_mfma_f32_16x16x32_bf16 v[82:85], v[186:189], v[218:221], v[82:85]
	v_mfma_f32_16x16x32_bf16 v[134:137], v[182:185], v[198:201], v[134:137]
	v_mfma_f32_16x16x32_bf16 v[130:133], v[190:193], v[198:201], v[130:133]
	v_mfma_f32_16x16x32_bf16 v[118:121], v[182:185], v[206:209], v[118:121]
	v_mfma_f32_16x16x32_bf16 v[114:117], v[190:193], v[206:209], v[114:117]
	v_mfma_f32_16x16x32_bf16 v[102:105], v[182:185], v[214:217], v[102:105]
	v_mfma_f32_16x16x32_bf16 v[98:101], v[190:193], v[214:217], v[98:101]
	v_mfma_f32_16x16x32_bf16 v[86:89], v[182:185], v[222:225], v[86:89]
	v_mfma_f32_16x16x32_bf16 v[82:85], v[190:193], v[222:225], v[82:85]
	s_barrier
	s_add_i32 s20, s57, s27
	s_mov_b32 m0, s20
	ds_read_b128 v[194:197], v176 offset:16384
	ds_read_b128 v[198:201], v176 offset:17408
	ds_read_b128 v[202:205], v176 offset:18432
	ds_read_b128 v[206:209], v176 offset:19456
	ds_read_b128 v[210:213], v176 offset:20480
	ds_read_b128 v[214:217], v176 offset:21504
	ds_read_b128 v[218:221], v176 offset:22528
	ds_read_b128 v[222:225], v176 offset:23552
	global_load_lds_dwordx4 v150, s[50:51]
	s_add_i32 m0, s20, 0x2000
	s_add_u32 s20, s50, 0x80000
	s_addc_u32 s21, s51, 0
	s_add_i32 s22, s58, s27
	global_load_lds_dwordx4 v146, s[50:51]
	s_mov_b32 m0, s22
	s_nop 0
	global_load_lds_dwordx4 v150, s[20:21]
	s_add_i32 m0, s22, 0x2000
	s_nop 0
	global_load_lds_dwordx4 v146, s[20:21]
	s_mov_b32 m0, s33
	s_nop 0
	global_load_lds_dwordx4 v152, s[52:53]
	s_mov_b32 m0, s34
	s_nop 0
	global_load_lds_dwordx4 v148, s[52:53]
	s_waitcnt vmcnt(8)
	s_waitcnt lgkmcnt(0)
	s_barrier
	s_waitcnt lgkmcnt(0)
	v_mfma_f32_16x16x32_bf16 v[62:65], v[66:69], v[194:197], v[62:65]
	v_mfma_f32_16x16x32_bf16 v[58:61], v[74:77], v[194:197], v[58:61]
	v_mfma_f32_16x16x32_bf16 v[46:49], v[66:69], v[202:205], v[46:49]
	v_mfma_f32_16x16x32_bf16 v[42:45], v[74:77], v[202:205], v[42:45]
	v_mfma_f32_16x16x32_bf16 v[30:33], v[66:69], v[210:213], v[30:33]
	v_mfma_f32_16x16x32_bf16 v[26:29], v[74:77], v[210:213], v[26:29]
	v_mfma_f32_16x16x32_bf16 v[14:17], v[66:69], v[218:221], v[14:17]
	v_mfma_f32_16x16x32_bf16 v[10:13], v[74:77], v[218:221], v[10:13]
	v_mfma_f32_16x16x32_bf16 v[62:65], v[70:73], v[198:201], v[62:65]
	v_mfma_f32_16x16x32_bf16 v[58:61], v[78:81], v[198:201], v[58:61]
	v_mfma_f32_16x16x32_bf16 v[46:49], v[70:73], v[206:209], v[46:49]
	v_mfma_f32_16x16x32_bf16 v[42:45], v[78:81], v[206:209], v[42:45]
	v_mfma_f32_16x16x32_bf16 v[30:33], v[70:73], v[214:217], v[30:33]
	v_mfma_f32_16x16x32_bf16 v[26:29], v[78:81], v[214:217], v[26:29]
	v_mfma_f32_16x16x32_bf16 v[14:17], v[70:73], v[222:225], v[14:17]
	v_mfma_f32_16x16x32_bf16 v[10:13], v[78:81], v[222:225], v[10:13]
	v_mfma_f32_16x16x32_bf16 v[54:57], v[162:165], v[194:197], v[54:57]
	v_mfma_f32_16x16x32_bf16 v[50:53], v[186:189], v[194:197], v[50:53]
	v_mfma_f32_16x16x32_bf16 v[38:41], v[162:165], v[202:205], v[38:41]
	v_mfma_f32_16x16x32_bf16 v[34:37], v[186:189], v[202:205], v[34:37]
	v_mfma_f32_16x16x32_bf16 v[22:25], v[162:165], v[210:213], v[22:25]
	v_mfma_f32_16x16x32_bf16 v[18:21], v[186:189], v[210:213], v[18:21]
	v_mfma_f32_16x16x32_bf16 v[6:9], v[162:165], v[218:221], v[6:9]
	v_mfma_f32_16x16x32_bf16 v[2:5], v[186:189], v[218:221], v[2:5]
	v_mfma_f32_16x16x32_bf16 v[54:57], v[182:185], v[198:201], v[54:57]
	v_mfma_f32_16x16x32_bf16 v[50:53], v[190:193], v[198:201], v[50:53]
	v_mfma_f32_16x16x32_bf16 v[38:41], v[182:185], v[206:209], v[38:41]
	v_mfma_f32_16x16x32_bf16 v[34:37], v[190:193], v[206:209], v[34:37]
	v_mfma_f32_16x16x32_bf16 v[22:25], v[182:185], v[214:217], v[22:25]
	v_mfma_f32_16x16x32_bf16 v[18:21], v[190:193], v[214:217], v[18:21]
	v_mfma_f32_16x16x32_bf16 v[6:9], v[182:185], v[222:225], v[6:9]
	v_mfma_f32_16x16x32_bf16 v[2:5], v[190:193], v[222:225], v[2:5]
	s_barrier
; #define PG8_STAGE(bufoff, gbase, voff) do { _Pragma("unroll") for (int _i = 0; _i < 2; ++_i) \
;         __builtin_amdgcn_global_load_lds((const unsigned*)((const char*)(gbase) + (voff)[_i]), (LAS unsigned*)(lds + (bufoff) + ldsw + _i * 8192), 16, 0, 0); } while (0)
; #define PG8_LDA(dst, b, h) do { _Pragma("unroll") for (int m = 0; m < 4; ++m) _Pragma("unroll") for (int k = 0; k < 2; ++k) dst[m][k] = *(const LAS bf16x8*)(lds + PG8_SA(b, h) + aoff + m * 2048 + k * 1024); } while (0)
; #define PG8_LDB(dst, b, h) do { _Pragma("unroll") for (int n = 0; n < 2; ++n) _Pragma("unroll") for (int k = 0; k < 2; ++k) dst[n][k] = *(const LAS bf16x8*)(lds + PG8_SB(b, h) + boff + n * 2048 + k * 1024); } while (0)
; #define PG8_MMA(ai, bj, At, Bt) do { __builtin_amdgcn_s_setprio(1); _Pragma("unroll") for (int m = 0; m < 4; ++m) _Pragma("unroll") for (int n = 0; n < 2; ++n) _Pragma("unroll") for (int k = 0; k < 2; ++k) \
;         acc[ai][bj][m][n] = __builtin_amdgcn_mfma_f32_16x16x32_bf16(Bt[n][k], At[m][k], acc[ai][bj][m][n], 0, 0, 0); __builtin_amdgcn_s_setprio(0); } while (0)
; #define PG8_WAIT_V(n) asm volatile("s_waitcnt vmcnt(" #n ")" ::: "memory")
; #define PG8_WAIT_L(n) asm volatile("s_waitcnt lgkmcnt(" #n ")" ::: "memory")
; #define PG8_BAR __builtin_amdgcn_s_barrier()
; #define PG8_SCHED __builtin_amdgcn_sched_barrier(0)
; template <class Epi, class Sched, bool ALIGN_EPI = false, bool SP2 = false>
; __device__ __forceinline__ void gemm_phase(LAS unsigned char* lds, const Gemm g, const Sched& S, const Epi& E) {
;     ...
;             PG8_LDB(B0, 1, 0); PG8_LDB(B1, 1, 1); PG8_SCHED; PG8_LDA(At, 1, 0); PG8_STAGE(PG8_SA(0, 1), a2 + hstep, voffA);
;             PG8_WAIT_V(8); PG8_WAIT_L(0); PG8_BAR; PG8_MMA(0, 0, At, B0); PG8_MMA(0, 1, At, B1); PG8_BAR; PG8_SCHED;
;             PG8_LDA(At, 1, 1); PG8_STAGE(PG8_SB(1, 0), b3, voffB); PG8_STAGE(PG8_SB(1, 1), b3 + hstepB, voffB); PG8_STAGE(PG8_SA(1, 0), a3, voffA);
;             PG8_WAIT_V(8); PG8_WAIT_L(0); PG8_BAR; PG8_MMA(1, 0, At, B0); PG8_MMA(1, 1, At, B1); PG8_BAR; PG8_SCHED;
;     ...
;         if constexpr (ALIGN_EPI) { if (wr == 0) PG8_BAR; }
	s_add_i32 s22, 0, 0x18000
	s_add_i32 s23, 0, 0x1c000
	v_add_u32_e32 v78, s22, v170
	v_add_u32_e32 v168, s23, v170
	ds_read_b128 v[66:69], v78
	ds_read_b128 v[70:73], v78 offset:1024
	ds_read_b128 v[74:77], v78 offset:2048
	ds_read_b128 v[78:81], v78 offset:3072
	ds_read_b128 v[162:165], v168
	ds_read_b128 v[182:185], v168 offset:1024
	ds_read_b128 v[186:189], v168 offset:2048
	ds_read_b128 v[190:193], v168 offset:3072
	s_add_u32 s20, s52, 0x80000
	s_addc_u32 s21, s53, 0
	s_mov_b32 m0, s35
	ds_read_b128 v[194:197], v176 offset:32768
	ds_read_b128 v[198:201], v176 offset:33792
	ds_read_b128 v[202:205], v176 offset:34816
	ds_read_b128 v[206:209], v176 offset:35840
	ds_read_b128 v[210:213], v176 offset:36864
	ds_read_b128 v[214:217], v176 offset:37888
	ds_read_b128 v[218:221], v176 offset:38912
	ds_read_b128 v[222:225], v176 offset:39936
	global_load_lds_dwordx4 v152, s[20:21]
	s_mov_b32 m0, s36
	s_nop 0
	global_load_lds_dwordx4 v148, s[20:21]
	s_waitcnt vmcnt(8)
	s_waitcnt lgkmcnt(0)
	s_barrier
	s_waitcnt lgkmcnt(0)
	v_mfma_f32_16x16x32_bf16 v[142:145], v[66:69], v[194:197], v[142:145]
	v_mfma_f32_16x16x32_bf16 v[138:141], v[74:77], v[194:197], v[138:141]
	v_mfma_f32_16x16x32_bf16 v[126:129], v[66:69], v[202:205], v[126:129]
	v_mfma_f32_16x16x32_bf16 v[122:125], v[74:77], v[202:205], v[122:125]
	v_mfma_f32_16x16x32_bf16 v[110:113], v[66:69], v[210:213], v[110:113]
	v_mfma_f32_16x16x32_bf16 v[106:109], v[74:77], v[210:213], v[106:109]
	v_mfma_f32_16x16x32_bf16 v[94:97], v[66:69], v[218:221], v[94:97]
	v_mfma_f32_16x16x32_bf16 v[90:93], v[74:77], v[218:221], v[90:93]
	v_mfma_f32_16x16x32_bf16 v[142:145], v[70:73], v[198:201], v[142:145]
	v_mfma_f32_16x16x32_bf16 v[138:141], v[78:81], v[198:201], v[138:141]
	v_mfma_f32_16x16x32_bf16 v[126:129], v[70:73], v[206:209], v[126:129]
	v_mfma_f32_16x16x32_bf16 v[122:125], v[78:81], v[206:209], v[122:125]
	v_mfma_f32_16x16x32_bf16 v[110:113], v[70:73], v[214:217], v[110:113]
	v_mfma_f32_16x16x32_bf16 v[106:109], v[78:81], v[214:217], v[106:109]
	v_mfma_f32_16x16x32_bf16 v[94:97], v[70:73], v[222:225], v[94:97]
	v_mfma_f32_16x16x32_bf16 v[90:93], v[78:81], v[222:225], v[90:93]
	v_mfma_f32_16x16x32_bf16 v[134:137], v[162:165], v[194:197], v[134:137]
	v_mfma_f32_16x16x32_bf16 v[130:133], v[186:189], v[194:197], v[130:133]
	v_mfma_f32_16x16x32_bf16 v[118:121], v[162:165], v[202:205], v[118:121]
	v_mfma_f32_16x16x32_bf16 v[114:117], v[186:189], v[202:205], v[114:117]
	v_mfma_f32_16x16x32_bf16 v[102:105], v[162:165], v[210:213], v[102:105]
	v_mfma_f32_16x16x32_bf16 v[98:101], v[186:189], v[210:213], v[98:101]
	v_mfma_f32_16x16x32_bf16 v[86:89], v[162:165], v[218:221], v[86:89]
	v_mfma_f32_16x16x32_bf16 v[82:85], v[186:189], v[218:221], v[82:85]
	v_mfma_f32_16x16x32_bf16 v[134:137], v[182:185], v[198:201], v[134:137]
	v_mfma_f32_16x16x32_bf16 v[130:133], v[190:193], v[198:201], v[130:133]
	v_mfma_f32_16x16x32_bf16 v[118:121], v[182:185], v[206:209], v[118:121]
	v_mfma_f32_16x16x32_bf16 v[114:117], v[190:193], v[206:209], v[114:117]
	v_mfma_f32_16x16x32_bf16 v[102:105], v[182:185], v[214:217], v[102:105]
	v_mfma_f32_16x16x32_bf16 v[98:101], v[190:193], v[214:217], v[98:101]
	v_mfma_f32_16x16x32_bf16 v[86:89], v[182:185], v[222:225], v[86:89]
	v_mfma_f32_16x16x32_bf16 v[82:85], v[190:193], v[222:225], v[82:85]
	s_barrier
	s_add_u32 s98, s50, 0x80
	s_addc_u32 s99, s51, 0
	s_add_u32 s100, s52, 0x80
	s_addc_u32 s101, s53, 0
	s_add_i32 s20, s22, s27
	s_mov_b32 m0, s20
	ds_read_b128 v[194:197], v176 offset:49152
	ds_read_b128 v[198:201], v176 offset:50176
	ds_read_b128 v[202:205], v176 offset:51200
	ds_read_b128 v[206:209], v176 offset:52224
	ds_read_b128 v[210:213], v176 offset:53248
	ds_read_b128 v[214:217], v176 offset:54272
	ds_read_b128 v[218:221], v176 offset:55296
	ds_read_b128 v[222:225], v176 offset:56320
	global_load_lds_dwordx4 v150, s[98:99]
	s_add_i32 m0, s20, 0x2000
	s_add_u32 s20, s50, 0x80080
	s_addc_u32 s21, s51, 0
	s_add_i32 s22, s23, s27
	global_load_lds_dwordx4 v146, s[98:99]
	s_mov_b32 m0, s22
	s_nop 0
	global_load_lds_dwordx4 v150, s[20:21]
	s_add_i32 m0, s22, 0x2000
	s_nop 0
	global_load_lds_dwordx4 v146, s[20:21]
	s_mov_b32 m0, s55
	s_nop 0
	global_load_lds_dwordx4 v152, s[100:101]
	s_mov_b32 m0, s56
	s_nop 0
	global_load_lds_dwordx4 v148, s[100:101]
	s_waitcnt vmcnt(8)
	s_waitcnt lgkmcnt(0)
	s_barrier
	s_waitcnt lgkmcnt(0)
	v_mfma_f32_16x16x32_bf16 v[62:65], v[66:69], v[194:197], v[62:65]
	v_mfma_f32_16x16x32_bf16 v[58:61], v[74:77], v[194:197], v[58:61]
	v_mfma_f32_16x16x32_bf16 v[46:49], v[66:69], v[202:205], v[46:49]
	v_mfma_f32_16x16x32_bf16 v[42:45], v[74:77], v[202:205], v[42:45]
	v_mfma_f32_16x16x32_bf16 v[30:33], v[66:69], v[210:213], v[30:33]
	v_mfma_f32_16x16x32_bf16 v[26:29], v[74:77], v[210:213], v[26:29]
	v_mfma_f32_16x16x32_bf16 v[14:17], v[66:69], v[218:221], v[14:17]
	v_mfma_f32_16x16x32_bf16 v[10:13], v[74:77], v[218:221], v[10:13]
	v_mfma_f32_16x16x32_bf16 v[62:65], v[70:73], v[198:201], v[62:65]
	v_mfma_f32_16x16x32_bf16 v[58:61], v[78:81], v[198:201], v[58:61]
	v_mfma_f32_16x16x32_bf16 v[46:49], v[70:73], v[206:209], v[46:49]
	v_mfma_f32_16x16x32_bf16 v[42:45], v[78:81], v[206:209], v[42:45]
	v_mfma_f32_16x16x32_bf16 v[30:33], v[70:73], v[214:217], v[30:33]
	v_mfma_f32_16x16x32_bf16 v[26:29], v[78:81], v[214:217], v[26:29]
	v_mfma_f32_16x16x32_bf16 v[14:17], v[70:73], v[222:225], v[14:17]
	v_mfma_f32_16x16x32_bf16 v[10:13], v[78:81], v[222:225], v[10:13]
	v_mfma_f32_16x16x32_bf16 v[54:57], v[162:165], v[194:197], v[54:57]
	v_mfma_f32_16x16x32_bf16 v[50:53], v[186:189], v[194:197], v[50:53]
	v_mfma_f32_16x16x32_bf16 v[38:41], v[162:165], v[202:205], v[38:41]
	v_mfma_f32_16x16x32_bf16 v[34:37], v[186:189], v[202:205], v[34:37]
	v_mfma_f32_16x16x32_bf16 v[22:25], v[162:165], v[210:213], v[22:25]
	v_mfma_f32_16x16x32_bf16 v[18:21], v[186:189], v[210:213], v[18:21]
	v_mfma_f32_16x16x32_bf16 v[6:9], v[162:165], v[218:221], v[6:9]
	v_mfma_f32_16x16x32_bf16 v[2:5], v[186:189], v[218:221], v[2:5]
	v_mfma_f32_16x16x32_bf16 v[54:57], v[182:185], v[198:201], v[54:57]
	v_mfma_f32_16x16x32_bf16 v[50:53], v[190:193], v[198:201], v[50:53]
	v_mfma_f32_16x16x32_bf16 v[38:41], v[182:185], v[206:209], v[38:41]
	v_mfma_f32_16x16x32_bf16 v[34:37], v[190:193], v[206:209], v[34:37]
	v_mfma_f32_16x16x32_bf16 v[22:25], v[182:185], v[214:217], v[22:25]
	v_mfma_f32_16x16x32_bf16 v[18:21], v[190:193], v[214:217], v[18:21]
	v_mfma_f32_16x16x32_bf16 v[6:9], v[182:185], v[222:225], v[6:9]
	v_mfma_f32_16x16x32_bf16 v[2:5], v[190:193], v[222:225], v[2:5]
	s_barrier
	s_add_i32 s19, s19, 2
	s_add_u32 s16, s16, 0x100
	s_addc_u32 s17, s17, 0
	s_add_u32 s15, s15, 0x100
	s_addc_u32 s18, s18, 0
	s_cmp_gt_u32 s19, 29
	s_cbranch_scc0 .LBB0_188
	s_setprio 0
	s_cmpk_gt_i32 s2, 0x7f
	s_mov_b64 s[16:17], 0xb000
	s_cbranch_scc1 .LBB0_193
	s_ashr_i32 s3, s2, 5
	s_mul_hi_i32 s17, s3, 0x2c00
	s_mul_i32 s16, s3, 0x2c00
; __device__ __forceinline__ unsigned cvt_pk_bf16(float lo, float hi) { unsigned r; asm volatile("v_cvt_pk_bf16_f32 %0, %1, %2" : "=v"(r) : "v"(lo), "v"(hi)); return r; }
; __device__ __forceinline__ float silu_mul(float a, float b) { return a * b * __builtin_amdgcn_rcpf(1.0f + __builtin_amdgcn_exp2f(-a * LOG2E)); }
; __device__ __forceinline__ float row_rstd(const float* ss, int row) { return 1.0f / sqrtf(ss[row] * (1.0f / DM) + 1e-6f); }
;     __device__ __forceinline__ void operator()(const f32x4 (&acc)[2][2][4][2], const Unit& u, int wr, int wc, int fr, int fq) const {
;         const int row0 = u.pm * BM + wr * 64 + fr, col0 = u.pn * HALF + wc * 32 + 8 * fq;
;         const int s = (u.pm < ML / BM) ? (u.pm >> 5) : 4;
;         const float* bp = bias + (size_t)s * BIAS_N + u.pn * BM + wc * 32 + 8 * fq;
;         const f32x4 ba0 = *(const f32x4*)bp, ba1 = *(const f32x4*)(bp + 4), bb0 = *(const f32x4*)(bp + HALF), bb1 = *(const f32x4*)(bp + HALF + 4);
;         const int lane = fq * 16 + fr;
;         const float rsl0 = row_rstd(ss, u.pm * BM + wr * 64 + lane), rsl1 = row_rstd(ss, u.pm * BM + HALF + wr * 64 + lane);
; #pragma unroll
;         for (int ai = 0; ai < 2; ++ai)
; #pragma unroll
;             for (int m = 0; m < 4; ++m) { const int row = row0 + ai * HALF + m * 16; const float rs = __shfl(ai ? rsl1 : rsl0, m * 16 + fr); bf16_t* rowp = O + (size_t)row * DFF + col0;
;                 const f32x4 a0 = acc[ai][0][m][0] * rs + ba0, a1 = acc[ai][0][m][1] * rs + ba1, b0 = acc[ai][1][m][0] * rs + bb0, b1 = acc[ai][1][m][1] * rs + bb1;
;                 u32x4 w; w.x = cvt_pk_bf16(silu_mul(a0[0], b0[0]), silu_mul(a0[1], b0[1])); w.y = cvt_pk_bf16(silu_mul(a0[2], b0[2]), silu_mul(a0[3], b0[3]));
;                 w.z = cvt_pk_bf16(silu_mul(a1[0], b1[0]), silu_mul(a1[1], b1[1])); w.w = cvt_pk_bf16(silu_mul(a1[2], b1[2]), silu_mul(a1[3], b1[3]));
;                 *(u32x4*)rowp = w; }
.LBB0_193:
	s_lshl_b32 s2, s2, 8
	s_add_i32 s12, s2, s54
	s_lshl_b64 s[2:3], s[16:17], 2
	s_add_u32 s13, s68, s2
	s_addc_u32 s14, s69, s3
	s_lshl_b32 s2, s0, 8
	s_ashr_i32 s3, s2, 31
	s_lshl_b64 s[2:3], s[2:3], 2
	v_lshl_or_b32 v164, s0, 7, v173
	s_add_u32 s0, s13, s2
	s_addc_u32 s3, s14, s3
	v_or_b32_e32 v162, s12, v171
	s_add_u32 s2, s0, s60
	v_ashrrev_i32_e32 v163, 31, v162
	s_addc_u32 s3, s3, 0
	v_lshl_add_u64 v[162:163], v[162:163], 2, s[8:9]
	v_mov_b32_e32 v74, v234
	v_mov_b32_e32 v75, v235
	v_mov_b32_e32 v76, v236
	v_mov_b32_e32 v77, v237
	v_mov_b32_e32 v78, v238
	v_mov_b32_e32 v79, v239
	v_mov_b32_e32 v80, v240
	v_mov_b32_e32 v81, v241
	v_mov_b32_e32 v66, v242
	v_mov_b32_e32 v67, v243
	v_mov_b32_e32 v68, v244
	v_mov_b32_e32 v69, v245
	v_mov_b32_e32 v70, v246
	v_mov_b32_e32 v71, v247
	v_mov_b32_e32 v72, v248
	v_mov_b32_e32 v73, v249
	v_or_b32_e32 v181, s12, v169
	v_mov_b32_e32 v162, v250
	s_waitcnt vmcnt(0)
	v_fmamk_f32 v162, v162, 0x3a000000, v178
	v_cmp_gt_f32_e32 vcc, s61, v162
	v_mul_f32_e32 v163, 0x4f800000, v162
	s_nop 0
	v_cndmask_b32_e32 v162, v162, v163, vcc
	v_sqrt_f32_e32 v163, v162
	s_nop 0
	v_add_u32_e32 v165, -1, v163
	v_fma_f32 v166, -v165, v163, v162
	v_cmp_ge_f32_e64 s[2:3], 0, v166
	v_add_u32_e32 v166, 1, v163
	s_nop 0
	v_cndmask_b32_e64 v165, v163, v165, s[2:3]
	v_fma_f32 v163, -v166, v163, v162
	v_cmp_lt_f32_e64 s[2:3], 0, v163
	s_nop 1
	v_cndmask_b32_e64 v163, v165, v166, s[2:3]
	v_mul_f32_e32 v165, 0x37800000, v163
	v_cndmask_b32_e32 v163, v163, v165, vcc
	v_cmp_class_f32_e32 vcc, v162, v179
	s_nop 1
	v_cndmask_b32_e32 v166, v163, v162, vcc
	v_add_u32_e32 v162, s12, v172
	v_ashrrev_i32_e32 v163, 31, v162
	v_lshl_add_u64 v[162:163], v[162:163], 2, s[8:9]
	v_mov_b32_e32 v162, v251
	v_fmamk_f32 v162, v162, 0x3a000000, v178
	v_cmp_gt_f32_e32 vcc, s61, v162
	v_mul_f32_e32 v163, 0x4f800000, v162
	s_nop 0
	v_cndmask_b32_e32 v162, v162, v163, vcc
	v_sqrt_f32_e32 v163, v162
	s_nop 0
	v_add_u32_e32 v165, -1, v163
	v_fma_f32 v167, -v165, v163, v162
	v_cmp_ge_f32_e64 s[2:3], 0, v167
	v_add_u32_e32 v167, 1, v163
	s_nop 0
	v_cndmask_b32_e64 v165, v163, v165, s[2:3]
	v_fma_f32 v163, -v167, v163, v162
	v_cmp_lt_f32_e64 s[2:3], 0, v163
	s_nop 1
	v_cndmask_b32_e64 v163, v165, v167, s[2:3]
	v_mul_f32_e32 v165, 0x37800000, v163
	v_cndmask_b32_e32 v163, v163, v165, vcc
	v_cmp_class_f32_e32 vcc, v162, v179
	v_ashrrev_i32_e32 v165, 31, v164
	v_lshlrev_b64 v[164:165], 1, v[164:165]
	v_cndmask_b32_e32 v182, v163, v162, vcc
	v_div_scale_f32 v162, s[2:3], v166, v166, 1.0
	v_rcp_f32_e32 v163, v162
	s_nop 0
	v_fma_f32 v167, -v162, v163, 1.0
	v_fmac_f32_e32 v163, v167, v163
	v_div_scale_f32 v167, vcc, 1.0, v166, 1.0
	v_mul_f32_e32 v168, v167, v163
	v_fma_f32 v183, -v162, v168, v167
	v_fmac_f32_e32 v168, v183, v163
	v_fma_f32 v162, -v162, v168, v167
	v_div_fmas_f32 v162, v162, v163, v168
	v_div_fixup_f32 v183, v162, v166, 1.0
	s_and_b64 vcc, exec, s[40:41]
	s_cbranch_vccz .Lalign_191
	s_barrier
.Lalign_191:
	s_mov_b32 s100, 0xbfb8aa3b
	ds_bpermute_b32 v242, v180, v183
	ds_bpermute_b32 v244, v180, v183 offset:64
	ds_bpermute_b32 v246, v180, v183 offset:128
	ds_bpermute_b32 v248, v180, v183 offset:192
	v_mov_b64_e32 v[162:163], s[96:97]
	v_mad_i64_i32 v[166:167], s[2:3], v181, s59, v[162:163]
	v_lshl_add_u64 v[166:167], v[166:167], 0, v[164:165]
	s_waitcnt lgkmcnt(0)
	v_pk_fma_f32 v[142:143], v[142:143], v[242:243], v[78:79] op_sel_hi:[1,0,1]
	v_pk_fma_f32 v[144:145], v[144:145], v[242:243], v[80:81] op_sel_hi:[1,0,1]
	v_pk_fma_f32 v[134:135], v[134:135], v[242:243], v[70:71] op_sel_hi:[1,0,1]
	v_pk_fma_f32 v[136:137], v[136:137], v[242:243], v[72:73] op_sel_hi:[1,0,1]
	v_pk_fma_f32 v[138:139], v[138:139], v[242:243], v[74:75] op_sel_hi:[1,0,1]
	v_pk_fma_f32 v[140:141], v[140:141], v[242:243], v[76:77] op_sel_hi:[1,0,1]
	v_pk_fma_f32 v[130:131], v[130:131], v[242:243], v[66:67] op_sel_hi:[1,0,1]
	v_pk_fma_f32 v[132:133], v[132:133], v[242:243], v[68:69] op_sel_hi:[1,0,1]
	v_pk_mul_f32 v[234:235], v[142:143], s[100:101] op_sel_hi:[1,0]
	v_pk_mul_f32 v[236:237], v[144:145], s[100:101] op_sel_hi:[1,0]
	v_exp_f32_e32 v234, v234
	v_exp_f32_e32 v235, v235
	v_exp_f32_e32 v236, v236
	v_exp_f32_e32 v237, v237
	v_pk_add_f32 v[234:235], v[234:235], 1.0 op_sel_hi:[1,0]
	v_pk_add_f32 v[236:237], v[236:237], 1.0 op_sel_hi:[1,0]
	v_rcp_f32_e32 v234, v234
	v_rcp_f32_e32 v235, v235
	v_rcp_f32_e32 v236, v236
	v_rcp_f32_e32 v237, v237
	v_pk_mul_f32 v[134:135], v[142:143], v[134:135]
	v_pk_mul_f32 v[136:137], v[144:145], v[136:137]
	v_pk_mul_f32 v[134:135], v[134:135], v[234:235]
	v_pk_mul_f32 v[136:137], v[136:137], v[236:237]
	v_cvt_pk_bf16_f32 v238, v134, v135
	v_cvt_pk_bf16_f32 v239, v136, v137
	v_pk_mul_f32 v[234:235], v[138:139], s[100:101] op_sel_hi:[1,0]
	v_pk_mul_f32 v[236:237], v[140:141], s[100:101] op_sel_hi:[1,0]
	v_exp_f32_e32 v234, v234
	v_exp_f32_e32 v235, v235
	v_exp_f32_e32 v236, v236
	v_exp_f32_e32 v237, v237
	v_pk_add_f32 v[234:235], v[234:235], 1.0 op_sel_hi:[1,0]
	v_pk_add_f32 v[236:237], v[236:237], 1.0 op_sel_hi:[1,0]
	v_rcp_f32_e32 v234, v234
	v_rcp_f32_e32 v235, v235
	v_rcp_f32_e32 v236, v236
	v_rcp_f32_e32 v237, v237
	v_pk_mul_f32 v[130:131], v[138:139], v[130:131]
	v_pk_mul_f32 v[132:133], v[140:141], v[132:133]
	v_pk_mul_f32 v[130:131], v[130:131], v[234:235]
	v_pk_mul_f32 v[132:133], v[132:133], v[236:237]
	v_cvt_pk_bf16_f32 v240, v130, v131
	v_cvt_pk_bf16_f32 v241, v132, v133
	global_store_dwordx4 v[166:167], v[238:241], off
	v_or_b32_e32 v131, 16, v181
	v_mad_i64_i32 v[132:133], s[2:3], v131, s59, v[162:163]
	v_lshl_add_u64 v[132:133], v[132:133], 0, v[164:165]
	v_pk_fma_f32 v[126:127], v[126:127], v[244:245], v[78:79] op_sel_hi:[1,0,1]
; __device__ __forceinline__ unsigned cvt_pk_bf16(float lo, float hi) { unsigned r; asm volatile("v_cvt_pk_bf16_f32 %0, %1, %2" : "=v"(r) : "v"(lo), "v"(hi)); return r; }
; __device__ __forceinline__ float silu_mul(float a, float b) { return a * b * __builtin_amdgcn_rcpf(1.0f + __builtin_amdgcn_exp2f(-a * LOG2E)); }
;     __device__ __forceinline__ void operator()(const f32x4 (&acc)[2][2][4][2], const Unit& u, int wr, int wc, int fr, int fq) const {
;     ...
;             for (int m = 0; m < 4; ++m) { const int row = row0 + ai * HALF + m * 16; const float rs = __shfl(ai ? rsl1 : rsl0, m * 16 + fr); bf16_t* rowp = O + (size_t)row * DFF + col0;
;                 const f32x4 a0 = acc[ai][0][m][0] * rs + ba0, a1 = acc[ai][0][m][1] * rs + ba1, b0 = acc[ai][1][m][0] * rs + bb0, b1 = acc[ai][1][m][1] * rs + bb1;
;                 u32x4 w; w.x = cvt_pk_bf16(silu_mul(a0[0], b0[0]), silu_mul(a0[1], b0[1])); w.y = cvt_pk_bf16(silu_mul(a0[2], b0[2]), silu_mul(a0[3], b0[3]));
;                 w.z = cvt_pk_bf16(silu_mul(a1[0], b1[0]), silu_mul(a1[1], b1[1])); w.w = cvt_pk_bf16(silu_mul(a1[2], b1[2]), silu_mul(a1[3], b1[3]));
;                 *(u32x4*)rowp = w; }
	v_pk_fma_f32 v[128:129], v[128:129], v[244:245], v[80:81] op_sel_hi:[1,0,1]
	v_pk_fma_f32 v[118:119], v[118:119], v[244:245], v[70:71] op_sel_hi:[1,0,1]
	v_pk_fma_f32 v[120:121], v[120:121], v[244:245], v[72:73] op_sel_hi:[1,0,1]
	v_pk_fma_f32 v[122:123], v[122:123], v[244:245], v[74:75] op_sel_hi:[1,0,1]
	v_pk_fma_f32 v[124:125], v[124:125], v[244:245], v[76:77] op_sel_hi:[1,0,1]
	v_pk_fma_f32 v[114:115], v[114:115], v[244:245], v[66:67] op_sel_hi:[1,0,1]
	v_pk_fma_f32 v[116:117], v[116:117], v[244:245], v[68:69] op_sel_hi:[1,0,1]
	v_pk_mul_f32 v[234:235], v[126:127], s[100:101] op_sel_hi:[1,0]
	v_pk_mul_f32 v[236:237], v[128:129], s[100:101] op_sel_hi:[1,0]
	v_exp_f32_e32 v234, v234
	v_exp_f32_e32 v235, v235
	v_exp_f32_e32 v236, v236
	v_exp_f32_e32 v237, v237
	v_pk_add_f32 v[234:235], v[234:235], 1.0 op_sel_hi:[1,0]
	v_pk_add_f32 v[236:237], v[236:237], 1.0 op_sel_hi:[1,0]
	v_rcp_f32_e32 v234, v234
	v_rcp_f32_e32 v235, v235
	v_rcp_f32_e32 v236, v236
	v_rcp_f32_e32 v237, v237
	v_pk_mul_f32 v[118:119], v[126:127], v[118:119]
	v_pk_mul_f32 v[120:121], v[128:129], v[120:121]
	v_pk_mul_f32 v[118:119], v[118:119], v[234:235]
	v_pk_mul_f32 v[120:121], v[120:121], v[236:237]
	v_cvt_pk_bf16_f32 v238, v118, v119
	v_cvt_pk_bf16_f32 v239, v120, v121
	v_pk_mul_f32 v[234:235], v[122:123], s[100:101] op_sel_hi:[1,0]
	v_pk_mul_f32 v[236:237], v[124:125], s[100:101] op_sel_hi:[1,0]
	v_exp_f32_e32 v234, v234
	v_exp_f32_e32 v235, v235
	v_exp_f32_e32 v236, v236
	v_exp_f32_e32 v237, v237
	v_pk_add_f32 v[234:235], v[234:235], 1.0 op_sel_hi:[1,0]
	v_pk_add_f32 v[236:237], v[236:237], 1.0 op_sel_hi:[1,0]
	v_rcp_f32_e32 v234, v234
	v_rcp_f32_e32 v235, v235
	v_rcp_f32_e32 v236, v236
	v_rcp_f32_e32 v237, v237
	v_pk_mul_f32 v[114:115], v[122:123], v[114:115]
	v_pk_mul_f32 v[116:117], v[124:125], v[116:117]
	v_pk_mul_f32 v[114:115], v[114:115], v[234:235]
	v_pk_mul_f32 v[116:117], v[116:117], v[236:237]
	v_cvt_pk_bf16_f32 v240, v114, v115
	v_cvt_pk_bf16_f32 v241, v116, v117
	global_store_dwordx4 v[132:133], v[238:241], off
	v_or_b32_e32 v115, 32, v181
	v_mad_i64_i32 v[116:117], s[2:3], v115, s59, v[162:163]
	v_lshl_add_u64 v[116:117], v[116:117], 0, v[164:165]
	v_pk_fma_f32 v[110:111], v[110:111], v[246:247], v[78:79] op_sel_hi:[1,0,1]
	v_pk_fma_f32 v[112:113], v[112:113], v[246:247], v[80:81] op_sel_hi:[1,0,1]
	v_pk_fma_f32 v[102:103], v[102:103], v[246:247], v[70:71] op_sel_hi:[1,0,1]
	v_pk_fma_f32 v[104:105], v[104:105], v[246:247], v[72:73] op_sel_hi:[1,0,1]
	v_pk_fma_f32 v[106:107], v[106:107], v[246:247], v[74:75] op_sel_hi:[1,0,1]
	v_pk_fma_f32 v[108:109], v[108:109], v[246:247], v[76:77] op_sel_hi:[1,0,1]
	v_pk_fma_f32 v[98:99], v[98:99], v[246:247], v[66:67] op_sel_hi:[1,0,1]
	v_pk_fma_f32 v[100:101], v[100:101], v[246:247], v[68:69] op_sel_hi:[1,0,1]
	v_pk_mul_f32 v[234:235], v[110:111], s[100:101] op_sel_hi:[1,0]
	v_pk_mul_f32 v[236:237], v[112:113], s[100:101] op_sel_hi:[1,0]
	v_exp_f32_e32 v234, v234
	v_exp_f32_e32 v235, v235
	v_exp_f32_e32 v236, v236
	v_exp_f32_e32 v237, v237
	v_pk_add_f32 v[234:235], v[234:235], 1.0 op_sel_hi:[1,0]
	v_pk_add_f32 v[236:237], v[236:237], 1.0 op_sel_hi:[1,0]
	v_rcp_f32_e32 v234, v234
	v_rcp_f32_e32 v235, v235
	v_rcp_f32_e32 v236, v236
	v_rcp_f32_e32 v237, v237
	v_pk_mul_f32 v[102:103], v[110:111], v[102:103]
	v_pk_mul_f32 v[104:105], v[112:113], v[104:105]
	v_pk_mul_f32 v[102:103], v[102:103], v[234:235]
	v_pk_mul_f32 v[104:105], v[104:105], v[236:237]
	v_cvt_pk_bf16_f32 v238, v102, v103
	v_cvt_pk_bf16_f32 v239, v104, v105
	v_pk_mul_f32 v[234:235], v[106:107], s[100:101] op_sel_hi:[1,0]
	v_pk_mul_f32 v[236:237], v[108:109], s[100:101] op_sel_hi:[1,0]
	v_exp_f32_e32 v234, v234
	v_exp_f32_e32 v235, v235
	v_exp_f32_e32 v236, v236
	v_exp_f32_e32 v237, v237
	v_pk_add_f32 v[234:235], v[234:235], 1.0 op_sel_hi:[1,0]
	v_pk_add_f32 v[236:237], v[236:237], 1.0 op_sel_hi:[1,0]
	v_rcp_f32_e32 v234, v234
	v_rcp_f32_e32 v235, v235
	v_rcp_f32_e32 v236, v236
	v_rcp_f32_e32 v237, v237
	v_pk_mul_f32 v[98:99], v[106:107], v[98:99]
	v_pk_mul_f32 v[100:101], v[108:109], v[100:101]
	v_pk_mul_f32 v[98:99], v[98:99], v[234:235]
	v_pk_mul_f32 v[100:101], v[100:101], v[236:237]
	v_cvt_pk_bf16_f32 v240, v98, v99
	v_cvt_pk_bf16_f32 v241, v100, v101
	global_store_dwordx4 v[116:117], v[238:241], off
	v_or_b32_e32 v99, 48, v181
	v_mad_i64_i32 v[100:101], s[2:3], v99, s59, v[162:163]
	v_lshl_add_u64 v[100:101], v[100:101], 0, v[164:165]
	v_pk_fma_f32 v[94:95], v[94:95], v[248:249], v[78:79] op_sel_hi:[1,0,1]
	v_pk_fma_f32 v[96:97], v[96:97], v[248:249], v[80:81] op_sel_hi:[1,0,1]
	v_pk_fma_f32 v[86:87], v[86:87], v[248:249], v[70:71] op_sel_hi:[1,0,1]
	v_pk_fma_f32 v[88:89], v[88:89], v[248:249], v[72:73] op_sel_hi:[1,0,1]
	v_pk_fma_f32 v[90:91], v[90:91], v[248:249], v[74:75] op_sel_hi:[1,0,1]
	v_pk_fma_f32 v[92:93], v[92:93], v[248:249], v[76:77] op_sel_hi:[1,0,1]
	v_pk_fma_f32 v[82:83], v[82:83], v[248:249], v[66:67] op_sel_hi:[1,0,1]
	v_pk_fma_f32 v[84:85], v[84:85], v[248:249], v[68:69] op_sel_hi:[1,0,1]
	v_pk_mul_f32 v[234:235], v[94:95], s[100:101] op_sel_hi:[1,0]
	v_pk_mul_f32 v[236:237], v[96:97], s[100:101] op_sel_hi:[1,0]
	v_exp_f32_e32 v234, v234
	v_exp_f32_e32 v235, v235
	v_exp_f32_e32 v236, v236
	v_exp_f32_e32 v237, v237
	v_pk_add_f32 v[234:235], v[234:235], 1.0 op_sel_hi:[1,0]
	v_pk_add_f32 v[236:237], v[236:237], 1.0 op_sel_hi:[1,0]
	v_rcp_f32_e32 v234, v234
	v_rcp_f32_e32 v235, v235
	v_rcp_f32_e32 v236, v236
	v_rcp_f32_e32 v237, v237
	v_pk_mul_f32 v[86:87], v[94:95], v[86:87]
	v_pk_mul_f32 v[88:89], v[96:97], v[88:89]
	v_pk_mul_f32 v[86:87], v[86:87], v[234:235]
	v_pk_mul_f32 v[88:89], v[88:89], v[236:237]
	v_cvt_pk_bf16_f32 v238, v86, v87
; __device__ __forceinline__ unsigned cvt_pk_bf16(float lo, float hi) { unsigned r; asm volatile("v_cvt_pk_bf16_f32 %0, %1, %2" : "=v"(r) : "v"(lo), "v"(hi)); return r; }
; __device__ __forceinline__ float row_rstd(const float* ss, int row) { return 1.0f / sqrtf(ss[row] * (1.0f / DM) + 1e-6f); }
; __device__ __forceinline__ float silu_mul(float a, float b) { return a * b * __builtin_amdgcn_rcpf(1.0f + __builtin_amdgcn_exp2f(-a * LOG2E)); }
;     __device__ __forceinline__ void operator()(const f32x4 (&acc)[2][2][4][2], const Unit& u, int wr, int wc, int fr, int fq) const {
;     ...
;         const float rsl0 = row_rstd(ss, u.pm * BM + wr * 64 + lane), rsl1 = row_rstd(ss, u.pm * BM + HALF + wr * 64 + lane);
; #pragma unroll
;         for (int ai = 0; ai < 2; ++ai)
; #pragma unroll
;             for (int m = 0; m < 4; ++m) { const int row = row0 + ai * HALF + m * 16; const float rs = __shfl(ai ? rsl1 : rsl0, m * 16 + fr); bf16_t* rowp = O + (size_t)row * DFF + col0;
;                 const f32x4 a0 = acc[ai][0][m][0] * rs + ba0, a1 = acc[ai][0][m][1] * rs + ba1, b0 = acc[ai][1][m][0] * rs + bb0, b1 = acc[ai][1][m][1] * rs + bb1;
;                 u32x4 w; w.x = cvt_pk_bf16(silu_mul(a0[0], b0[0]), silu_mul(a0[1], b0[1])); w.y = cvt_pk_bf16(silu_mul(a0[2], b0[2]), silu_mul(a0[3], b0[3]));
;                 w.z = cvt_pk_bf16(silu_mul(a1[0], b1[0]), silu_mul(a1[1], b1[1])); w.w = cvt_pk_bf16(silu_mul(a1[2], b1[2]), silu_mul(a1[3], b1[3]));
;                 *(u32x4*)rowp = w; }
	v_cvt_pk_bf16_f32 v239, v88, v89
	v_pk_mul_f32 v[234:235], v[90:91], s[100:101] op_sel_hi:[1,0]
	v_pk_mul_f32 v[236:237], v[92:93], s[100:101] op_sel_hi:[1,0]
	v_exp_f32_e32 v234, v234
	v_exp_f32_e32 v235, v235
	v_exp_f32_e32 v236, v236
	v_exp_f32_e32 v237, v237
	v_pk_add_f32 v[234:235], v[234:235], 1.0 op_sel_hi:[1,0]
	v_pk_add_f32 v[236:237], v[236:237], 1.0 op_sel_hi:[1,0]
	v_rcp_f32_e32 v234, v234
	v_rcp_f32_e32 v235, v235
	v_rcp_f32_e32 v236, v236
	v_rcp_f32_e32 v237, v237
	v_pk_mul_f32 v[82:83], v[90:91], v[82:83]
	v_pk_mul_f32 v[84:85], v[92:93], v[84:85]
	v_pk_mul_f32 v[82:83], v[82:83], v[234:235]
	v_pk_mul_f32 v[84:85], v[84:85], v[236:237]
	v_cvt_pk_bf16_f32 v240, v82, v83
	v_cvt_pk_bf16_f32 v241, v84, v85
	global_store_dwordx4 v[100:101], v[238:241], off
	s_nop 1
	v_div_scale_f32 v82, s[2:3], v182, v182, 1.0
	v_rcp_f32_e32 v84, v82
	v_add_u32_e32 v83, 0x80, v181
	v_fma_f32 v85, -v82, v84, 1.0
	v_fmac_f32_e32 v84, v85, v84
	v_div_scale_f32 v85, vcc, 1.0, v182, 1.0
	v_mul_f32_e32 v86, v85, v84
	v_fma_f32 v87, -v82, v86, v85
	v_fmac_f32_e32 v86, v87, v84
	v_fma_f32 v82, -v82, v86, v85
	v_div_fmas_f32 v82, v82, v84, v86
	v_div_fixup_f32 v82, v82, v182, 1.0
	ds_bpermute_b32 v242, v180, v82
	ds_bpermute_b32 v244, v180, v82 offset:64
	ds_bpermute_b32 v246, v180, v82 offset:128
	ds_bpermute_b32 v248, v180, v82 offset:192
	v_mad_i64_i32 v[86:87], s[2:3], v83, s59, v[162:163]
	v_lshl_add_u64 v[86:87], v[86:87], 0, v[164:165]
	s_andn2_b64 vcc, exec, s[38:39]
	s_waitcnt lgkmcnt(0)
	v_pk_fma_f32 v[62:63], v[62:63], v[242:243], v[78:79] op_sel_hi:[1,0,1]
	v_pk_fma_f32 v[64:65], v[64:65], v[242:243], v[80:81] op_sel_hi:[1,0,1]
	v_pk_fma_f32 v[54:55], v[54:55], v[242:243], v[70:71] op_sel_hi:[1,0,1]
	v_pk_fma_f32 v[56:57], v[56:57], v[242:243], v[72:73] op_sel_hi:[1,0,1]
	v_pk_fma_f32 v[58:59], v[58:59], v[242:243], v[74:75] op_sel_hi:[1,0,1]
	v_pk_fma_f32 v[60:61], v[60:61], v[242:243], v[76:77] op_sel_hi:[1,0,1]
	v_pk_fma_f32 v[50:51], v[50:51], v[242:243], v[66:67] op_sel_hi:[1,0,1]
	v_pk_fma_f32 v[52:53], v[52:53], v[242:243], v[68:69] op_sel_hi:[1,0,1]
	v_pk_mul_f32 v[234:235], v[62:63], s[100:101] op_sel_hi:[1,0]
	v_pk_mul_f32 v[236:237], v[64:65], s[100:101] op_sel_hi:[1,0]
	v_exp_f32_e32 v234, v234
	v_exp_f32_e32 v235, v235
	v_exp_f32_e32 v236, v236
	v_exp_f32_e32 v237, v237
	v_pk_add_f32 v[234:235], v[234:235], 1.0 op_sel_hi:[1,0]
	v_pk_add_f32 v[236:237], v[236:237], 1.0 op_sel_hi:[1,0]
	v_rcp_f32_e32 v234, v234
	v_rcp_f32_e32 v235, v235
	v_rcp_f32_e32 v236, v236
	v_rcp_f32_e32 v237, v237
	v_pk_mul_f32 v[54:55], v[62:63], v[54:55]
	v_pk_mul_f32 v[56:57], v[64:65], v[56:57]
	v_pk_mul_f32 v[54:55], v[54:55], v[234:235]
	v_pk_mul_f32 v[56:57], v[56:57], v[236:237]
	v_cvt_pk_bf16_f32 v238, v54, v55
	v_cvt_pk_bf16_f32 v239, v56, v57
	v_pk_mul_f32 v[234:235], v[58:59], s[100:101] op_sel_hi:[1,0]
	v_pk_mul_f32 v[236:237], v[60:61], s[100:101] op_sel_hi:[1,0]
	v_exp_f32_e32 v234, v234
	v_exp_f32_e32 v235, v235
	v_exp_f32_e32 v236, v236
	v_exp_f32_e32 v237, v237
	v_pk_add_f32 v[234:235], v[234:235], 1.0 op_sel_hi:[1,0]
	v_pk_add_f32 v[236:237], v[236:237], 1.0 op_sel_hi:[1,0]
	v_rcp_f32_e32 v234, v234
	v_rcp_f32_e32 v235, v235
	v_rcp_f32_e32 v236, v236
	v_rcp_f32_e32 v237, v237
	v_pk_mul_f32 v[50:51], v[58:59], v[50:51]
	v_pk_mul_f32 v[52:53], v[60:61], v[52:53]
	v_pk_mul_f32 v[50:51], v[50:51], v[234:235]
	v_pk_mul_f32 v[52:53], v[52:53], v[236:237]
	v_cvt_pk_bf16_f32 v240, v50, v51
	v_cvt_pk_bf16_f32 v241, v52, v53
	global_store_dwordx4 v[86:87], v[238:241], off
	v_add_u32_e32 v51, 0x90, v181
	v_mad_i64_i32 v[52:53], s[2:3], v51, s59, v[162:163]
	v_lshl_add_u64 v[52:53], v[52:53], 0, v[164:165]
	v_pk_fma_f32 v[46:47], v[46:47], v[244:245], v[78:79] op_sel_hi:[1,0,1]
	v_pk_fma_f32 v[48:49], v[48:49], v[244:245], v[80:81] op_sel_hi:[1,0,1]
	v_pk_fma_f32 v[38:39], v[38:39], v[244:245], v[70:71] op_sel_hi:[1,0,1]
	v_pk_fma_f32 v[40:41], v[40:41], v[244:245], v[72:73] op_sel_hi:[1,0,1]
	v_pk_fma_f32 v[42:43], v[42:43], v[244:245], v[74:75] op_sel_hi:[1,0,1]
	v_pk_fma_f32 v[44:45], v[44:45], v[244:245], v[76:77] op_sel_hi:[1,0,1]
	v_pk_fma_f32 v[34:35], v[34:35], v[244:245], v[66:67] op_sel_hi:[1,0,1]
	v_pk_fma_f32 v[36:37], v[36:37], v[244:245], v[68:69] op_sel_hi:[1,0,1]
	v_pk_mul_f32 v[234:235], v[46:47], s[100:101] op_sel_hi:[1,0]
	v_pk_mul_f32 v[236:237], v[48:49], s[100:101] op_sel_hi:[1,0]
	v_exp_f32_e32 v234, v234
	v_exp_f32_e32 v235, v235
	v_exp_f32_e32 v236, v236
	v_exp_f32_e32 v237, v237
	v_pk_add_f32 v[234:235], v[234:235], 1.0 op_sel_hi:[1,0]
	v_pk_add_f32 v[236:237], v[236:237], 1.0 op_sel_hi:[1,0]
	v_rcp_f32_e32 v234, v234
	v_rcp_f32_e32 v235, v235
	v_rcp_f32_e32 v236, v236
	v_rcp_f32_e32 v237, v237
	v_pk_mul_f32 v[38:39], v[46:47], v[38:39]
	v_pk_mul_f32 v[40:41], v[48:49], v[40:41]
	v_pk_mul_f32 v[38:39], v[38:39], v[234:235]
	v_pk_mul_f32 v[40:41], v[40:41], v[236:237]
	v_cvt_pk_bf16_f32 v238, v38, v39
	v_cvt_pk_bf16_f32 v239, v40, v41
	v_pk_mul_f32 v[234:235], v[42:43], s[100:101] op_sel_hi:[1,0]
	v_pk_mul_f32 v[236:237], v[44:45], s[100:101] op_sel_hi:[1,0]
; __device__ __forceinline__ unsigned cvt_pk_bf16(float lo, float hi) { unsigned r; asm volatile("v_cvt_pk_bf16_f32 %0, %1, %2" : "=v"(r) : "v"(lo), "v"(hi)); return r; }
; __device__ __forceinline__ float silu_mul(float a, float b) { return a * b * __builtin_amdgcn_rcpf(1.0f + __builtin_amdgcn_exp2f(-a * LOG2E)); }
; #define PG8_BAR __builtin_amdgcn_s_barrier()
;     __device__ __forceinline__ void operator()(const f32x4 (&acc)[2][2][4][2], const Unit& u, int wr, int wc, int fr, int fq) const {
;     ...
;             for (int m = 0; m < 4; ++m) { const int row = row0 + ai * HALF + m * 16; const float rs = __shfl(ai ? rsl1 : rsl0, m * 16 + fr); bf16_t* rowp = O + (size_t)row * DFF + col0;
;                 const f32x4 a0 = acc[ai][0][m][0] * rs + ba0, a1 = acc[ai][0][m][1] * rs + ba1, b0 = acc[ai][1][m][0] * rs + bb0, b1 = acc[ai][1][m][1] * rs + bb1;
;                 u32x4 w; w.x = cvt_pk_bf16(silu_mul(a0[0], b0[0]), silu_mul(a0[1], b0[1])); w.y = cvt_pk_bf16(silu_mul(a0[2], b0[2]), silu_mul(a0[3], b0[3]));
;                 w.z = cvt_pk_bf16(silu_mul(a1[0], b1[0]), silu_mul(a1[1], b1[1])); w.w = cvt_pk_bf16(silu_mul(a1[2], b1[2]), silu_mul(a1[3], b1[3]));
;                 *(u32x4*)rowp = w; }
; template <class Epi, class Sched, bool ALIGN_EPI = false, bool SP2 = false>
; __device__ __forceinline__ void gemm_phase(LAS unsigned char* lds, const Gemm g, const Sched& S, const Epi& E) {
;     ...
;         if constexpr (!Epi::AFTER_DRAIN) { E(acc, cur, wr, wc, fr, fq); S.done(cur); }
;         if (!has_next) break;
; #pragma unroll
;         for (int a = 0; a < 2; ++a)
; #pragma unroll
;             for (int b = 0; b < 2; ++b)
; #pragma unroll
;                 for (int m = 0; m < 4; ++m)
; #pragma unroll
;                     for (int n = 0; n < 2; ++n) acc[a][b][m][n] = (f32x4){0.f, 0.f, 0.f, 0.f};
;         cur = nxt; cA = nA; cB = nB; ++ui;
;         if constexpr (ALIGN_EPI) { if (wr == 1) PG8_BAR; }
	v_exp_f32_e32 v234, v234
	v_exp_f32_e32 v235, v235
	v_exp_f32_e32 v236, v236
	v_exp_f32_e32 v237, v237
	v_pk_add_f32 v[234:235], v[234:235], 1.0 op_sel_hi:[1,0]
	v_pk_add_f32 v[236:237], v[236:237], 1.0 op_sel_hi:[1,0]
	v_rcp_f32_e32 v234, v234
	v_rcp_f32_e32 v235, v235
	v_rcp_f32_e32 v236, v236
	v_rcp_f32_e32 v237, v237
	v_pk_mul_f32 v[34:35], v[42:43], v[34:35]
	v_pk_mul_f32 v[36:37], v[44:45], v[36:37]
	v_pk_mul_f32 v[34:35], v[34:35], v[234:235]
	v_pk_mul_f32 v[36:37], v[36:37], v[236:237]
	v_cvt_pk_bf16_f32 v240, v34, v35
	v_cvt_pk_bf16_f32 v241, v36, v37
	global_store_dwordx4 v[52:53], v[238:241], off
	v_add_u32_e32 v35, 0xa0, v181
	v_mad_i64_i32 v[36:37], s[2:3], v35, s59, v[162:163]
	v_lshl_add_u64 v[36:37], v[36:37], 0, v[164:165]
	v_pk_fma_f32 v[30:31], v[30:31], v[246:247], v[78:79] op_sel_hi:[1,0,1]
	v_pk_fma_f32 v[32:33], v[32:33], v[246:247], v[80:81] op_sel_hi:[1,0,1]
	v_pk_fma_f32 v[22:23], v[22:23], v[246:247], v[70:71] op_sel_hi:[1,0,1]
	v_pk_fma_f32 v[24:25], v[24:25], v[246:247], v[72:73] op_sel_hi:[1,0,1]
	v_pk_fma_f32 v[26:27], v[26:27], v[246:247], v[74:75] op_sel_hi:[1,0,1]
	v_pk_fma_f32 v[28:29], v[28:29], v[246:247], v[76:77] op_sel_hi:[1,0,1]
	v_pk_fma_f32 v[18:19], v[18:19], v[246:247], v[66:67] op_sel_hi:[1,0,1]
	v_pk_fma_f32 v[20:21], v[20:21], v[246:247], v[68:69] op_sel_hi:[1,0,1]
	v_pk_mul_f32 v[234:235], v[30:31], s[100:101] op_sel_hi:[1,0]
	v_pk_mul_f32 v[236:237], v[32:33], s[100:101] op_sel_hi:[1,0]
	v_exp_f32_e32 v234, v234
	v_exp_f32_e32 v235, v235
	v_exp_f32_e32 v236, v236
	v_exp_f32_e32 v237, v237
	v_pk_add_f32 v[234:235], v[234:235], 1.0 op_sel_hi:[1,0]
	v_pk_add_f32 v[236:237], v[236:237], 1.0 op_sel_hi:[1,0]
	v_rcp_f32_e32 v234, v234
	v_rcp_f32_e32 v235, v235
	v_rcp_f32_e32 v236, v236
	v_rcp_f32_e32 v237, v237
	v_pk_mul_f32 v[22:23], v[30:31], v[22:23]
	v_pk_mul_f32 v[24:25], v[32:33], v[24:25]
	v_pk_mul_f32 v[22:23], v[22:23], v[234:235]
	v_pk_mul_f32 v[24:25], v[24:25], v[236:237]
	v_cvt_pk_bf16_f32 v238, v22, v23
	v_cvt_pk_bf16_f32 v239, v24, v25
	v_pk_mul_f32 v[234:235], v[26:27], s[100:101] op_sel_hi:[1,0]
	v_pk_mul_f32 v[236:237], v[28:29], s[100:101] op_sel_hi:[1,0]
	v_exp_f32_e32 v234, v234
	v_exp_f32_e32 v235, v235
	v_exp_f32_e32 v236, v236
	v_exp_f32_e32 v237, v237
	v_pk_add_f32 v[234:235], v[234:235], 1.0 op_sel_hi:[1,0]
	v_pk_add_f32 v[236:237], v[236:237], 1.0 op_sel_hi:[1,0]
	v_rcp_f32_e32 v234, v234
	v_rcp_f32_e32 v235, v235
	v_rcp_f32_e32 v236, v236
	v_rcp_f32_e32 v237, v237
	v_pk_mul_f32 v[18:19], v[26:27], v[18:19]
	v_pk_mul_f32 v[20:21], v[28:29], v[20:21]
	v_pk_mul_f32 v[18:19], v[18:19], v[234:235]
	v_pk_mul_f32 v[20:21], v[20:21], v[236:237]
	v_cvt_pk_bf16_f32 v240, v18, v19
	v_cvt_pk_bf16_f32 v241, v20, v21
	global_store_dwordx4 v[36:37], v[238:241], off
	v_add_u32_e32 v19, 0xb0, v181
	v_mad_i64_i32 v[20:21], s[2:3], v19, s59, v[162:163]
	v_lshl_add_u64 v[20:21], v[20:21], 0, v[164:165]
	s_mov_b64 s[2:3], -1
	v_pk_fma_f32 v[14:15], v[14:15], v[248:249], v[78:79] op_sel_hi:[1,0,1]
	v_pk_fma_f32 v[16:17], v[16:17], v[248:249], v[80:81] op_sel_hi:[1,0,1]
	v_pk_fma_f32 v[6:7], v[6:7], v[248:249], v[70:71] op_sel_hi:[1,0,1]
	v_pk_fma_f32 v[8:9], v[8:9], v[248:249], v[72:73] op_sel_hi:[1,0,1]
	v_pk_fma_f32 v[10:11], v[10:11], v[248:249], v[74:75] op_sel_hi:[1,0,1]
	v_pk_fma_f32 v[12:13], v[12:13], v[248:249], v[76:77] op_sel_hi:[1,0,1]
	v_pk_fma_f32 v[2:3], v[2:3], v[248:249], v[66:67] op_sel_hi:[1,0,1]
	v_pk_fma_f32 v[4:5], v[4:5], v[248:249], v[68:69] op_sel_hi:[1,0,1]
	v_pk_mul_f32 v[234:235], v[14:15], s[100:101] op_sel_hi:[1,0]
	v_pk_mul_f32 v[236:237], v[16:17], s[100:101] op_sel_hi:[1,0]
	v_exp_f32_e32 v234, v234
	v_exp_f32_e32 v235, v235
	v_exp_f32_e32 v236, v236
	v_exp_f32_e32 v237, v237
	v_pk_add_f32 v[234:235], v[234:235], 1.0 op_sel_hi:[1,0]
	v_pk_add_f32 v[236:237], v[236:237], 1.0 op_sel_hi:[1,0]
	v_rcp_f32_e32 v234, v234
	v_rcp_f32_e32 v235, v235
	v_rcp_f32_e32 v236, v236
	v_rcp_f32_e32 v237, v237
	v_pk_mul_f32 v[6:7], v[14:15], v[6:7]
	v_pk_mul_f32 v[8:9], v[16:17], v[8:9]
	v_pk_mul_f32 v[6:7], v[6:7], v[234:235]
	v_pk_mul_f32 v[8:9], v[8:9], v[236:237]
	v_cvt_pk_bf16_f32 v238, v6, v7
	v_cvt_pk_bf16_f32 v239, v8, v9
	v_pk_mul_f32 v[234:235], v[10:11], s[100:101] op_sel_hi:[1,0]
	v_pk_mul_f32 v[236:237], v[12:13], s[100:101] op_sel_hi:[1,0]
	v_exp_f32_e32 v234, v234
	v_exp_f32_e32 v235, v235
	v_exp_f32_e32 v236, v236
	v_exp_f32_e32 v237, v237
	v_pk_add_f32 v[234:235], v[234:235], 1.0 op_sel_hi:[1,0]
	v_pk_add_f32 v[236:237], v[236:237], 1.0 op_sel_hi:[1,0]
	v_rcp_f32_e32 v234, v234
	v_rcp_f32_e32 v235, v235
	v_rcp_f32_e32 v236, v236
	v_rcp_f32_e32 v237, v237
	v_pk_mul_f32 v[2:3], v[10:11], v[2:3]
	v_pk_mul_f32 v[4:5], v[12:13], v[4:5]
	v_pk_mul_f32 v[2:3], v[2:3], v[234:235]
	v_pk_mul_f32 v[4:5], v[4:5], v[236:237]
	v_cvt_pk_bf16_f32 v240, v2, v3
	v_cvt_pk_bf16_f32 v241, v4, v5
	global_store_dwordx4 v[20:21], v[238:241], off
	s_cbranch_vccnz .LBB0_184
	s_andn2_b64 vcc, exec, s[4:5]
	s_cbranch_vccnz .LBB0_183
	s_barrier
	s_branch .LBB0_183

; #define PG8_STAGE(bufoff, gbase, voff) do { _Pragma("unroll") for (int _i = 0; _i < 2; ++_i) \
;         __builtin_amdgcn_global_load_lds((const unsigned*)((const char*)(gbase) + (voff)[_i]), (LAS unsigned*)(lds + (bufoff) + ldsw + _i * 8192), 16, 0, 0); } while (0)
; #define PG8_LDA(dst, b, h) do { _Pragma("unroll") for (int m = 0; m < 4; ++m) _Pragma("unroll") for (int k = 0; k < 2; ++k) dst[m][k] = *(const LAS bf16x8*)(lds + PG8_SA(b, h) + aoff + m * 2048 + k * 1024); } while (0)
; #define PG8_LDB(dst, b, h) do { _Pragma("unroll") for (int n = 0; n < 2; ++n) _Pragma("unroll") for (int k = 0; k < 2; ++k) dst[n][k] = *(const LAS bf16x8*)(lds + PG8_SB(b, h) + boff + n * 2048 + k * 1024); } while (0)
; #define PG8_MMA(ai, bj, At, Bt) do { __builtin_amdgcn_s_setprio(1); _Pragma("unroll") for (int m = 0; m < 4; ++m) _Pragma("unroll") for (int n = 0; n < 2; ++n) _Pragma("unroll") for (int k = 0; k < 2; ++k) \
;         acc[ai][bj][m][n] = __builtin_amdgcn_mfma_f32_16x16x32_bf16(Bt[n][k], At[m][k], acc[ai][bj][m][n], 0, 0, 0); __builtin_amdgcn_s_setprio(0); } while (0)
; #define PG8_WAIT_V(n) asm volatile("s_waitcnt vmcnt(" #n ")" ::: "memory")
; #define PG8_WAIT_L(n) asm volatile("s_waitcnt lgkmcnt(" #n ")" ::: "memory")
; #define PG8_BAR __builtin_amdgcn_s_barrier()
; #define PG8_SCHED __builtin_amdgcn_sched_barrier(0)
; template <class Epi, class Sched, bool ALIGN_EPI = false, bool SP2 = false>
; __device__ __forceinline__ void gemm_phase(LAS unsigned char* lds, const Gemm g, const Sched& S, const Epi& E) {
;     ...
;             PG8_LDB(B0, 0, 0); PG8_LDB(B1, 0, 1); PG8_SCHED; PG8_LDA(At, 0, 0); PG8_STAGE(PG8_SA(1, 1), a1 + hstep, voffA);
;             PG8_WAIT_V(8); PG8_WAIT_L(0); PG8_BAR; PG8_MMA(0, 0, At, B0); PG8_MMA(0, 1, At, B1); PG8_BAR; PG8_SCHED;
;             PG8_LDA(At, 0, 1); PG8_STAGE(PG8_SB(0, 0), b2, voffB); PG8_STAGE(PG8_SB(0, 1), b2 + hstepB, voffB); PG8_STAGE(PG8_SA(0, 0), a2, voffA);
;             PG8_WAIT_V(8); PG8_WAIT_L(0); PG8_BAR; PG8_MMA(1, 0, At, B0); PG8_MMA(1, 1, At, B1); PG8_BAR; PG8_SCHED;
.LBB0_1465:
	ds_read_b128 v[66:69], v174
	ds_read_b128 v[70:73], v174 offset:1024
	ds_read_b128 v[74:77], v174 offset:2048
	ds_read_b128 v[78:81], v174 offset:3072
	ds_read_b128 v[162:165], v175
	ds_read_b128 v[182:185], v175 offset:1024
	ds_read_b128 v[186:189], v175 offset:2048
	ds_read_b128 v[190:193], v175 offset:3072
	s_add_u32 s22, s16, 0xfff80080
	s_addc_u32 s23, s17, -1
	s_cmp_eq_u32 s53, 28
	s_cselect_b32 s41, s3, s23
	s_cselect_b32 s40, s15, s22
	s_cselect_b32 s23, s13, s52
	s_cselect_b32 s22, s24, s25
	s_add_i32 m0, s33, 0xc000
	ds_read_b128 v[194:197], v176
	ds_read_b128 v[198:201], v176 offset:1024
	ds_read_b128 v[202:205], v176 offset:2048
	ds_read_b128 v[206:209], v176 offset:3072
	ds_read_b128 v[210:213], v176 offset:4096
	ds_read_b128 v[214:217], v176 offset:5120
	ds_read_b128 v[218:221], v176 offset:6144
	ds_read_b128 v[222:225], v176 offset:7168
	global_load_lds_dwordx4 v154, s[16:17]
	s_add_i32 m0, s33, 0xe000
	s_nop 0
	global_load_lds_dwordx4 v156, s[16:17]
	s_waitcnt vmcnt(8)
	s_waitcnt lgkmcnt(0)
	s_barrier
	s_waitcnt lgkmcnt(0)
	v_mfma_f32_16x16x32_bf16 v[142:145], v[66:69], v[194:197], v[142:145]
	v_mfma_f32_16x16x32_bf16 v[138:141], v[74:77], v[194:197], v[138:141]
	v_mfma_f32_16x16x32_bf16 v[126:129], v[66:69], v[202:205], v[126:129]
	v_mfma_f32_16x16x32_bf16 v[122:125], v[74:77], v[202:205], v[122:125]
	v_mfma_f32_16x16x32_bf16 v[110:113], v[66:69], v[210:213], v[110:113]
	v_mfma_f32_16x16x32_bf16 v[106:109], v[74:77], v[210:213], v[106:109]
	v_mfma_f32_16x16x32_bf16 v[94:97], v[66:69], v[218:221], v[94:97]
	v_mfma_f32_16x16x32_bf16 v[90:93], v[74:77], v[218:221], v[90:93]
	v_mfma_f32_16x16x32_bf16 v[142:145], v[70:73], v[198:201], v[142:145]
	v_mfma_f32_16x16x32_bf16 v[138:141], v[78:81], v[198:201], v[138:141]
	v_mfma_f32_16x16x32_bf16 v[126:129], v[70:73], v[206:209], v[126:129]
	v_mfma_f32_16x16x32_bf16 v[122:125], v[78:81], v[206:209], v[122:125]
	v_mfma_f32_16x16x32_bf16 v[110:113], v[70:73], v[214:217], v[110:113]
	v_mfma_f32_16x16x32_bf16 v[106:109], v[78:81], v[214:217], v[106:109]
	v_mfma_f32_16x16x32_bf16 v[94:97], v[70:73], v[222:225], v[94:97]
	v_mfma_f32_16x16x32_bf16 v[90:93], v[78:81], v[222:225], v[90:93]
	v_mfma_f32_16x16x32_bf16 v[134:137], v[162:165], v[194:197], v[134:137]
	v_mfma_f32_16x16x32_bf16 v[130:133], v[186:189], v[194:197], v[130:133]
	v_mfma_f32_16x16x32_bf16 v[118:121], v[162:165], v[202:205], v[118:121]
	v_mfma_f32_16x16x32_bf16 v[114:117], v[186:189], v[202:205], v[114:117]
	v_mfma_f32_16x16x32_bf16 v[102:105], v[162:165], v[210:213], v[102:105]
	v_mfma_f32_16x16x32_bf16 v[98:101], v[186:189], v[210:213], v[98:101]
	v_mfma_f32_16x16x32_bf16 v[86:89], v[162:165], v[218:221], v[86:89]
	v_mfma_f32_16x16x32_bf16 v[82:85], v[186:189], v[218:221], v[82:85]
	v_mfma_f32_16x16x32_bf16 v[134:137], v[182:185], v[198:201], v[134:137]
	v_mfma_f32_16x16x32_bf16 v[130:133], v[190:193], v[198:201], v[130:133]
	v_mfma_f32_16x16x32_bf16 v[118:121], v[182:185], v[206:209], v[118:121]
	v_mfma_f32_16x16x32_bf16 v[114:117], v[190:193], v[206:209], v[114:117]
	v_mfma_f32_16x16x32_bf16 v[102:105], v[182:185], v[214:217], v[102:105]
	v_mfma_f32_16x16x32_bf16 v[98:101], v[190:193], v[214:217], v[98:101]
	v_mfma_f32_16x16x32_bf16 v[86:89], v[182:185], v[222:225], v[86:89]
	v_mfma_f32_16x16x32_bf16 v[82:85], v[190:193], v[222:225], v[82:85]
	s_barrier
	s_add_i32 s54, s47, s29
	s_mov_b32 m0, s54
	ds_read_b128 v[194:197], v176 offset:16384
	ds_read_b128 v[198:201], v176 offset:17408
	ds_read_b128 v[202:205], v176 offset:18432
	ds_read_b128 v[206:209], v176 offset:19456
	ds_read_b128 v[210:213], v176 offset:20480
	ds_read_b128 v[214:217], v176 offset:21504
	ds_read_b128 v[218:221], v176 offset:22528
	ds_read_b128 v[222:225], v176 offset:23552
	global_load_lds_dwordx4 v150, s[22:23]
	s_add_i32 m0, s54, 0x2000
	s_add_u32 s54, s22, 0x80000
	v_lshl_add_u64 v[226:227], s[22:23], 0, v[146:147]
	s_addc_u32 s55, s23, 0
	s_add_i32 s56, s48, s29
	global_load_lds_dwordx4 v146, s[22:23]
	s_mov_b32 m0, s56
	v_lshl_add_u64 v[230:231], s[40:41], 0, v[148:149]
	global_load_lds_dwordx4 v150, s[54:55]
	s_add_i32 m0, s56, 0x2000
	s_nop 0
	global_load_lds_dwordx4 v146, s[54:55]
	v_lshl_add_u64 v[228:229], s[40:41], 0, v[152:153]
	s_mov_b32 m0, s33
	s_nop 0
	global_load_lds_dwordx4 v152, s[40:41]
	s_mov_b32 m0, s34
	s_nop 0
	global_load_lds_dwordx4 v148, s[40:41]
	s_waitcnt vmcnt(8)
	s_waitcnt lgkmcnt(0)
	s_barrier
	s_waitcnt lgkmcnt(0)
	v_mfma_f32_16x16x32_bf16 v[62:65], v[66:69], v[194:197], v[62:65]
	v_mfma_f32_16x16x32_bf16 v[58:61], v[74:77], v[194:197], v[58:61]
	v_mfma_f32_16x16x32_bf16 v[46:49], v[66:69], v[202:205], v[46:49]
	v_mfma_f32_16x16x32_bf16 v[42:45], v[74:77], v[202:205], v[42:45]
	v_mfma_f32_16x16x32_bf16 v[30:33], v[66:69], v[210:213], v[30:33]
	v_mfma_f32_16x16x32_bf16 v[26:29], v[74:77], v[210:213], v[26:29]
	v_mfma_f32_16x16x32_bf16 v[14:17], v[66:69], v[218:221], v[14:17]
	v_mfma_f32_16x16x32_bf16 v[10:13], v[74:77], v[218:221], v[10:13]
	v_mfma_f32_16x16x32_bf16 v[62:65], v[70:73], v[198:201], v[62:65]
	v_mfma_f32_16x16x32_bf16 v[58:61], v[78:81], v[198:201], v[58:61]
	v_mfma_f32_16x16x32_bf16 v[46:49], v[70:73], v[206:209], v[46:49]
	v_mfma_f32_16x16x32_bf16 v[42:45], v[78:81], v[206:209], v[42:45]
	v_mfma_f32_16x16x32_bf16 v[30:33], v[70:73], v[214:217], v[30:33]
	v_mfma_f32_16x16x32_bf16 v[26:29], v[78:81], v[214:217], v[26:29]
	v_mfma_f32_16x16x32_bf16 v[14:17], v[70:73], v[222:225], v[14:17]
	v_mfma_f32_16x16x32_bf16 v[10:13], v[78:81], v[222:225], v[10:13]
	v_mfma_f32_16x16x32_bf16 v[54:57], v[162:165], v[194:197], v[54:57]
	v_mfma_f32_16x16x32_bf16 v[50:53], v[186:189], v[194:197], v[50:53]
	v_mfma_f32_16x16x32_bf16 v[38:41], v[162:165], v[202:205], v[38:41]
	v_mfma_f32_16x16x32_bf16 v[34:37], v[186:189], v[202:205], v[34:37]
	v_mfma_f32_16x16x32_bf16 v[22:25], v[162:165], v[210:213], v[22:25]
	v_mfma_f32_16x16x32_bf16 v[18:21], v[186:189], v[210:213], v[18:21]
	v_mfma_f32_16x16x32_bf16 v[6:9], v[162:165], v[218:221], v[6:9]
	v_mfma_f32_16x16x32_bf16 v[2:5], v[186:189], v[218:221], v[2:5]
	v_mfma_f32_16x16x32_bf16 v[54:57], v[182:185], v[198:201], v[54:57]
	v_mfma_f32_16x16x32_bf16 v[50:53], v[190:193], v[198:201], v[50:53]
	v_mfma_f32_16x16x32_bf16 v[38:41], v[182:185], v[206:209], v[38:41]
	v_mfma_f32_16x16x32_bf16 v[34:37], v[190:193], v[206:209], v[34:37]
	v_mfma_f32_16x16x32_bf16 v[22:25], v[182:185], v[214:217], v[22:25]
	v_mfma_f32_16x16x32_bf16 v[18:21], v[190:193], v[214:217], v[18:21]
	v_mfma_f32_16x16x32_bf16 v[6:9], v[182:185], v[222:225], v[6:9]
	v_mfma_f32_16x16x32_bf16 v[2:5], v[190:193], v[222:225], v[2:5]
	s_barrier
; #define PG8_STAGE(bufoff, gbase, voff) do { _Pragma("unroll") for (int _i = 0; _i < 2; ++_i) \
;         __builtin_amdgcn_global_load_lds((const unsigned*)((const char*)(gbase) + (voff)[_i]), (LAS unsigned*)(lds + (bufoff) + ldsw + _i * 8192), 16, 0, 0); } while (0)
; #define PG8_BAR __builtin_amdgcn_s_barrier()
; template <class Epi, class Sched, bool ALIGN_EPI = false, bool SP2 = false>
; __device__ __forceinline__ void gemm_phase(LAS unsigned char* lds, const Gemm g, const Sched& S, const Epi& E) {
;     ...
;             PG8_LDB(B0, 1, 0); PG8_LDB(B1, 1, 1); PG8_SCHED; PG8_LDA(At, 1, 0); PG8_STAGE(PG8_SA(0, 1), a2 + hstep, voffA);
;             PG8_WAIT_V(8); PG8_WAIT_L(0); PG8_BAR; PG8_MMA(0, 0, At, B0); PG8_MMA(0, 1, At, B1); PG8_BAR; PG8_SCHED;
;             PG8_LDA(At, 1, 1); PG8_STAGE(PG8_SB(1, 0), b3, voffB); PG8_STAGE(PG8_SB(1, 1), b3 + hstepB, voffB); PG8_STAGE(PG8_SA(1, 0), a3, voffA);
;             PG8_WAIT_V(8); PG8_WAIT_L(0); PG8_BAR; PG8_MMA(1, 0, At, B0); PG8_MMA(1, 1, At, B1); PG8_BAR; PG8_SCHED;
;             } else {
;             PG8_LDB(B0, 0, 0); PG8_SCHED; PG8_LDA(At, 0, 0); PG8_STAGE(PG8_SA(1, 1), a1 + hstep, voffA);
;             PG8_WAIT_L(8); PG8_BAR; PG8_WAIT_L(0); PG8_MMA(0, 0, At, B0); PG8_BAR; PG8_SCHED;
;             PG8_LDB(B1, 0, 1); PG8_STAGE(PG8_SB(0, 0), b2, voffB);
;             PG8_BAR; PG8_WAIT_L(0); PG8_MMA(0, 1, At, B1); PG8_BAR;
;             PG8_LDA(At, 0, 1); PG8_STAGE(PG8_SA(0, 0), a2, voffA);
;             PG8_BAR; PG8_WAIT_L(0); PG8_MMA(1, 0, At, B0); PG8_BAR; PG8_SCHED;
;             PG8_STAGE(PG8_SB(0, 1), b2 + hstepB, voffB);
;             PG8_WAIT_V(6); PG8_BAR; PG8_MMA(1, 1, At, B1); PG8_BAR;
;             PG8_LDB(B0, 1, 0); PG8_SCHED; PG8_LDA(At, 1, 0); PG8_STAGE(PG8_SA(0, 1), a2 + hstep, voffA);
;             PG8_WAIT_L(8); PG8_BAR; PG8_WAIT_L(0); PG8_MMA(0, 0, At, B0); PG8_BAR; PG8_SCHED;
;             PG8_LDB(B1, 1, 1); PG8_STAGE(PG8_SB(1, 0), b3, voffB);
;             PG8_BAR; PG8_WAIT_L(0); PG8_MMA(0, 1, At, B1); PG8_BAR;
;             PG8_LDA(At, 1, 1); PG8_STAGE(PG8_SA(1, 0), a3, voffA);
;             PG8_BAR; PG8_WAIT_L(0); PG8_MMA(1, 0, At, B0); PG8_BAR; PG8_SCHED;
;             PG8_STAGE(PG8_SB(1, 1), b3 + hstepB, voffB);
;             PG8_WAIT_V(6); PG8_BAR; PG8_MMA(1, 1, At, B1); PG8_BAR;
;             }
;         }
;         if constexpr (ALIGN_EPI) { if (wr == 0) PG8_BAR; }
	s_add_i32 s54, 0, 0x18000
	s_add_i32 s55, 0, 0x1c000
	v_add_u32_e32 v78, s54, v170
	v_add_u32_e32 v168, s55, v170
	ds_read_b128 v[66:69], v78
	ds_read_b128 v[70:73], v78 offset:1024
	ds_read_b128 v[74:77], v78 offset:2048
	ds_read_b128 v[78:81], v78 offset:3072
	ds_read_b128 v[162:165], v168
	ds_read_b128 v[182:185], v168 offset:1024
	ds_read_b128 v[186:189], v168 offset:2048
	ds_read_b128 v[190:193], v168 offset:3072
	s_add_u32 s40, s40, 0x80000
	s_addc_u32 s41, s41, 0
	s_mov_b32 m0, s35
	ds_read_b128 v[194:197], v176 offset:32768
	ds_read_b128 v[198:201], v176 offset:33792
	ds_read_b128 v[202:205], v176 offset:34816
	ds_read_b128 v[206:209], v176 offset:35840
	ds_read_b128 v[210:213], v176 offset:36864
	ds_read_b128 v[214:217], v176 offset:37888
	ds_read_b128 v[218:221], v176 offset:38912
	ds_read_b128 v[222:225], v176 offset:39936
	global_load_lds_dwordx4 v152, s[40:41]
	s_mov_b32 m0, s36
	s_nop 0
	global_load_lds_dwordx4 v148, s[40:41]
	s_waitcnt vmcnt(8)
	s_waitcnt lgkmcnt(0)
	s_barrier
	s_waitcnt lgkmcnt(0)
	v_mfma_f32_16x16x32_bf16 v[142:145], v[66:69], v[194:197], v[142:145]
	v_mfma_f32_16x16x32_bf16 v[138:141], v[74:77], v[194:197], v[138:141]
	v_mfma_f32_16x16x32_bf16 v[126:129], v[66:69], v[202:205], v[126:129]
	v_mfma_f32_16x16x32_bf16 v[122:125], v[74:77], v[202:205], v[122:125]
	v_mfma_f32_16x16x32_bf16 v[110:113], v[66:69], v[210:213], v[110:113]
	v_mfma_f32_16x16x32_bf16 v[106:109], v[74:77], v[210:213], v[106:109]
	v_mfma_f32_16x16x32_bf16 v[94:97], v[66:69], v[218:221], v[94:97]
	v_mfma_f32_16x16x32_bf16 v[90:93], v[74:77], v[218:221], v[90:93]
	v_mfma_f32_16x16x32_bf16 v[142:145], v[70:73], v[198:201], v[142:145]
	v_mfma_f32_16x16x32_bf16 v[138:141], v[78:81], v[198:201], v[138:141]
	v_mfma_f32_16x16x32_bf16 v[126:129], v[70:73], v[206:209], v[126:129]
	v_mfma_f32_16x16x32_bf16 v[122:125], v[78:81], v[206:209], v[122:125]
	v_mfma_f32_16x16x32_bf16 v[110:113], v[70:73], v[214:217], v[110:113]
	v_mfma_f32_16x16x32_bf16 v[106:109], v[78:81], v[214:217], v[106:109]
	v_mfma_f32_16x16x32_bf16 v[94:97], v[70:73], v[222:225], v[94:97]
	v_mfma_f32_16x16x32_bf16 v[90:93], v[78:81], v[222:225], v[90:93]
	v_mfma_f32_16x16x32_bf16 v[134:137], v[162:165], v[194:197], v[134:137]
	v_mfma_f32_16x16x32_bf16 v[130:133], v[186:189], v[194:197], v[130:133]
	v_mfma_f32_16x16x32_bf16 v[118:121], v[162:165], v[202:205], v[118:121]
	v_mfma_f32_16x16x32_bf16 v[114:117], v[186:189], v[202:205], v[114:117]
	v_mfma_f32_16x16x32_bf16 v[102:105], v[162:165], v[210:213], v[102:105]
	v_mfma_f32_16x16x32_bf16 v[98:101], v[186:189], v[210:213], v[98:101]
	v_mfma_f32_16x16x32_bf16 v[86:89], v[162:165], v[218:221], v[86:89]
	v_mfma_f32_16x16x32_bf16 v[82:85], v[186:189], v[218:221], v[82:85]
	v_mfma_f32_16x16x32_bf16 v[134:137], v[182:185], v[198:201], v[134:137]
	v_mfma_f32_16x16x32_bf16 v[130:133], v[190:193], v[198:201], v[130:133]
	v_mfma_f32_16x16x32_bf16 v[118:121], v[182:185], v[206:209], v[118:121]
	v_mfma_f32_16x16x32_bf16 v[114:117], v[190:193], v[206:209], v[114:117]
	v_mfma_f32_16x16x32_bf16 v[102:105], v[182:185], v[214:217], v[102:105]
	v_mfma_f32_16x16x32_bf16 v[98:101], v[190:193], v[214:217], v[98:101]
	v_mfma_f32_16x16x32_bf16 v[86:89], v[182:185], v[222:225], v[86:89]
	v_mfma_f32_16x16x32_bf16 v[82:85], v[190:193], v[222:225], v[82:85]
	s_barrier
	s_add_u32 s98, s22, 0x80
	s_addc_u32 s99, s23, 0
	s_add_i32 s40, s54, s29
	s_mov_b32 m0, s40
	ds_read_b128 v[194:197], v176 offset:49152
	ds_read_b128 v[198:201], v176 offset:50176
	ds_read_b128 v[202:205], v176 offset:51200
	ds_read_b128 v[206:209], v176 offset:52224
	ds_read_b128 v[210:213], v176 offset:53248
	ds_read_b128 v[214:217], v176 offset:54272
	ds_read_b128 v[218:221], v176 offset:55296
	ds_read_b128 v[222:225], v176 offset:56320
	global_load_lds_dwordx4 v150, s[98:99]
	s_add_i32 m0, s40, 0x2000
	s_add_u32 s22, s22, 0x80080
	v_lshl_add_u64 v[166:167], v[226:227], 0, s[8:9]
	s_addc_u32 s23, s23, 0
	s_add_i32 s40, s55, s29
	global_load_lds_dwordx4 v[166:167], off
	s_mov_b32 m0, s40
	s_nop 0
	global_load_lds_dwordx4 v150, s[22:23]
	s_add_i32 m0, s40, 0x2000
	s_nop 0
	global_load_lds_dwordx4 v146, s[22:23]
	v_lshl_add_u64 v[166:167], v[228:229], 0, s[8:9]
	s_mov_b32 m0, s45
	s_nop 0
	global_load_lds_dwordx4 v[166:167], off
	v_lshl_add_u64 v[166:167], v[230:231], 0, s[8:9]
	s_mov_b32 m0, s46
	s_nop 0
	global_load_lds_dwordx4 v[166:167], off
	s_waitcnt vmcnt(8)
	s_waitcnt lgkmcnt(0)
	s_barrier
	s_waitcnt lgkmcnt(0)
	v_mfma_f32_16x16x32_bf16 v[62:65], v[66:69], v[194:197], v[62:65]
	v_mfma_f32_16x16x32_bf16 v[58:61], v[74:77], v[194:197], v[58:61]
	v_mfma_f32_16x16x32_bf16 v[46:49], v[66:69], v[202:205], v[46:49]
	v_mfma_f32_16x16x32_bf16 v[42:45], v[74:77], v[202:205], v[42:45]
	v_mfma_f32_16x16x32_bf16 v[30:33], v[66:69], v[210:213], v[30:33]
	v_mfma_f32_16x16x32_bf16 v[26:29], v[74:77], v[210:213], v[26:29]
	v_mfma_f32_16x16x32_bf16 v[14:17], v[66:69], v[218:221], v[14:17]
	v_mfma_f32_16x16x32_bf16 v[10:13], v[74:77], v[218:221], v[10:13]
	v_mfma_f32_16x16x32_bf16 v[62:65], v[70:73], v[198:201], v[62:65]
	v_mfma_f32_16x16x32_bf16 v[58:61], v[78:81], v[198:201], v[58:61]
	v_mfma_f32_16x16x32_bf16 v[46:49], v[70:73], v[206:209], v[46:49]
	v_mfma_f32_16x16x32_bf16 v[42:45], v[78:81], v[206:209], v[42:45]
	v_mfma_f32_16x16x32_bf16 v[30:33], v[70:73], v[214:217], v[30:33]
	v_mfma_f32_16x16x32_bf16 v[26:29], v[78:81], v[214:217], v[26:29]
	v_mfma_f32_16x16x32_bf16 v[14:17], v[70:73], v[222:225], v[14:17]
	v_mfma_f32_16x16x32_bf16 v[10:13], v[78:81], v[222:225], v[10:13]
	v_mfma_f32_16x16x32_bf16 v[54:57], v[162:165], v[194:197], v[54:57]
	v_mfma_f32_16x16x32_bf16 v[50:53], v[186:189], v[194:197], v[50:53]
	v_mfma_f32_16x16x32_bf16 v[38:41], v[162:165], v[202:205], v[38:41]
	v_mfma_f32_16x16x32_bf16 v[34:37], v[186:189], v[202:205], v[34:37]
	v_mfma_f32_16x16x32_bf16 v[22:25], v[162:165], v[210:213], v[22:25]
	v_mfma_f32_16x16x32_bf16 v[18:21], v[186:189], v[210:213], v[18:21]
	v_mfma_f32_16x16x32_bf16 v[6:9], v[162:165], v[218:221], v[6:9]
	v_mfma_f32_16x16x32_bf16 v[2:5], v[186:189], v[218:221], v[2:5]
	v_mfma_f32_16x16x32_bf16 v[54:57], v[182:185], v[198:201], v[54:57]
	v_mfma_f32_16x16x32_bf16 v[50:53], v[190:193], v[198:201], v[50:53]
	v_mfma_f32_16x16x32_bf16 v[38:41], v[182:185], v[206:209], v[38:41]
	v_mfma_f32_16x16x32_bf16 v[34:37], v[190:193], v[206:209], v[34:37]
	v_mfma_f32_16x16x32_bf16 v[22:25], v[182:185], v[214:217], v[22:25]
	v_mfma_f32_16x16x32_bf16 v[18:21], v[190:193], v[214:217], v[18:21]
	v_mfma_f32_16x16x32_bf16 v[6:9], v[182:185], v[222:225], v[6:9]
	v_mfma_f32_16x16x32_bf16 v[2:5], v[190:193], v[222:225], v[2:5]
	s_barrier
	s_add_i32 s53, s53, 2
	s_add_u32 s16, s16, 0x100
	s_addc_u32 s17, s17, 0
	s_add_u32 s25, s25, 0x100
	s_addc_u32 s52, s52, 0
	s_cmp_gt_u32 s53, 29
	s_cbranch_scc0 .LBB0_1465
	s_setprio 0
	s_cmpk_gt_i32 s2, 0x7f
	s_mov_b64 s[16:17], 0xb000
	s_cbranch_scc1 .LBB0_1470
	s_ashr_i32 s3, s2, 5
	s_mul_hi_i32 s17, s3, 0x2c00
	s_mul_i32 s16, s3, 0x2c00
; __device__ __forceinline__ unsigned cvt_pk_bf16(float lo, float hi) { unsigned r; asm volatile("v_cvt_pk_bf16_f32 %0, %1, %2" : "=v"(r) : "v"(lo), "v"(hi)); return r; }
; __device__ __forceinline__ float row_rstd(const float* ss, int row) { return 1.0f / sqrtf(ss[row] * (1.0f / DM) + 1e-6f); }
; __device__ __forceinline__ float silu_mul(float a, float b) { return a * b * __builtin_amdgcn_rcpf(1.0f + __builtin_amdgcn_exp2f(-a * LOG2E)); }
; #define PG8_BAR __builtin_amdgcn_s_barrier()
;     __device__ __forceinline__ void operator()(const f32x4 (&acc)[2][2][4][2], const Unit& u, int wr, int wc, int fr, int fq) const {
;         const int row0 = u.pm * BM + wr * 64 + fr, col0 = u.pn * HALF + wc * 32 + 8 * fq;
;         const int s = (u.pm < ML / BM) ? (u.pm >> 5) : 4;
;         const float* bp = bias + (size_t)s * BIAS_N + u.pn * BM + wc * 32 + 8 * fq;
;         const f32x4 ba0 = *(const f32x4*)bp, ba1 = *(const f32x4*)(bp + 4), bb0 = *(const f32x4*)(bp + HALF), bb1 = *(const f32x4*)(bp + HALF + 4);
;         const int lane = fq * 16 + fr;
;         const float rsl0 = row_rstd(ss, u.pm * BM + wr * 64 + lane), rsl1 = row_rstd(ss, u.pm * BM + HALF + wr * 64 + lane);
; #pragma unroll
;         for (int ai = 0; ai < 2; ++ai)
; #pragma unroll
;             for (int m = 0; m < 4; ++m) { const int row = row0 + ai * HALF + m * 16; const float rs = __shfl(ai ? rsl1 : rsl0, m * 16 + fr); bf16_t* rowp = O + (size_t)row * DFF + col0;
;                 const f32x4 a0 = acc[ai][0][m][0] * rs + ba0, a1 = acc[ai][0][m][1] * rs + ba1, b0 = acc[ai][1][m][0] * rs + bb0, b1 = acc[ai][1][m][1] * rs + bb1;
;                 u32x4 w; w.x = cvt_pk_bf16(silu_mul(a0[0], b0[0]), silu_mul(a0[1], b0[1])); w.y = cvt_pk_bf16(silu_mul(a0[2], b0[2]), silu_mul(a0[3], b0[3]));
;                 w.z = cvt_pk_bf16(silu_mul(a1[0], b1[0]), silu_mul(a1[1], b1[1])); w.w = cvt_pk_bf16(silu_mul(a1[2], b1[2]), silu_mul(a1[3], b1[3]));
;                 *(u32x4*)rowp = w; }
; template <class Epi, class Sched, bool ALIGN_EPI = false, bool SP2 = false>
; __device__ __forceinline__ void gemm_phase(LAS unsigned char* lds, const Gemm g, const Sched& S, const Epi& E) {
;     ...
;         if constexpr (ALIGN_EPI) { if (wr == 0) PG8_BAR; }
;         if constexpr (!Epi::AFTER_DRAIN) { E(acc, cur, wr, wc, fr, fq); S.done(cur); }
.LBB0_1470:
	s_lshl_b32 s2, s2, 8
	s_add_i32 s13, s2, s42
	s_lshl_b64 s[2:3], s[16:17], 2
	s_add_u32 s15, s43, s2
	s_addc_u32 s16, s44, s3
	s_lshl_b32 s2, s0, 8
	s_ashr_i32 s3, s2, 31
	s_lshl_b64 s[2:3], s[2:3], 2
	v_lshl_or_b32 v164, s0, 7, v173
	s_add_u32 s0, s15, s2
	s_addc_u32 s3, s16, s3
	v_or_b32_e32 v162, s13, v171
	s_add_u32 s2, s0, s50
	v_ashrrev_i32_e32 v163, 31, v162
	s_addc_u32 s3, s3, 0
	v_lshl_add_u64 v[162:163], v[162:163], 2, s[64:65]
	v_mov_b32_e32 v74, v234
	v_mov_b32_e32 v75, v235
	v_mov_b32_e32 v76, v236
	v_mov_b32_e32 v77, v237
	v_mov_b32_e32 v78, v238
	v_mov_b32_e32 v79, v239
	v_mov_b32_e32 v80, v240
	v_mov_b32_e32 v81, v241
	v_mov_b32_e32 v66, v242
	v_mov_b32_e32 v67, v243
	v_mov_b32_e32 v68, v244
	v_mov_b32_e32 v69, v245
	v_mov_b32_e32 v70, v246
	v_mov_b32_e32 v71, v247
	v_mov_b32_e32 v72, v248
	v_mov_b32_e32 v73, v249
	v_or_b32_e32 v181, s13, v169
	v_mov_b32_e32 v162, v250
	s_waitcnt vmcnt(0)
	v_fmamk_f32 v162, v162, 0x3a000000, v178
	v_cmp_gt_f32_e32 vcc, s51, v162
	v_mul_f32_e32 v163, 0x4f800000, v162
	s_nop 0
	v_cndmask_b32_e32 v162, v162, v163, vcc
	v_sqrt_f32_e32 v163, v162
	s_nop 0
	v_add_u32_e32 v165, -1, v163
	v_fma_f32 v166, -v165, v163, v162
	v_cmp_ge_f32_e64 s[2:3], 0, v166
	v_add_u32_e32 v166, 1, v163
	s_nop 0
	v_cndmask_b32_e64 v165, v163, v165, s[2:3]
	v_fma_f32 v163, -v166, v163, v162
	v_cmp_lt_f32_e64 s[2:3], 0, v163
	s_nop 1
	v_cndmask_b32_e64 v163, v165, v166, s[2:3]
	v_mul_f32_e32 v165, 0x37800000, v163
	v_cndmask_b32_e32 v163, v163, v165, vcc
	v_cmp_class_f32_e32 vcc, v162, v179
	s_nop 1
	v_cndmask_b32_e32 v166, v163, v162, vcc
	v_add_u32_e32 v162, s13, v172
	v_ashrrev_i32_e32 v163, 31, v162
	v_lshl_add_u64 v[162:163], v[162:163], 2, s[64:65]
	v_mov_b32_e32 v162, v251
	v_fmamk_f32 v162, v162, 0x3a000000, v178
	v_cmp_gt_f32_e32 vcc, s51, v162
	v_mul_f32_e32 v163, 0x4f800000, v162
	s_nop 0
	v_cndmask_b32_e32 v162, v162, v163, vcc
	v_sqrt_f32_e32 v163, v162
	s_nop 0
	v_add_u32_e32 v165, -1, v163
	v_fma_f32 v167, -v165, v163, v162
	v_cmp_ge_f32_e64 s[2:3], 0, v167
	v_add_u32_e32 v167, 1, v163
	s_nop 0
	v_cndmask_b32_e64 v165, v163, v165, s[2:3]
	v_fma_f32 v163, -v167, v163, v162
	v_cmp_lt_f32_e64 s[2:3], 0, v163
	s_nop 1
	v_cndmask_b32_e64 v163, v165, v167, s[2:3]
	v_mul_f32_e32 v165, 0x37800000, v163
	v_cndmask_b32_e32 v163, v163, v165, vcc
	v_cmp_class_f32_e32 vcc, v162, v179
	v_ashrrev_i32_e32 v165, 31, v164
	v_lshlrev_b64 v[164:165], 1, v[164:165]
	v_cndmask_b32_e32 v182, v163, v162, vcc
	v_div_scale_f32 v162, s[2:3], v166, v166, 1.0
	v_rcp_f32_e32 v163, v162
	s_nop 0
	v_fma_f32 v167, -v162, v163, 1.0
	v_fmac_f32_e32 v163, v167, v163
	v_div_scale_f32 v167, vcc, 1.0, v166, 1.0
	v_mul_f32_e32 v168, v167, v163
	v_fma_f32 v183, -v162, v168, v167
	v_fmac_f32_e32 v168, v183, v163
	v_fma_f32 v162, -v162, v168, v167
	v_div_fmas_f32 v162, v162, v163, v168
	v_div_fixup_f32 v183, v162, v166, 1.0
	s_and_b64 vcc, exec, s[10:11]
	s_cbranch_vccz .Lalign_1468
	s_barrier
.Lalign_1468:
	s_mov_b32 s100, 0xbfb8aa3b
	ds_bpermute_b32 v242, v180, v183
	ds_bpermute_b32 v244, v180, v183 offset:64
	ds_bpermute_b32 v246, v180, v183 offset:128
	ds_bpermute_b32 v248, v180, v183 offset:192
	v_mov_b64_e32 v[162:163], s[96:97]
	v_mad_i64_i32 v[166:167], s[2:3], v181, s49, v[162:163]
	v_lshl_add_u64 v[166:167], v[166:167], 0, v[164:165]
	s_waitcnt lgkmcnt(0)
	v_pk_fma_f32 v[142:143], v[142:143], v[242:243], v[78:79] op_sel_hi:[1,0,1]
	v_pk_fma_f32 v[144:145], v[144:145], v[242:243], v[80:81] op_sel_hi:[1,0,1]
	v_pk_fma_f32 v[134:135], v[134:135], v[242:243], v[70:71] op_sel_hi:[1,0,1]
	v_pk_fma_f32 v[136:137], v[136:137], v[242:243], v[72:73] op_sel_hi:[1,0,1]
	v_pk_fma_f32 v[138:139], v[138:139], v[242:243], v[74:75] op_sel_hi:[1,0,1]
	v_pk_fma_f32 v[140:141], v[140:141], v[242:243], v[76:77] op_sel_hi:[1,0,1]
	v_pk_fma_f32 v[130:131], v[130:131], v[242:243], v[66:67] op_sel_hi:[1,0,1]
	v_pk_fma_f32 v[132:133], v[132:133], v[242:243], v[68:69] op_sel_hi:[1,0,1]
	v_pk_mul_f32 v[234:235], v[142:143], s[100:101] op_sel_hi:[1,0]
	v_pk_mul_f32 v[236:237], v[144:145], s[100:101] op_sel_hi:[1,0]
	v_exp_f32_e32 v234, v234
	v_exp_f32_e32 v235, v235
	v_exp_f32_e32 v236, v236
	v_exp_f32_e32 v237, v237
	v_pk_add_f32 v[234:235], v[234:235], 1.0 op_sel_hi:[1,0]
	v_pk_add_f32 v[236:237], v[236:237], 1.0 op_sel_hi:[1,0]
	v_rcp_f32_e32 v234, v234
	v_rcp_f32_e32 v235, v235
	v_rcp_f32_e32 v236, v236
	v_rcp_f32_e32 v237, v237
	v_pk_mul_f32 v[134:135], v[142:143], v[134:135]
	v_pk_mul_f32 v[136:137], v[144:145], v[136:137]
	v_pk_mul_f32 v[134:135], v[134:135], v[234:235]
	v_pk_mul_f32 v[136:137], v[136:137], v[236:237]
	v_cvt_pk_bf16_f32 v238, v134, v135
	v_cvt_pk_bf16_f32 v239, v136, v137
	v_pk_mul_f32 v[234:235], v[138:139], s[100:101] op_sel_hi:[1,0]
	v_pk_mul_f32 v[236:237], v[140:141], s[100:101] op_sel_hi:[1,0]
	v_exp_f32_e32 v234, v234
	v_exp_f32_e32 v235, v235
	v_exp_f32_e32 v236, v236
	v_exp_f32_e32 v237, v237
	v_pk_add_f32 v[234:235], v[234:235], 1.0 op_sel_hi:[1,0]
	v_pk_add_f32 v[236:237], v[236:237], 1.0 op_sel_hi:[1,0]
	v_rcp_f32_e32 v234, v234
	v_rcp_f32_e32 v235, v235
	v_rcp_f32_e32 v236, v236
	v_rcp_f32_e32 v237, v237
	v_pk_mul_f32 v[130:131], v[138:139], v[130:131]
	v_pk_mul_f32 v[132:133], v[140:141], v[132:133]
	v_pk_mul_f32 v[130:131], v[130:131], v[234:235]
	v_pk_mul_f32 v[132:133], v[132:133], v[236:237]
	v_cvt_pk_bf16_f32 v240, v130, v131
	v_cvt_pk_bf16_f32 v241, v132, v133
	global_store_dwordx4 v[166:167], v[238:241], off
	v_or_b32_e32 v131, 16, v181
	v_mad_i64_i32 v[132:133], s[2:3], v131, s49, v[162:163]
	v_lshl_add_u64 v[132:133], v[132:133], 0, v[164:165]
	v_pk_fma_f32 v[126:127], v[126:127], v[244:245], v[78:79] op_sel_hi:[1,0,1]
; __device__ __forceinline__ unsigned cvt_pk_bf16(float lo, float hi) { unsigned r; asm volatile("v_cvt_pk_bf16_f32 %0, %1, %2" : "=v"(r) : "v"(lo), "v"(hi)); return r; }
; __device__ __forceinline__ float silu_mul(float a, float b) { return a * b * __builtin_amdgcn_rcpf(1.0f + __builtin_amdgcn_exp2f(-a * LOG2E)); }
;     __device__ __forceinline__ void operator()(const f32x4 (&acc)[2][2][4][2], const Unit& u, int wr, int wc, int fr, int fq) const {
;     ...
;         for (int ai = 0; ai < 2; ++ai)
; #pragma unroll
;             for (int m = 0; m < 4; ++m) { const int row = row0 + ai * HALF + m * 16; const float rs = __shfl(ai ? rsl1 : rsl0, m * 16 + fr); bf16_t* rowp = O + (size_t)row * DFF + col0;
;                 const f32x4 a0 = acc[ai][0][m][0] * rs + ba0, a1 = acc[ai][0][m][1] * rs + ba1, b0 = acc[ai][1][m][0] * rs + bb0, b1 = acc[ai][1][m][1] * rs + bb1;
;                 u32x4 w; w.x = cvt_pk_bf16(silu_mul(a0[0], b0[0]), silu_mul(a0[1], b0[1])); w.y = cvt_pk_bf16(silu_mul(a0[2], b0[2]), silu_mul(a0[3], b0[3]));
;                 w.z = cvt_pk_bf16(silu_mul(a1[0], b1[0]), silu_mul(a1[1], b1[1])); w.w = cvt_pk_bf16(silu_mul(a1[2], b1[2]), silu_mul(a1[3], b1[3]));
;                 *(u32x4*)rowp = w; }
	v_pk_fma_f32 v[128:129], v[128:129], v[244:245], v[80:81] op_sel_hi:[1,0,1]
	v_pk_fma_f32 v[118:119], v[118:119], v[244:245], v[70:71] op_sel_hi:[1,0,1]
	v_pk_fma_f32 v[120:121], v[120:121], v[244:245], v[72:73] op_sel_hi:[1,0,1]
	v_pk_fma_f32 v[122:123], v[122:123], v[244:245], v[74:75] op_sel_hi:[1,0,1]
	v_pk_fma_f32 v[124:125], v[124:125], v[244:245], v[76:77] op_sel_hi:[1,0,1]
	v_pk_fma_f32 v[114:115], v[114:115], v[244:245], v[66:67] op_sel_hi:[1,0,1]
	v_pk_fma_f32 v[116:117], v[116:117], v[244:245], v[68:69] op_sel_hi:[1,0,1]
	v_pk_mul_f32 v[234:235], v[126:127], s[100:101] op_sel_hi:[1,0]
	v_pk_mul_f32 v[236:237], v[128:129], s[100:101] op_sel_hi:[1,0]
	v_exp_f32_e32 v234, v234
	v_exp_f32_e32 v235, v235
	v_exp_f32_e32 v236, v236
	v_exp_f32_e32 v237, v237
	v_pk_add_f32 v[234:235], v[234:235], 1.0 op_sel_hi:[1,0]
	v_pk_add_f32 v[236:237], v[236:237], 1.0 op_sel_hi:[1,0]
	v_rcp_f32_e32 v234, v234
	v_rcp_f32_e32 v235, v235
	v_rcp_f32_e32 v236, v236
	v_rcp_f32_e32 v237, v237
	v_pk_mul_f32 v[118:119], v[126:127], v[118:119]
	v_pk_mul_f32 v[120:121], v[128:129], v[120:121]
	v_pk_mul_f32 v[118:119], v[118:119], v[234:235]
	v_pk_mul_f32 v[120:121], v[120:121], v[236:237]
	v_cvt_pk_bf16_f32 v238, v118, v119
	v_cvt_pk_bf16_f32 v239, v120, v121
	v_pk_mul_f32 v[234:235], v[122:123], s[100:101] op_sel_hi:[1,0]
	v_pk_mul_f32 v[236:237], v[124:125], s[100:101] op_sel_hi:[1,0]
	v_exp_f32_e32 v234, v234
	v_exp_f32_e32 v235, v235
	v_exp_f32_e32 v236, v236
	v_exp_f32_e32 v237, v237
	v_pk_add_f32 v[234:235], v[234:235], 1.0 op_sel_hi:[1,0]
	v_pk_add_f32 v[236:237], v[236:237], 1.0 op_sel_hi:[1,0]
	v_rcp_f32_e32 v234, v234
	v_rcp_f32_e32 v235, v235
	v_rcp_f32_e32 v236, v236
	v_rcp_f32_e32 v237, v237
	v_pk_mul_f32 v[114:115], v[122:123], v[114:115]
	v_pk_mul_f32 v[116:117], v[124:125], v[116:117]
	v_pk_mul_f32 v[114:115], v[114:115], v[234:235]
	v_pk_mul_f32 v[116:117], v[116:117], v[236:237]
	v_cvt_pk_bf16_f32 v240, v114, v115
	v_cvt_pk_bf16_f32 v241, v116, v117
	global_store_dwordx4 v[132:133], v[238:241], off
	v_or_b32_e32 v115, 32, v181
	v_mad_i64_i32 v[116:117], s[2:3], v115, s49, v[162:163]
	v_lshl_add_u64 v[116:117], v[116:117], 0, v[164:165]
	v_pk_fma_f32 v[110:111], v[110:111], v[246:247], v[78:79] op_sel_hi:[1,0,1]
	v_pk_fma_f32 v[112:113], v[112:113], v[246:247], v[80:81] op_sel_hi:[1,0,1]
	v_pk_fma_f32 v[102:103], v[102:103], v[246:247], v[70:71] op_sel_hi:[1,0,1]
	v_pk_fma_f32 v[104:105], v[104:105], v[246:247], v[72:73] op_sel_hi:[1,0,1]
	v_pk_fma_f32 v[106:107], v[106:107], v[246:247], v[74:75] op_sel_hi:[1,0,1]
	v_pk_fma_f32 v[108:109], v[108:109], v[246:247], v[76:77] op_sel_hi:[1,0,1]
	v_pk_fma_f32 v[98:99], v[98:99], v[246:247], v[66:67] op_sel_hi:[1,0,1]
	v_pk_fma_f32 v[100:101], v[100:101], v[246:247], v[68:69] op_sel_hi:[1,0,1]
	v_pk_mul_f32 v[234:235], v[110:111], s[100:101] op_sel_hi:[1,0]
	v_pk_mul_f32 v[236:237], v[112:113], s[100:101] op_sel_hi:[1,0]
	v_exp_f32_e32 v234, v234
	v_exp_f32_e32 v235, v235
	v_exp_f32_e32 v236, v236
	v_exp_f32_e32 v237, v237
	v_pk_add_f32 v[234:235], v[234:235], 1.0 op_sel_hi:[1,0]
	v_pk_add_f32 v[236:237], v[236:237], 1.0 op_sel_hi:[1,0]
	v_rcp_f32_e32 v234, v234
	v_rcp_f32_e32 v235, v235
	v_rcp_f32_e32 v236, v236
	v_rcp_f32_e32 v237, v237
	v_pk_mul_f32 v[102:103], v[110:111], v[102:103]
	v_pk_mul_f32 v[104:105], v[112:113], v[104:105]
	v_pk_mul_f32 v[102:103], v[102:103], v[234:235]
	v_pk_mul_f32 v[104:105], v[104:105], v[236:237]
	v_cvt_pk_bf16_f32 v238, v102, v103
	v_cvt_pk_bf16_f32 v239, v104, v105
	v_pk_mul_f32 v[234:235], v[106:107], s[100:101] op_sel_hi:[1,0]
	v_pk_mul_f32 v[236:237], v[108:109], s[100:101] op_sel_hi:[1,0]
	v_exp_f32_e32 v234, v234
	v_exp_f32_e32 v235, v235
	v_exp_f32_e32 v236, v236
	v_exp_f32_e32 v237, v237
	v_pk_add_f32 v[234:235], v[234:235], 1.0 op_sel_hi:[1,0]
	v_pk_add_f32 v[236:237], v[236:237], 1.0 op_sel_hi:[1,0]
	v_rcp_f32_e32 v234, v234
	v_rcp_f32_e32 v235, v235
	v_rcp_f32_e32 v236, v236
	v_rcp_f32_e32 v237, v237
	v_pk_mul_f32 v[98:99], v[106:107], v[98:99]
	v_pk_mul_f32 v[100:101], v[108:109], v[100:101]
	v_pk_mul_f32 v[98:99], v[98:99], v[234:235]
	v_pk_mul_f32 v[100:101], v[100:101], v[236:237]
	v_cvt_pk_bf16_f32 v240, v98, v99
	v_cvt_pk_bf16_f32 v241, v100, v101
	global_store_dwordx4 v[116:117], v[238:241], off
	v_or_b32_e32 v99, 48, v181
	v_mad_i64_i32 v[100:101], s[2:3], v99, s49, v[162:163]
	v_lshl_add_u64 v[100:101], v[100:101], 0, v[164:165]
	v_pk_fma_f32 v[94:95], v[94:95], v[248:249], v[78:79] op_sel_hi:[1,0,1]
	v_pk_fma_f32 v[96:97], v[96:97], v[248:249], v[80:81] op_sel_hi:[1,0,1]
	v_pk_fma_f32 v[86:87], v[86:87], v[248:249], v[70:71] op_sel_hi:[1,0,1]
	v_pk_fma_f32 v[88:89], v[88:89], v[248:249], v[72:73] op_sel_hi:[1,0,1]
	v_pk_fma_f32 v[90:91], v[90:91], v[248:249], v[74:75] op_sel_hi:[1,0,1]
	v_pk_fma_f32 v[92:93], v[92:93], v[248:249], v[76:77] op_sel_hi:[1,0,1]
	v_pk_fma_f32 v[82:83], v[82:83], v[248:249], v[66:67] op_sel_hi:[1,0,1]
	v_pk_fma_f32 v[84:85], v[84:85], v[248:249], v[68:69] op_sel_hi:[1,0,1]
	v_pk_mul_f32 v[234:235], v[94:95], s[100:101] op_sel_hi:[1,0]
	v_pk_mul_f32 v[236:237], v[96:97], s[100:101] op_sel_hi:[1,0]
	v_exp_f32_e32 v234, v234
	v_exp_f32_e32 v235, v235
	v_exp_f32_e32 v236, v236
	v_exp_f32_e32 v237, v237
	v_pk_add_f32 v[234:235], v[234:235], 1.0 op_sel_hi:[1,0]
	v_pk_add_f32 v[236:237], v[236:237], 1.0 op_sel_hi:[1,0]
	v_rcp_f32_e32 v234, v234
	v_rcp_f32_e32 v235, v235
	v_rcp_f32_e32 v236, v236
	v_rcp_f32_e32 v237, v237
	v_pk_mul_f32 v[86:87], v[94:95], v[86:87]
	v_pk_mul_f32 v[88:89], v[96:97], v[88:89]
	v_pk_mul_f32 v[86:87], v[86:87], v[234:235]
	v_pk_mul_f32 v[88:89], v[88:89], v[236:237]
	v_cvt_pk_bf16_f32 v238, v86, v87
; __device__ __forceinline__ unsigned cvt_pk_bf16(float lo, float hi) { unsigned r; asm volatile("v_cvt_pk_bf16_f32 %0, %1, %2" : "=v"(r) : "v"(lo), "v"(hi)); return r; }
; __device__ __forceinline__ float row_rstd(const float* ss, int row) { return 1.0f / sqrtf(ss[row] * (1.0f / DM) + 1e-6f); }
; __device__ __forceinline__ float silu_mul(float a, float b) { return a * b * __builtin_amdgcn_rcpf(1.0f + __builtin_amdgcn_exp2f(-a * LOG2E)); }
;     __device__ __forceinline__ void operator()(const f32x4 (&acc)[2][2][4][2], const Unit& u, int wr, int wc, int fr, int fq) const {
;     ...
;         const float rsl0 = row_rstd(ss, u.pm * BM + wr * 64 + lane), rsl1 = row_rstd(ss, u.pm * BM + HALF + wr * 64 + lane);
;     ...
;         for (int ai = 0; ai < 2; ++ai)
; #pragma unroll
;             for (int m = 0; m < 4; ++m) { const int row = row0 + ai * HALF + m * 16; const float rs = __shfl(ai ? rsl1 : rsl0, m * 16 + fr); bf16_t* rowp = O + (size_t)row * DFF + col0;
;                 const f32x4 a0 = acc[ai][0][m][0] * rs + ba0, a1 = acc[ai][0][m][1] * rs + ba1, b0 = acc[ai][1][m][0] * rs + bb0, b1 = acc[ai][1][m][1] * rs + bb1;
;                 u32x4 w; w.x = cvt_pk_bf16(silu_mul(a0[0], b0[0]), silu_mul(a0[1], b0[1])); w.y = cvt_pk_bf16(silu_mul(a0[2], b0[2]), silu_mul(a0[3], b0[3]));
;                 w.z = cvt_pk_bf16(silu_mul(a1[0], b1[0]), silu_mul(a1[1], b1[1])); w.w = cvt_pk_bf16(silu_mul(a1[2], b1[2]), silu_mul(a1[3], b1[3]));
;                 *(u32x4*)rowp = w; }
	v_cvt_pk_bf16_f32 v239, v88, v89
	v_pk_mul_f32 v[234:235], v[90:91], s[100:101] op_sel_hi:[1,0]
	v_pk_mul_f32 v[236:237], v[92:93], s[100:101] op_sel_hi:[1,0]
	v_exp_f32_e32 v234, v234
	v_exp_f32_e32 v235, v235
	v_exp_f32_e32 v236, v236
	v_exp_f32_e32 v237, v237
	v_pk_add_f32 v[234:235], v[234:235], 1.0 op_sel_hi:[1,0]
	v_pk_add_f32 v[236:237], v[236:237], 1.0 op_sel_hi:[1,0]
	v_rcp_f32_e32 v234, v234
	v_rcp_f32_e32 v235, v235
	v_rcp_f32_e32 v236, v236
	v_rcp_f32_e32 v237, v237
	v_pk_mul_f32 v[82:83], v[90:91], v[82:83]
	v_pk_mul_f32 v[84:85], v[92:93], v[84:85]
	v_pk_mul_f32 v[82:83], v[82:83], v[234:235]
	v_pk_mul_f32 v[84:85], v[84:85], v[236:237]
	v_cvt_pk_bf16_f32 v240, v82, v83
	v_cvt_pk_bf16_f32 v241, v84, v85
	global_store_dwordx4 v[100:101], v[238:241], off
	s_nop 1
	v_div_scale_f32 v82, s[2:3], v182, v182, 1.0
	v_rcp_f32_e32 v84, v82
	v_add_u32_e32 v83, 0x80, v181
	v_fma_f32 v85, -v82, v84, 1.0
	v_fmac_f32_e32 v84, v85, v84
	v_div_scale_f32 v85, vcc, 1.0, v182, 1.0
	v_mul_f32_e32 v86, v85, v84
	v_fma_f32 v87, -v82, v86, v85
	v_fmac_f32_e32 v86, v87, v84
	v_fma_f32 v82, -v82, v86, v85
	v_div_fmas_f32 v82, v82, v84, v86
	v_div_fixup_f32 v82, v82, v182, 1.0
	ds_bpermute_b32 v242, v180, v82
	ds_bpermute_b32 v244, v180, v82 offset:64
	ds_bpermute_b32 v246, v180, v82 offset:128
	ds_bpermute_b32 v248, v180, v82 offset:192
	v_mad_i64_i32 v[86:87], s[2:3], v83, s49, v[162:163]
	v_lshl_add_u64 v[86:87], v[86:87], 0, v[164:165]
	s_andn2_b64 vcc, exec, s[38:39]
	s_waitcnt lgkmcnt(0)
	v_pk_fma_f32 v[62:63], v[62:63], v[242:243], v[78:79] op_sel_hi:[1,0,1]
	v_pk_fma_f32 v[64:65], v[64:65], v[242:243], v[80:81] op_sel_hi:[1,0,1]
	v_pk_fma_f32 v[54:55], v[54:55], v[242:243], v[70:71] op_sel_hi:[1,0,1]
	v_pk_fma_f32 v[56:57], v[56:57], v[242:243], v[72:73] op_sel_hi:[1,0,1]
	v_pk_fma_f32 v[58:59], v[58:59], v[242:243], v[74:75] op_sel_hi:[1,0,1]
	v_pk_fma_f32 v[60:61], v[60:61], v[242:243], v[76:77] op_sel_hi:[1,0,1]
	v_pk_fma_f32 v[50:51], v[50:51], v[242:243], v[66:67] op_sel_hi:[1,0,1]
	v_pk_fma_f32 v[52:53], v[52:53], v[242:243], v[68:69] op_sel_hi:[1,0,1]
	v_pk_mul_f32 v[234:235], v[62:63], s[100:101] op_sel_hi:[1,0]
	v_pk_mul_f32 v[236:237], v[64:65], s[100:101] op_sel_hi:[1,0]
	v_exp_f32_e32 v234, v234
	v_exp_f32_e32 v235, v235
	v_exp_f32_e32 v236, v236
	v_exp_f32_e32 v237, v237
	v_pk_add_f32 v[234:235], v[234:235], 1.0 op_sel_hi:[1,0]
	v_pk_add_f32 v[236:237], v[236:237], 1.0 op_sel_hi:[1,0]
	v_rcp_f32_e32 v234, v234
	v_rcp_f32_e32 v235, v235
	v_rcp_f32_e32 v236, v236
	v_rcp_f32_e32 v237, v237
	v_pk_mul_f32 v[54:55], v[62:63], v[54:55]
	v_pk_mul_f32 v[56:57], v[64:65], v[56:57]
	v_pk_mul_f32 v[54:55], v[54:55], v[234:235]
	v_pk_mul_f32 v[56:57], v[56:57], v[236:237]
	v_cvt_pk_bf16_f32 v238, v54, v55
	v_cvt_pk_bf16_f32 v239, v56, v57
	v_pk_mul_f32 v[234:235], v[58:59], s[100:101] op_sel_hi:[1,0]
	v_pk_mul_f32 v[236:237], v[60:61], s[100:101] op_sel_hi:[1,0]
	v_exp_f32_e32 v234, v234
	v_exp_f32_e32 v235, v235
	v_exp_f32_e32 v236, v236
	v_exp_f32_e32 v237, v237
	v_pk_add_f32 v[234:235], v[234:235], 1.0 op_sel_hi:[1,0]
	v_pk_add_f32 v[236:237], v[236:237], 1.0 op_sel_hi:[1,0]
	v_rcp_f32_e32 v234, v234
	v_rcp_f32_e32 v235, v235
	v_rcp_f32_e32 v236, v236
	v_rcp_f32_e32 v237, v237
	v_pk_mul_f32 v[50:51], v[58:59], v[50:51]
	v_pk_mul_f32 v[52:53], v[60:61], v[52:53]
	v_pk_mul_f32 v[50:51], v[50:51], v[234:235]
	v_pk_mul_f32 v[52:53], v[52:53], v[236:237]
	v_cvt_pk_bf16_f32 v240, v50, v51
	v_cvt_pk_bf16_f32 v241, v52, v53
	global_store_dwordx4 v[86:87], v[238:241], off
	v_add_u32_e32 v51, 0x90, v181
	v_mad_i64_i32 v[52:53], s[2:3], v51, s49, v[162:163]
	v_lshl_add_u64 v[52:53], v[52:53], 0, v[164:165]
	v_pk_fma_f32 v[46:47], v[46:47], v[244:245], v[78:79] op_sel_hi:[1,0,1]
	v_pk_fma_f32 v[48:49], v[48:49], v[244:245], v[80:81] op_sel_hi:[1,0,1]
	v_pk_fma_f32 v[38:39], v[38:39], v[244:245], v[70:71] op_sel_hi:[1,0,1]
	v_pk_fma_f32 v[40:41], v[40:41], v[244:245], v[72:73] op_sel_hi:[1,0,1]
	v_pk_fma_f32 v[42:43], v[42:43], v[244:245], v[74:75] op_sel_hi:[1,0,1]
	v_pk_fma_f32 v[44:45], v[44:45], v[244:245], v[76:77] op_sel_hi:[1,0,1]
	v_pk_fma_f32 v[34:35], v[34:35], v[244:245], v[66:67] op_sel_hi:[1,0,1]
	v_pk_fma_f32 v[36:37], v[36:37], v[244:245], v[68:69] op_sel_hi:[1,0,1]
	v_pk_mul_f32 v[234:235], v[46:47], s[100:101] op_sel_hi:[1,0]
	v_pk_mul_f32 v[236:237], v[48:49], s[100:101] op_sel_hi:[1,0]
	v_exp_f32_e32 v234, v234
	v_exp_f32_e32 v235, v235
	v_exp_f32_e32 v236, v236
	v_exp_f32_e32 v237, v237
	v_pk_add_f32 v[234:235], v[234:235], 1.0 op_sel_hi:[1,0]
	v_pk_add_f32 v[236:237], v[236:237], 1.0 op_sel_hi:[1,0]
	v_rcp_f32_e32 v234, v234
	v_rcp_f32_e32 v235, v235
	v_rcp_f32_e32 v236, v236
	v_rcp_f32_e32 v237, v237
	v_pk_mul_f32 v[38:39], v[46:47], v[38:39]
	v_pk_mul_f32 v[40:41], v[48:49], v[40:41]
	v_pk_mul_f32 v[38:39], v[38:39], v[234:235]
	v_pk_mul_f32 v[40:41], v[40:41], v[236:237]
	v_cvt_pk_bf16_f32 v238, v38, v39
	v_cvt_pk_bf16_f32 v239, v40, v41
	v_pk_mul_f32 v[234:235], v[42:43], s[100:101] op_sel_hi:[1,0]
	v_pk_mul_f32 v[236:237], v[44:45], s[100:101] op_sel_hi:[1,0]
; __device__ __forceinline__ unsigned cvt_pk_bf16(float lo, float hi) { unsigned r; asm volatile("v_cvt_pk_bf16_f32 %0, %1, %2" : "=v"(r) : "v"(lo), "v"(hi)); return r; }
; __device__ __forceinline__ float silu_mul(float a, float b) { return a * b * __builtin_amdgcn_rcpf(1.0f + __builtin_amdgcn_exp2f(-a * LOG2E)); }
; #define PG8_BAR __builtin_amdgcn_s_barrier()
;     __device__ __forceinline__ void operator()(const f32x4 (&acc)[2][2][4][2], const Unit& u, int wr, int wc, int fr, int fq) const {
;     ...
;         for (int ai = 0; ai < 2; ++ai)
; #pragma unroll
;             for (int m = 0; m < 4; ++m) { const int row = row0 + ai * HALF + m * 16; const float rs = __shfl(ai ? rsl1 : rsl0, m * 16 + fr); bf16_t* rowp = O + (size_t)row * DFF + col0;
;                 const f32x4 a0 = acc[ai][0][m][0] * rs + ba0, a1 = acc[ai][0][m][1] * rs + ba1, b0 = acc[ai][1][m][0] * rs + bb0, b1 = acc[ai][1][m][1] * rs + bb1;
;                 u32x4 w; w.x = cvt_pk_bf16(silu_mul(a0[0], b0[0]), silu_mul(a0[1], b0[1])); w.y = cvt_pk_bf16(silu_mul(a0[2], b0[2]), silu_mul(a0[3], b0[3]));
;                 w.z = cvt_pk_bf16(silu_mul(a1[0], b1[0]), silu_mul(a1[1], b1[1])); w.w = cvt_pk_bf16(silu_mul(a1[2], b1[2]), silu_mul(a1[3], b1[3]));
;                 *(u32x4*)rowp = w; }
; template <class Epi, class Sched, bool ALIGN_EPI = false, bool SP2 = false>
; __device__ __forceinline__ void gemm_phase(LAS unsigned char* lds, const Gemm g, const Sched& S, const Epi& E) {
;     ...
;         if (!has_next) break;
; #pragma unroll
;         for (int a = 0; a < 2; ++a)
; #pragma unroll
;             for (int b = 0; b < 2; ++b)
; #pragma unroll
;                 for (int m = 0; m < 4; ++m)
; #pragma unroll
;                     for (int n = 0; n < 2; ++n) acc[a][b][m][n] = (f32x4){0.f, 0.f, 0.f, 0.f};
;         cur = nxt; cA = nA; cB = nB; ++ui;
;         if constexpr (ALIGN_EPI) { if (wr == 1) PG8_BAR; }
	v_exp_f32_e32 v234, v234
	v_exp_f32_e32 v235, v235
	v_exp_f32_e32 v236, v236
	v_exp_f32_e32 v237, v237
	v_pk_add_f32 v[234:235], v[234:235], 1.0 op_sel_hi:[1,0]
	v_pk_add_f32 v[236:237], v[236:237], 1.0 op_sel_hi:[1,0]
	v_rcp_f32_e32 v234, v234
	v_rcp_f32_e32 v235, v235
	v_rcp_f32_e32 v236, v236
	v_rcp_f32_e32 v237, v237
	v_pk_mul_f32 v[34:35], v[42:43], v[34:35]
	v_pk_mul_f32 v[36:37], v[44:45], v[36:37]
	v_pk_mul_f32 v[34:35], v[34:35], v[234:235]
	v_pk_mul_f32 v[36:37], v[36:37], v[236:237]
	v_cvt_pk_bf16_f32 v240, v34, v35
	v_cvt_pk_bf16_f32 v241, v36, v37
	global_store_dwordx4 v[52:53], v[238:241], off
	v_add_u32_e32 v35, 0xa0, v181
	v_mad_i64_i32 v[36:37], s[2:3], v35, s49, v[162:163]
	v_lshl_add_u64 v[36:37], v[36:37], 0, v[164:165]
	v_pk_fma_f32 v[30:31], v[30:31], v[246:247], v[78:79] op_sel_hi:[1,0,1]
	v_pk_fma_f32 v[32:33], v[32:33], v[246:247], v[80:81] op_sel_hi:[1,0,1]
	v_pk_fma_f32 v[22:23], v[22:23], v[246:247], v[70:71] op_sel_hi:[1,0,1]
	v_pk_fma_f32 v[24:25], v[24:25], v[246:247], v[72:73] op_sel_hi:[1,0,1]
	v_pk_fma_f32 v[26:27], v[26:27], v[246:247], v[74:75] op_sel_hi:[1,0,1]
	v_pk_fma_f32 v[28:29], v[28:29], v[246:247], v[76:77] op_sel_hi:[1,0,1]
	v_pk_fma_f32 v[18:19], v[18:19], v[246:247], v[66:67] op_sel_hi:[1,0,1]
	v_pk_fma_f32 v[20:21], v[20:21], v[246:247], v[68:69] op_sel_hi:[1,0,1]
	v_pk_mul_f32 v[234:235], v[30:31], s[100:101] op_sel_hi:[1,0]
	v_pk_mul_f32 v[236:237], v[32:33], s[100:101] op_sel_hi:[1,0]
	v_exp_f32_e32 v234, v234
	v_exp_f32_e32 v235, v235
	v_exp_f32_e32 v236, v236
	v_exp_f32_e32 v237, v237
	v_pk_add_f32 v[234:235], v[234:235], 1.0 op_sel_hi:[1,0]
	v_pk_add_f32 v[236:237], v[236:237], 1.0 op_sel_hi:[1,0]
	v_rcp_f32_e32 v234, v234
	v_rcp_f32_e32 v235, v235
	v_rcp_f32_e32 v236, v236
	v_rcp_f32_e32 v237, v237
	v_pk_mul_f32 v[22:23], v[30:31], v[22:23]
	v_pk_mul_f32 v[24:25], v[32:33], v[24:25]
	v_pk_mul_f32 v[22:23], v[22:23], v[234:235]
	v_pk_mul_f32 v[24:25], v[24:25], v[236:237]
	v_cvt_pk_bf16_f32 v238, v22, v23
	v_cvt_pk_bf16_f32 v239, v24, v25
	v_pk_mul_f32 v[234:235], v[26:27], s[100:101] op_sel_hi:[1,0]
	v_pk_mul_f32 v[236:237], v[28:29], s[100:101] op_sel_hi:[1,0]
	v_exp_f32_e32 v234, v234
	v_exp_f32_e32 v235, v235
	v_exp_f32_e32 v236, v236
	v_exp_f32_e32 v237, v237
	v_pk_add_f32 v[234:235], v[234:235], 1.0 op_sel_hi:[1,0]
	v_pk_add_f32 v[236:237], v[236:237], 1.0 op_sel_hi:[1,0]
	v_rcp_f32_e32 v234, v234
	v_rcp_f32_e32 v235, v235
	v_rcp_f32_e32 v236, v236
	v_rcp_f32_e32 v237, v237
	v_pk_mul_f32 v[18:19], v[26:27], v[18:19]
	v_pk_mul_f32 v[20:21], v[28:29], v[20:21]
	v_pk_mul_f32 v[18:19], v[18:19], v[234:235]
	v_pk_mul_f32 v[20:21], v[20:21], v[236:237]
	v_cvt_pk_bf16_f32 v240, v18, v19
	v_cvt_pk_bf16_f32 v241, v20, v21
	global_store_dwordx4 v[36:37], v[238:241], off
	v_add_u32_e32 v19, 0xb0, v181
	v_mad_i64_i32 v[20:21], s[2:3], v19, s49, v[162:163]
	v_lshl_add_u64 v[20:21], v[20:21], 0, v[164:165]
	s_mov_b64 s[2:3], -1
	v_pk_fma_f32 v[14:15], v[14:15], v[248:249], v[78:79] op_sel_hi:[1,0,1]
	v_pk_fma_f32 v[16:17], v[16:17], v[248:249], v[80:81] op_sel_hi:[1,0,1]
	v_pk_fma_f32 v[6:7], v[6:7], v[248:249], v[70:71] op_sel_hi:[1,0,1]
	v_pk_fma_f32 v[8:9], v[8:9], v[248:249], v[72:73] op_sel_hi:[1,0,1]
	v_pk_fma_f32 v[10:11], v[10:11], v[248:249], v[74:75] op_sel_hi:[1,0,1]
	v_pk_fma_f32 v[12:13], v[12:13], v[248:249], v[76:77] op_sel_hi:[1,0,1]
	v_pk_fma_f32 v[2:3], v[2:3], v[248:249], v[66:67] op_sel_hi:[1,0,1]
	v_pk_fma_f32 v[4:5], v[4:5], v[248:249], v[68:69] op_sel_hi:[1,0,1]
	v_pk_mul_f32 v[234:235], v[14:15], s[100:101] op_sel_hi:[1,0]
	v_pk_mul_f32 v[236:237], v[16:17], s[100:101] op_sel_hi:[1,0]
	v_exp_f32_e32 v234, v234
	v_exp_f32_e32 v235, v235
	v_exp_f32_e32 v236, v236
	v_exp_f32_e32 v237, v237
	v_pk_add_f32 v[234:235], v[234:235], 1.0 op_sel_hi:[1,0]
	v_pk_add_f32 v[236:237], v[236:237], 1.0 op_sel_hi:[1,0]
	v_rcp_f32_e32 v234, v234
	v_rcp_f32_e32 v235, v235
	v_rcp_f32_e32 v236, v236
	v_rcp_f32_e32 v237, v237
	v_pk_mul_f32 v[6:7], v[14:15], v[6:7]
	v_pk_mul_f32 v[8:9], v[16:17], v[8:9]
	v_pk_mul_f32 v[6:7], v[6:7], v[234:235]
	v_pk_mul_f32 v[8:9], v[8:9], v[236:237]
	v_cvt_pk_bf16_f32 v238, v6, v7
	v_cvt_pk_bf16_f32 v239, v8, v9
	v_pk_mul_f32 v[234:235], v[10:11], s[100:101] op_sel_hi:[1,0]
	v_pk_mul_f32 v[236:237], v[12:13], s[100:101] op_sel_hi:[1,0]
	v_exp_f32_e32 v234, v234
	v_exp_f32_e32 v235, v235
	v_exp_f32_e32 v236, v236
	v_exp_f32_e32 v237, v237
	v_pk_add_f32 v[234:235], v[234:235], 1.0 op_sel_hi:[1,0]
	v_pk_add_f32 v[236:237], v[236:237], 1.0 op_sel_hi:[1,0]
	v_rcp_f32_e32 v234, v234
	v_rcp_f32_e32 v235, v235
	v_rcp_f32_e32 v236, v236
	v_rcp_f32_e32 v237, v237
	v_pk_mul_f32 v[2:3], v[10:11], v[2:3]
	v_pk_mul_f32 v[4:5], v[12:13], v[4:5]
	v_pk_mul_f32 v[2:3], v[2:3], v[234:235]
	v_pk_mul_f32 v[4:5], v[4:5], v[236:237]
	v_cvt_pk_bf16_f32 v240, v2, v3
	v_cvt_pk_bf16_f32 v241, v4, v5
	global_store_dwordx4 v[20:21], v[238:241], off
	s_cbranch_vccnz .LBB0_1461
	s_andn2_b64 vcc, exec, s[4:5]
	s_cbranch_vccnz .LBB0_1460
	s_barrier
	s_branch .LBB0_1460

; #define PG8_STAGE(bufoff, gbase, voff) do { _Pragma("unroll") for (int _i = 0; _i < 2; ++_i) \
;         __builtin_amdgcn_global_load_lds((const unsigned*)((const char*)(gbase) + (voff)[_i]), (LAS unsigned*)(lds + (bufoff) + ldsw + _i * 8192), 16, 0, 0); } while (0)
; #define PG8_LDA(dst, b, h) do { _Pragma("unroll") for (int m = 0; m < 4; ++m) _Pragma("unroll") for (int k = 0; k < 2; ++k) dst[m][k] = *(const LAS bf16x8*)(lds + PG8_SA(b, h) + aoff + m * 2048 + k * 1024); } while (0)
; #define PG8_LDB(dst, b, h) do { _Pragma("unroll") for (int n = 0; n < 2; ++n) _Pragma("unroll") for (int k = 0; k < 2; ++k) dst[n][k] = *(const LAS bf16x8*)(lds + PG8_SB(b, h) + boff + n * 2048 + k * 1024); } while (0)
; #define PG8_MMA(ai, bj, At, Bt) do { __builtin_amdgcn_s_setprio(1); _Pragma("unroll") for (int m = 0; m < 4; ++m) _Pragma("unroll") for (int n = 0; n < 2; ++n) _Pragma("unroll") for (int k = 0; k < 2; ++k) \
;         acc[ai][bj][m][n] = __builtin_amdgcn_mfma_f32_16x16x32_bf16(Bt[n][k], At[m][k], acc[ai][bj][m][n], 0, 0, 0); __builtin_amdgcn_s_setprio(0); } while (0)
; #define PG8_WAIT_V(n) asm volatile("s_waitcnt vmcnt(" #n ")" ::: "memory")
; #define PG8_WAIT_L(n) asm volatile("s_waitcnt lgkmcnt(" #n ")" ::: "memory")
; template <class Epi, class Sched, bool ALIGN_EPI = false, bool SP2 = false>
; __device__ __forceinline__ void gemm_phase(LAS unsigned char* lds, const Gemm g, const Sched& S, const Epi& E) {
;     ...
;         for (int t = 0; t < nt; t += 2) {
;             const bool last = (t == nt - 2);
;             const char* a1 = cA + (size_t)(t + 1) * kstep;
;             const char* a2 = last ? nA : cA + (size_t)(t + 2) * kstep; const char* b2 = last ? nB : cB + (size_t)(t + 2) * kstep;
;             const char* a3 = a2 + kstep; const char* b3 = b2 + kstep;
;             if (last && has_next) S.a_ready(nxt);
;             if constexpr (SP2) {
;             PG8_LDB(B0, 0, 0); PG8_LDB(B1, 0, 1); PG8_SCHED; PG8_LDA(At, 0, 0); PG8_STAGE(PG8_SA(1, 1), a1 + hstep, voffA);
;             PG8_WAIT_V(8); PG8_WAIT_L(0); PG8_BAR; PG8_MMA(0, 0, At, B0); PG8_MMA(0, 1, At, B1); PG8_BAR; PG8_SCHED;
;             PG8_LDA(At, 0, 1); PG8_STAGE(PG8_SB(0, 0), b2, voffB); PG8_STAGE(PG8_SB(0, 1), b2 + hstepB, voffB); PG8_STAGE(PG8_SA(0, 0), a2, voffA);
;             PG8_WAIT_V(8); PG8_WAIT_L(0); PG8_BAR; PG8_MMA(1, 0, At, B0); PG8_MMA(1, 1, At, B1); PG8_BAR; PG8_SCHED;
.LBB0_1822:
	ds_read_b128 v[66:69], v173
	ds_read_b128 v[70:73], v173 offset:1024
	ds_read_b128 v[74:77], v173 offset:2048
	ds_read_b128 v[78:81], v173 offset:3072
	ds_read_b128 v[162:165], v174
	ds_read_b128 v[180:183], v174 offset:1024
	ds_read_b128 v[184:187], v174 offset:2048
	ds_read_b128 v[188:191], v174 offset:3072
	s_add_u32 s22, s16, 0xfff80080
	s_addc_u32 s23, s17, -1
	s_cmp_eq_u32 s50, 28
	s_cselect_b32 s41, s3, s23
	s_cselect_b32 s40, s15, s22
	s_cselect_b32 s23, s13, s49
	s_cselect_b32 s22, s24, s25
	s_add_i32 m0, s29, 0xc000
	ds_read_b128 v[192:195], v175
	ds_read_b128 v[196:199], v175 offset:1024
	ds_read_b128 v[200:203], v175 offset:2048
	ds_read_b128 v[204:207], v175 offset:3072
	ds_read_b128 v[208:211], v175 offset:4096
	ds_read_b128 v[212:215], v175 offset:5120
	ds_read_b128 v[216:219], v175 offset:6144
	ds_read_b128 v[220:223], v175 offset:7168
	global_load_lds_dwordx4 v156, s[16:17]
	s_add_i32 m0, s29, 0xe000
	s_nop 0
	global_load_lds_dwordx4 v154, s[16:17]
	s_waitcnt vmcnt(8)
	s_waitcnt lgkmcnt(0)
	s_barrier
	s_waitcnt lgkmcnt(0)
	v_mfma_f32_16x16x32_bf16 v[142:145], v[66:69], v[192:195], v[142:145]
	v_mfma_f32_16x16x32_bf16 v[138:141], v[74:77], v[192:195], v[138:141]
	v_mfma_f32_16x16x32_bf16 v[126:129], v[66:69], v[200:203], v[126:129]
	v_mfma_f32_16x16x32_bf16 v[122:125], v[74:77], v[200:203], v[122:125]
	v_mfma_f32_16x16x32_bf16 v[110:113], v[66:69], v[208:211], v[110:113]
	v_mfma_f32_16x16x32_bf16 v[106:109], v[74:77], v[208:211], v[106:109]
	v_mfma_f32_16x16x32_bf16 v[94:97], v[66:69], v[216:219], v[94:97]
	v_mfma_f32_16x16x32_bf16 v[90:93], v[74:77], v[216:219], v[90:93]
	v_mfma_f32_16x16x32_bf16 v[142:145], v[70:73], v[196:199], v[142:145]
	v_mfma_f32_16x16x32_bf16 v[138:141], v[78:81], v[196:199], v[138:141]
	v_mfma_f32_16x16x32_bf16 v[126:129], v[70:73], v[204:207], v[126:129]
	v_mfma_f32_16x16x32_bf16 v[122:125], v[78:81], v[204:207], v[122:125]
	v_mfma_f32_16x16x32_bf16 v[110:113], v[70:73], v[212:215], v[110:113]
	v_mfma_f32_16x16x32_bf16 v[106:109], v[78:81], v[212:215], v[106:109]
	v_mfma_f32_16x16x32_bf16 v[94:97], v[70:73], v[220:223], v[94:97]
	v_mfma_f32_16x16x32_bf16 v[90:93], v[78:81], v[220:223], v[90:93]
	v_mfma_f32_16x16x32_bf16 v[134:137], v[162:165], v[192:195], v[134:137]
	v_mfma_f32_16x16x32_bf16 v[130:133], v[184:187], v[192:195], v[130:133]
	v_mfma_f32_16x16x32_bf16 v[118:121], v[162:165], v[200:203], v[118:121]
	v_mfma_f32_16x16x32_bf16 v[114:117], v[184:187], v[200:203], v[114:117]
	v_mfma_f32_16x16x32_bf16 v[102:105], v[162:165], v[208:211], v[102:105]
	v_mfma_f32_16x16x32_bf16 v[98:101], v[184:187], v[208:211], v[98:101]
	v_mfma_f32_16x16x32_bf16 v[86:89], v[162:165], v[216:219], v[86:89]
	v_mfma_f32_16x16x32_bf16 v[82:85], v[184:187], v[216:219], v[82:85]
	v_mfma_f32_16x16x32_bf16 v[134:137], v[180:183], v[196:199], v[134:137]
	v_mfma_f32_16x16x32_bf16 v[130:133], v[188:191], v[196:199], v[130:133]
	v_mfma_f32_16x16x32_bf16 v[118:121], v[180:183], v[204:207], v[118:121]
	v_mfma_f32_16x16x32_bf16 v[114:117], v[188:191], v[204:207], v[114:117]
	v_mfma_f32_16x16x32_bf16 v[102:105], v[180:183], v[212:215], v[102:105]
	v_mfma_f32_16x16x32_bf16 v[98:101], v[188:191], v[212:215], v[98:101]
	v_mfma_f32_16x16x32_bf16 v[86:89], v[180:183], v[220:223], v[86:89]
	v_mfma_f32_16x16x32_bf16 v[82:85], v[188:191], v[220:223], v[82:85]
	s_barrier
	s_add_i32 s51, s44, s26
	s_mov_b32 m0, s51
	ds_read_b128 v[192:195], v175 offset:16384
	ds_read_b128 v[196:199], v175 offset:17408
	ds_read_b128 v[200:203], v175 offset:18432
	ds_read_b128 v[204:207], v175 offset:19456
	ds_read_b128 v[208:211], v175 offset:20480
	ds_read_b128 v[212:215], v175 offset:21504
	ds_read_b128 v[216:219], v175 offset:22528
	ds_read_b128 v[220:223], v175 offset:23552
	global_load_lds_dwordx4 v150, s[22:23]
	s_add_i32 m0, s51, 0x2000
	s_add_u32 s52, s22, 0x80000
	v_lshl_add_u64 v[224:225], s[22:23], 0, v[146:147]
	s_addc_u32 s53, s23, 0
	s_add_i32 s51, s45, s26
	global_load_lds_dwordx4 v146, s[22:23]
	s_mov_b32 m0, s51
	v_lshl_add_u64 v[228:229], s[40:41], 0, v[148:149]
	global_load_lds_dwordx4 v150, s[52:53]
	s_add_i32 m0, s51, 0x2000
	s_nop 0
	global_load_lds_dwordx4 v146, s[52:53]
	v_lshl_add_u64 v[226:227], s[40:41], 0, v[152:153]
	s_mov_b32 m0, s29
	s_nop 0
	global_load_lds_dwordx4 v152, s[40:41]
	s_mov_b32 m0, s30
	s_nop 0
	global_load_lds_dwordx4 v148, s[40:41]
	s_waitcnt vmcnt(8)
	s_waitcnt lgkmcnt(0)
	s_barrier
	s_waitcnt lgkmcnt(0)
	v_mfma_f32_16x16x32_bf16 v[62:65], v[66:69], v[192:195], v[62:65]
	v_mfma_f32_16x16x32_bf16 v[58:61], v[74:77], v[192:195], v[58:61]
	v_mfma_f32_16x16x32_bf16 v[46:49], v[66:69], v[200:203], v[46:49]
	v_mfma_f32_16x16x32_bf16 v[42:45], v[74:77], v[200:203], v[42:45]
	v_mfma_f32_16x16x32_bf16 v[30:33], v[66:69], v[208:211], v[30:33]
	v_mfma_f32_16x16x32_bf16 v[26:29], v[74:77], v[208:211], v[26:29]
	v_mfma_f32_16x16x32_bf16 v[14:17], v[66:69], v[216:219], v[14:17]
	v_mfma_f32_16x16x32_bf16 v[10:13], v[74:77], v[216:219], v[10:13]
	v_mfma_f32_16x16x32_bf16 v[62:65], v[70:73], v[196:199], v[62:65]
	v_mfma_f32_16x16x32_bf16 v[58:61], v[78:81], v[196:199], v[58:61]
	v_mfma_f32_16x16x32_bf16 v[46:49], v[70:73], v[204:207], v[46:49]
	v_mfma_f32_16x16x32_bf16 v[42:45], v[78:81], v[204:207], v[42:45]
	v_mfma_f32_16x16x32_bf16 v[30:33], v[70:73], v[212:215], v[30:33]
	v_mfma_f32_16x16x32_bf16 v[26:29], v[78:81], v[212:215], v[26:29]
	v_mfma_f32_16x16x32_bf16 v[14:17], v[70:73], v[220:223], v[14:17]
	v_mfma_f32_16x16x32_bf16 v[10:13], v[78:81], v[220:223], v[10:13]
	v_mfma_f32_16x16x32_bf16 v[54:57], v[162:165], v[192:195], v[54:57]
	v_mfma_f32_16x16x32_bf16 v[50:53], v[184:187], v[192:195], v[50:53]
	v_mfma_f32_16x16x32_bf16 v[38:41], v[162:165], v[200:203], v[38:41]
	v_mfma_f32_16x16x32_bf16 v[34:37], v[184:187], v[200:203], v[34:37]
	v_mfma_f32_16x16x32_bf16 v[22:25], v[162:165], v[208:211], v[22:25]
	v_mfma_f32_16x16x32_bf16 v[18:21], v[184:187], v[208:211], v[18:21]
	v_mfma_f32_16x16x32_bf16 v[6:9], v[162:165], v[216:219], v[6:9]
	v_mfma_f32_16x16x32_bf16 v[2:5], v[184:187], v[216:219], v[2:5]
	v_mfma_f32_16x16x32_bf16 v[54:57], v[180:183], v[196:199], v[54:57]
	v_mfma_f32_16x16x32_bf16 v[50:53], v[188:191], v[196:199], v[50:53]
	v_mfma_f32_16x16x32_bf16 v[38:41], v[180:183], v[204:207], v[38:41]
	v_mfma_f32_16x16x32_bf16 v[34:37], v[188:191], v[204:207], v[34:37]
	v_mfma_f32_16x16x32_bf16 v[22:25], v[180:183], v[212:215], v[22:25]
	v_mfma_f32_16x16x32_bf16 v[18:21], v[188:191], v[212:215], v[18:21]
	v_mfma_f32_16x16x32_bf16 v[6:9], v[180:183], v[220:223], v[6:9]
	v_mfma_f32_16x16x32_bf16 v[2:5], v[188:191], v[220:223], v[2:5]
	s_barrier
; #define PG8_STAGE(bufoff, gbase, voff) do { _Pragma("unroll") for (int _i = 0; _i < 2; ++_i) \
;         __builtin_amdgcn_global_load_lds((const unsigned*)((const char*)(gbase) + (voff)[_i]), (LAS unsigned*)(lds + (bufoff) + ldsw + _i * 8192), 16, 0, 0); } while (0)
; #define PG8_BAR __builtin_amdgcn_s_barrier()
; template <class Epi, class Sched, bool ALIGN_EPI = false, bool SP2 = false>
; __device__ __forceinline__ void gemm_phase(LAS unsigned char* lds, const Gemm g, const Sched& S, const Epi& E) {
;     ...
;             PG8_LDB(B0, 1, 0); PG8_LDB(B1, 1, 1); PG8_SCHED; PG8_LDA(At, 1, 0); PG8_STAGE(PG8_SA(0, 1), a2 + hstep, voffA);
;             PG8_WAIT_V(8); PG8_WAIT_L(0); PG8_BAR; PG8_MMA(0, 0, At, B0); PG8_MMA(0, 1, At, B1); PG8_BAR; PG8_SCHED;
;             PG8_LDA(At, 1, 1); PG8_STAGE(PG8_SB(1, 0), b3, voffB); PG8_STAGE(PG8_SB(1, 1), b3 + hstepB, voffB); PG8_STAGE(PG8_SA(1, 0), a3, voffA);
;             PG8_WAIT_V(8); PG8_WAIT_L(0); PG8_BAR; PG8_MMA(1, 0, At, B0); PG8_MMA(1, 1, At, B1); PG8_BAR; PG8_SCHED;
;             } else {
;             PG8_LDB(B0, 0, 0); PG8_SCHED; PG8_LDA(At, 0, 0); PG8_STAGE(PG8_SA(1, 1), a1 + hstep, voffA);
;             PG8_WAIT_L(8); PG8_BAR; PG8_WAIT_L(0); PG8_MMA(0, 0, At, B0); PG8_BAR; PG8_SCHED;
;             PG8_LDB(B1, 0, 1); PG8_STAGE(PG8_SB(0, 0), b2, voffB);
;             PG8_BAR; PG8_WAIT_L(0); PG8_MMA(0, 1, At, B1); PG8_BAR;
;             PG8_LDA(At, 0, 1); PG8_STAGE(PG8_SA(0, 0), a2, voffA);
;             PG8_BAR; PG8_WAIT_L(0); PG8_MMA(1, 0, At, B0); PG8_BAR; PG8_SCHED;
;             PG8_STAGE(PG8_SB(0, 1), b2 + hstepB, voffB);
;             PG8_WAIT_V(6); PG8_BAR; PG8_MMA(1, 1, At, B1); PG8_BAR;
;             PG8_LDB(B0, 1, 0); PG8_SCHED; PG8_LDA(At, 1, 0); PG8_STAGE(PG8_SA(0, 1), a2 + hstep, voffA);
;             PG8_WAIT_L(8); PG8_BAR; PG8_WAIT_L(0); PG8_MMA(0, 0, At, B0); PG8_BAR; PG8_SCHED;
;             PG8_LDB(B1, 1, 1); PG8_STAGE(PG8_SB(1, 0), b3, voffB);
;             PG8_BAR; PG8_WAIT_L(0); PG8_MMA(0, 1, At, B1); PG8_BAR;
;             PG8_LDA(At, 1, 1); PG8_STAGE(PG8_SA(1, 0), a3, voffA);
;             PG8_BAR; PG8_WAIT_L(0); PG8_MMA(1, 0, At, B0); PG8_BAR; PG8_SCHED;
;             PG8_STAGE(PG8_SB(1, 1), b3 + hstepB, voffB);
;             PG8_WAIT_V(6); PG8_BAR; PG8_MMA(1, 1, At, B1); PG8_BAR;
;             }
;         }
;         if constexpr (ALIGN_EPI) { if (wr == 0) PG8_BAR; }
	s_add_i32 s51, 0, 0x18000
	s_add_i32 s52, 0, 0x1c000
	v_add_u32_e32 v78, s51, v169
	v_add_u32_e32 v168, s52, v169
	ds_read_b128 v[66:69], v78
	ds_read_b128 v[70:73], v78 offset:1024
	ds_read_b128 v[74:77], v78 offset:2048
	ds_read_b128 v[78:81], v78 offset:3072
	ds_read_b128 v[162:165], v168
	ds_read_b128 v[180:183], v168 offset:1024
	ds_read_b128 v[184:187], v168 offset:2048
	ds_read_b128 v[188:191], v168 offset:3072
	s_add_u32 s40, s40, 0x80000
	s_addc_u32 s41, s41, 0
	s_mov_b32 m0, s31
	ds_read_b128 v[192:195], v175 offset:32768
	ds_read_b128 v[196:199], v175 offset:33792
	ds_read_b128 v[200:203], v175 offset:34816
	ds_read_b128 v[204:207], v175 offset:35840
	ds_read_b128 v[208:211], v175 offset:36864
	ds_read_b128 v[212:215], v175 offset:37888
	ds_read_b128 v[216:219], v175 offset:38912
	ds_read_b128 v[220:223], v175 offset:39936
	global_load_lds_dwordx4 v152, s[40:41]
	s_mov_b32 m0, s33
	s_nop 0
	global_load_lds_dwordx4 v148, s[40:41]
	s_waitcnt vmcnt(8)
	s_waitcnt lgkmcnt(0)
	s_barrier
	s_waitcnt lgkmcnt(0)
	v_mfma_f32_16x16x32_bf16 v[142:145], v[66:69], v[192:195], v[142:145]
	v_mfma_f32_16x16x32_bf16 v[138:141], v[74:77], v[192:195], v[138:141]
	v_mfma_f32_16x16x32_bf16 v[126:129], v[66:69], v[200:203], v[126:129]
	v_mfma_f32_16x16x32_bf16 v[122:125], v[74:77], v[200:203], v[122:125]
	v_mfma_f32_16x16x32_bf16 v[110:113], v[66:69], v[208:211], v[110:113]
	v_mfma_f32_16x16x32_bf16 v[106:109], v[74:77], v[208:211], v[106:109]
	v_mfma_f32_16x16x32_bf16 v[94:97], v[66:69], v[216:219], v[94:97]
	v_mfma_f32_16x16x32_bf16 v[90:93], v[74:77], v[216:219], v[90:93]
	v_mfma_f32_16x16x32_bf16 v[142:145], v[70:73], v[196:199], v[142:145]
	v_mfma_f32_16x16x32_bf16 v[138:141], v[78:81], v[196:199], v[138:141]
	v_mfma_f32_16x16x32_bf16 v[126:129], v[70:73], v[204:207], v[126:129]
	v_mfma_f32_16x16x32_bf16 v[122:125], v[78:81], v[204:207], v[122:125]
	v_mfma_f32_16x16x32_bf16 v[110:113], v[70:73], v[212:215], v[110:113]
	v_mfma_f32_16x16x32_bf16 v[106:109], v[78:81], v[212:215], v[106:109]
	v_mfma_f32_16x16x32_bf16 v[94:97], v[70:73], v[220:223], v[94:97]
	v_mfma_f32_16x16x32_bf16 v[90:93], v[78:81], v[220:223], v[90:93]
	v_mfma_f32_16x16x32_bf16 v[134:137], v[162:165], v[192:195], v[134:137]
	v_mfma_f32_16x16x32_bf16 v[130:133], v[184:187], v[192:195], v[130:133]
	v_mfma_f32_16x16x32_bf16 v[118:121], v[162:165], v[200:203], v[118:121]
	v_mfma_f32_16x16x32_bf16 v[114:117], v[184:187], v[200:203], v[114:117]
	v_mfma_f32_16x16x32_bf16 v[102:105], v[162:165], v[208:211], v[102:105]
	v_mfma_f32_16x16x32_bf16 v[98:101], v[184:187], v[208:211], v[98:101]
	v_mfma_f32_16x16x32_bf16 v[86:89], v[162:165], v[216:219], v[86:89]
	v_mfma_f32_16x16x32_bf16 v[82:85], v[184:187], v[216:219], v[82:85]
	v_mfma_f32_16x16x32_bf16 v[134:137], v[180:183], v[196:199], v[134:137]
	v_mfma_f32_16x16x32_bf16 v[130:133], v[188:191], v[196:199], v[130:133]
	v_mfma_f32_16x16x32_bf16 v[118:121], v[180:183], v[204:207], v[118:121]
	v_mfma_f32_16x16x32_bf16 v[114:117], v[188:191], v[204:207], v[114:117]
	v_mfma_f32_16x16x32_bf16 v[102:105], v[180:183], v[212:215], v[102:105]
	v_mfma_f32_16x16x32_bf16 v[98:101], v[188:191], v[212:215], v[98:101]
	v_mfma_f32_16x16x32_bf16 v[86:89], v[180:183], v[220:223], v[86:89]
	v_mfma_f32_16x16x32_bf16 v[82:85], v[188:191], v[220:223], v[82:85]
	s_barrier
	s_add_u32 s98, s22, 0x80
	s_addc_u32 s99, s23, 0
	s_add_i32 s40, s51, s26
	s_mov_b32 m0, s40
	ds_read_b128 v[192:195], v175 offset:49152
	ds_read_b128 v[196:199], v175 offset:50176
	ds_read_b128 v[200:203], v175 offset:51200
	ds_read_b128 v[204:207], v175 offset:52224
	ds_read_b128 v[208:211], v175 offset:53248
	ds_read_b128 v[212:215], v175 offset:54272
	ds_read_b128 v[216:219], v175 offset:55296
	ds_read_b128 v[220:223], v175 offset:56320
	global_load_lds_dwordx4 v150, s[98:99]
	s_add_i32 m0, s40, 0x2000
	s_add_u32 s22, s22, 0x80080
	v_lshl_add_u64 v[166:167], v[224:225], 0, s[8:9]
	s_addc_u32 s23, s23, 0
	s_add_i32 s40, s52, s26
	global_load_lds_dwordx4 v[166:167], off
	s_mov_b32 m0, s40
	s_nop 0
	global_load_lds_dwordx4 v150, s[22:23]
	s_add_i32 m0, s40, 0x2000
	s_nop 0
	global_load_lds_dwordx4 v146, s[22:23]
	v_lshl_add_u64 v[166:167], v[226:227], 0, s[8:9]
	s_mov_b32 m0, s42
	s_nop 0
	global_load_lds_dwordx4 v[166:167], off
	v_lshl_add_u64 v[166:167], v[228:229], 0, s[8:9]
	s_mov_b32 m0, s43
	s_nop 0
	global_load_lds_dwordx4 v[166:167], off
	s_waitcnt vmcnt(8)
	s_waitcnt lgkmcnt(0)
	s_barrier
	s_waitcnt lgkmcnt(0)
	v_mfma_f32_16x16x32_bf16 v[62:65], v[66:69], v[192:195], v[62:65]
	v_mfma_f32_16x16x32_bf16 v[58:61], v[74:77], v[192:195], v[58:61]
	v_mfma_f32_16x16x32_bf16 v[46:49], v[66:69], v[200:203], v[46:49]
	v_mfma_f32_16x16x32_bf16 v[42:45], v[74:77], v[200:203], v[42:45]
	v_mfma_f32_16x16x32_bf16 v[30:33], v[66:69], v[208:211], v[30:33]
	v_mfma_f32_16x16x32_bf16 v[26:29], v[74:77], v[208:211], v[26:29]
	v_mfma_f32_16x16x32_bf16 v[14:17], v[66:69], v[216:219], v[14:17]
	v_mfma_f32_16x16x32_bf16 v[10:13], v[74:77], v[216:219], v[10:13]
	v_mfma_f32_16x16x32_bf16 v[62:65], v[70:73], v[196:199], v[62:65]
	v_mfma_f32_16x16x32_bf16 v[58:61], v[78:81], v[196:199], v[58:61]
	v_mfma_f32_16x16x32_bf16 v[46:49], v[70:73], v[204:207], v[46:49]
	v_mfma_f32_16x16x32_bf16 v[42:45], v[78:81], v[204:207], v[42:45]
	v_mfma_f32_16x16x32_bf16 v[30:33], v[70:73], v[212:215], v[30:33]
	v_mfma_f32_16x16x32_bf16 v[26:29], v[78:81], v[212:215], v[26:29]
	v_mfma_f32_16x16x32_bf16 v[14:17], v[70:73], v[220:223], v[14:17]
	v_mfma_f32_16x16x32_bf16 v[10:13], v[78:81], v[220:223], v[10:13]
	v_mfma_f32_16x16x32_bf16 v[54:57], v[162:165], v[192:195], v[54:57]
	v_mfma_f32_16x16x32_bf16 v[50:53], v[184:187], v[192:195], v[50:53]
	v_mfma_f32_16x16x32_bf16 v[38:41], v[162:165], v[200:203], v[38:41]
	v_mfma_f32_16x16x32_bf16 v[34:37], v[184:187], v[200:203], v[34:37]
	v_mfma_f32_16x16x32_bf16 v[22:25], v[162:165], v[208:211], v[22:25]
	v_mfma_f32_16x16x32_bf16 v[18:21], v[184:187], v[208:211], v[18:21]
	v_mfma_f32_16x16x32_bf16 v[6:9], v[162:165], v[216:219], v[6:9]
	v_mfma_f32_16x16x32_bf16 v[2:5], v[184:187], v[216:219], v[2:5]
	v_mfma_f32_16x16x32_bf16 v[54:57], v[180:183], v[196:199], v[54:57]
	v_mfma_f32_16x16x32_bf16 v[50:53], v[188:191], v[196:199], v[50:53]
	v_mfma_f32_16x16x32_bf16 v[38:41], v[180:183], v[204:207], v[38:41]
	v_mfma_f32_16x16x32_bf16 v[34:37], v[188:191], v[204:207], v[34:37]
	v_mfma_f32_16x16x32_bf16 v[22:25], v[180:183], v[212:215], v[22:25]
	v_mfma_f32_16x16x32_bf16 v[18:21], v[188:191], v[212:215], v[18:21]
	v_mfma_f32_16x16x32_bf16 v[6:9], v[180:183], v[220:223], v[6:9]
	v_mfma_f32_16x16x32_bf16 v[2:5], v[188:191], v[220:223], v[2:5]
	s_barrier
	s_add_i32 s50, s50, 2
	s_add_u32 s25, s25, 0x100
	s_addc_u32 s49, s49, 0
	s_add_u32 s16, s16, 0x100
	s_addc_u32 s17, s17, 0
	s_cmp_lt_u32 s50, 30
	s_cbranch_scc1 .LBB0_1822
	s_setprio 0
	s_cmpk_gt_i32 s2, 0x7f
	s_mov_b64 s[16:17], 0xb000
	s_cbranch_scc1 .LBB0_1827
	s_ashr_i32 s3, s2, 5
	s_mul_hi_i32 s17, s3, 0x2c00
	s_mul_i32 s16, s3, 0x2c00
; __device__ __forceinline__ unsigned cvt_pk_bf16(float lo, float hi) { unsigned r; asm volatile("v_cvt_pk_bf16_f32 %0, %1, %2" : "=v"(r) : "v"(lo), "v"(hi)); return r; }
; __device__ __forceinline__ float row_rstd(const float* ss, int row) { return 1.0f / sqrtf(ss[row] * (1.0f / DM) + 1e-6f); }
; __device__ __forceinline__ float silu_mul(float a, float b) { return a * b * __builtin_amdgcn_rcpf(1.0f + __builtin_amdgcn_exp2f(-a * LOG2E)); }
; #define PG8_BAR __builtin_amdgcn_s_barrier()
;     __device__ __forceinline__ void operator()(const f32x4 (&acc)[2][2][4][2], const Unit& u, int wr, int wc, int fr, int fq) const {
;         const int row0 = u.pm * BM + wr * 64 + fr, col0 = u.pn * HALF + wc * 32 + 8 * fq;
;         const int s = (u.pm < ML / BM) ? (u.pm >> 5) : 4;
;         const float* bp = bias + (size_t)s * BIAS_N + u.pn * BM + wc * 32 + 8 * fq;
;         const f32x4 ba0 = *(const f32x4*)bp, ba1 = *(const f32x4*)(bp + 4), bb0 = *(const f32x4*)(bp + HALF), bb1 = *(const f32x4*)(bp + HALF + 4);
;         const int lane = fq * 16 + fr;
;         const float rsl0 = row_rstd(ss, u.pm * BM + wr * 64 + lane), rsl1 = row_rstd(ss, u.pm * BM + HALF + wr * 64 + lane);
; #pragma unroll
;         for (int ai = 0; ai < 2; ++ai)
; #pragma unroll
;             for (int m = 0; m < 4; ++m) { const int row = row0 + ai * HALF + m * 16; const float rs = __shfl(ai ? rsl1 : rsl0, m * 16 + fr); bf16_t* rowp = O + (size_t)row * DFF + col0;
;                 const f32x4 a0 = acc[ai][0][m][0] * rs + ba0, a1 = acc[ai][0][m][1] * rs + ba1, b0 = acc[ai][1][m][0] * rs + bb0, b1 = acc[ai][1][m][1] * rs + bb1;
;                 u32x4 w; w.x = cvt_pk_bf16(silu_mul(a0[0], b0[0]), silu_mul(a0[1], b0[1])); w.y = cvt_pk_bf16(silu_mul(a0[2], b0[2]), silu_mul(a0[3], b0[3]));
;                 w.z = cvt_pk_bf16(silu_mul(a1[0], b1[0]), silu_mul(a1[1], b1[1])); w.w = cvt_pk_bf16(silu_mul(a1[2], b1[2]), silu_mul(a1[3], b1[3]));
;                 *(u32x4*)rowp = w; }
; template <class Epi, class Sched, bool ALIGN_EPI = false, bool SP2 = false>
; __device__ __forceinline__ void gemm_phase(LAS unsigned char* lds, const Gemm g, const Sched& S, const Epi& E) {
;     ...
;         if constexpr (ALIGN_EPI) { if (wr == 0) PG8_BAR; }
;         if constexpr (!Epi::AFTER_DRAIN) { E(acc, cur, wr, wc, fr, fq); S.done(cur); }
.LBB0_1827:
	s_lshl_b32 s2, s2, 8
	s_add_i32 s13, s2, s35
	s_lshl_b64 s[2:3], s[16:17], 2
	s_add_u32 s15, s36, s2
	s_addc_u32 s16, s37, s3
	s_lshl_b32 s2, s0, 8
	s_ashr_i32 s3, s2, 31
	s_lshl_b64 s[2:3], s[2:3], 2
	v_lshl_or_b32 v164, s0, 7, v172
	s_add_u32 s0, s15, s2
	s_addc_u32 s3, s16, s3
	v_or_b32_e32 v162, s13, v170
	s_add_u32 s2, s0, s47
	v_ashrrev_i32_e32 v163, 31, v162
	s_addc_u32 s3, s3, 0
	v_lshl_add_u64 v[162:163], v[162:163], 2, s[6:7]
	v_mov_b32_e32 v74, v234
	v_mov_b32_e32 v75, v235
	v_mov_b32_e32 v76, v236
	v_mov_b32_e32 v77, v237
	v_mov_b32_e32 v78, v238
	v_mov_b32_e32 v79, v239
	v_mov_b32_e32 v80, v240
	v_mov_b32_e32 v81, v241
	v_mov_b32_e32 v66, v242
	v_mov_b32_e32 v67, v243
	v_mov_b32_e32 v68, v244
	v_mov_b32_e32 v69, v245
	v_mov_b32_e32 v70, v246
	v_mov_b32_e32 v71, v247
	v_mov_b32_e32 v72, v248
	v_mov_b32_e32 v73, v249
	v_or_b32_e32 v180, s13, v1
	v_mov_b32_e32 v162, v250
	s_waitcnt vmcnt(0)
	v_fmamk_f32 v162, v162, 0x3a000000, v177
	v_cmp_gt_f32_e32 vcc, s48, v162
	v_mul_f32_e32 v163, 0x4f800000, v162
	s_nop 0
	v_cndmask_b32_e32 v162, v162, v163, vcc
	v_sqrt_f32_e32 v163, v162
	s_nop 0
	v_add_u32_e32 v165, -1, v163
	v_fma_f32 v166, -v165, v163, v162
	v_cmp_ge_f32_e64 s[2:3], 0, v166
	v_add_u32_e32 v166, 1, v163
	s_nop 0
	v_cndmask_b32_e64 v165, v163, v165, s[2:3]
	v_fma_f32 v163, -v166, v163, v162
	v_cmp_lt_f32_e64 s[2:3], 0, v163
	s_nop 1
	v_cndmask_b32_e64 v163, v165, v166, s[2:3]
	v_mul_f32_e32 v165, 0x37800000, v163
	v_cndmask_b32_e32 v163, v163, v165, vcc
	v_cmp_class_f32_e32 vcc, v162, v178
	s_nop 1
	v_cndmask_b32_e32 v166, v163, v162, vcc
	v_add_u32_e32 v162, s13, v171
	v_ashrrev_i32_e32 v163, 31, v162
	v_lshl_add_u64 v[162:163], v[162:163], 2, s[6:7]
	v_mov_b32_e32 v162, v251
	v_fmamk_f32 v162, v162, 0x3a000000, v177
	v_cmp_gt_f32_e32 vcc, s48, v162
	v_mul_f32_e32 v163, 0x4f800000, v162
	s_nop 0
	v_cndmask_b32_e32 v162, v162, v163, vcc
	v_sqrt_f32_e32 v163, v162
	s_nop 0
	v_add_u32_e32 v165, -1, v163
	v_fma_f32 v167, -v165, v163, v162
	v_cmp_ge_f32_e64 s[2:3], 0, v167
	v_add_u32_e32 v167, 1, v163
	s_nop 0
	v_cndmask_b32_e64 v165, v163, v165, s[2:3]
	v_fma_f32 v163, -v167, v163, v162
	v_cmp_lt_f32_e64 s[2:3], 0, v163
	s_nop 1
	v_cndmask_b32_e64 v163, v165, v167, s[2:3]
	v_mul_f32_e32 v165, 0x37800000, v163
	v_cndmask_b32_e32 v163, v163, v165, vcc
	v_cmp_class_f32_e32 vcc, v162, v178
	v_ashrrev_i32_e32 v165, 31, v164
	v_lshlrev_b64 v[164:165], 1, v[164:165]
	v_cndmask_b32_e32 v181, v163, v162, vcc
	v_div_scale_f32 v162, s[2:3], v166, v166, 1.0
	v_rcp_f32_e32 v163, v162
	s_nop 0
	v_fma_f32 v167, -v162, v163, 1.0
	v_fmac_f32_e32 v163, v167, v163
	v_div_scale_f32 v167, vcc, 1.0, v166, 1.0
	v_mul_f32_e32 v168, v167, v163
	v_fma_f32 v182, -v162, v168, v167
	v_fmac_f32_e32 v168, v182, v163
	v_fma_f32 v162, -v162, v168, v167
	v_div_fmas_f32 v162, v162, v163, v168
	v_div_fixup_f32 v182, v162, v166, 1.0
	s_andn2_b64 vcc, exec, s[10:11]
	s_cbranch_vccnz .Lalign_1825
	s_barrier
.Lalign_1825:
	s_mov_b32 s100, 0xbfb8aa3b
	ds_bpermute_b32 v242, v179, v182
	ds_bpermute_b32 v244, v179, v182 offset:64
	ds_bpermute_b32 v246, v179, v182 offset:128
	ds_bpermute_b32 v248, v179, v182 offset:192
	v_mov_b64_e32 v[162:163], s[96:97]
	v_mad_i64_i32 v[166:167], s[2:3], v180, s46, v[162:163]
	v_lshl_add_u64 v[166:167], v[166:167], 0, v[164:165]
	s_waitcnt lgkmcnt(0)
	v_pk_fma_f32 v[142:143], v[142:143], v[242:243], v[78:79] op_sel_hi:[1,0,1]
	v_pk_fma_f32 v[144:145], v[144:145], v[242:243], v[80:81] op_sel_hi:[1,0,1]
	v_pk_fma_f32 v[134:135], v[134:135], v[242:243], v[70:71] op_sel_hi:[1,0,1]
	v_pk_fma_f32 v[136:137], v[136:137], v[242:243], v[72:73] op_sel_hi:[1,0,1]
	v_pk_fma_f32 v[138:139], v[138:139], v[242:243], v[74:75] op_sel_hi:[1,0,1]
	v_pk_fma_f32 v[140:141], v[140:141], v[242:243], v[76:77] op_sel_hi:[1,0,1]
	v_pk_fma_f32 v[130:131], v[130:131], v[242:243], v[66:67] op_sel_hi:[1,0,1]
	v_pk_fma_f32 v[132:133], v[132:133], v[242:243], v[68:69] op_sel_hi:[1,0,1]
	v_pk_mul_f32 v[234:235], v[142:143], s[100:101] op_sel_hi:[1,0]
	v_pk_mul_f32 v[236:237], v[144:145], s[100:101] op_sel_hi:[1,0]
	v_exp_f32_e32 v234, v234
	v_exp_f32_e32 v235, v235
	v_exp_f32_e32 v236, v236
	v_exp_f32_e32 v237, v237
	v_pk_add_f32 v[234:235], v[234:235], 1.0 op_sel_hi:[1,0]
	v_pk_add_f32 v[236:237], v[236:237], 1.0 op_sel_hi:[1,0]
	v_rcp_f32_e32 v234, v234
	v_rcp_f32_e32 v235, v235
	v_rcp_f32_e32 v236, v236
	v_rcp_f32_e32 v237, v237
	v_pk_mul_f32 v[134:135], v[142:143], v[134:135]
	v_pk_mul_f32 v[136:137], v[144:145], v[136:137]
	v_pk_mul_f32 v[134:135], v[134:135], v[234:235]
	v_pk_mul_f32 v[136:137], v[136:137], v[236:237]
	v_cvt_pk_bf16_f32 v238, v134, v135
	v_cvt_pk_bf16_f32 v239, v136, v137
	v_pk_mul_f32 v[234:235], v[138:139], s[100:101] op_sel_hi:[1,0]
	v_pk_mul_f32 v[236:237], v[140:141], s[100:101] op_sel_hi:[1,0]
	v_exp_f32_e32 v234, v234
	v_exp_f32_e32 v235, v235
	v_exp_f32_e32 v236, v236
	v_exp_f32_e32 v237, v237
	v_pk_add_f32 v[234:235], v[234:235], 1.0 op_sel_hi:[1,0]
	v_pk_add_f32 v[236:237], v[236:237], 1.0 op_sel_hi:[1,0]
	v_rcp_f32_e32 v234, v234
	v_rcp_f32_e32 v235, v235
	v_rcp_f32_e32 v236, v236
	v_rcp_f32_e32 v237, v237
	v_pk_mul_f32 v[130:131], v[138:139], v[130:131]
	v_pk_mul_f32 v[132:133], v[140:141], v[132:133]
	v_pk_mul_f32 v[130:131], v[130:131], v[234:235]
	v_pk_mul_f32 v[132:133], v[132:133], v[236:237]
	v_cvt_pk_bf16_f32 v240, v130, v131
	v_cvt_pk_bf16_f32 v241, v132, v133
	global_store_dwordx4 v[166:167], v[238:241], off
	v_or_b32_e32 v131, 16, v180
	v_mad_i64_i32 v[132:133], s[2:3], v131, s46, v[162:163]
	v_lshl_add_u64 v[132:133], v[132:133], 0, v[164:165]
	v_pk_fma_f32 v[126:127], v[126:127], v[244:245], v[78:79] op_sel_hi:[1,0,1]
; __device__ __forceinline__ unsigned cvt_pk_bf16(float lo, float hi) { unsigned r; asm volatile("v_cvt_pk_bf16_f32 %0, %1, %2" : "=v"(r) : "v"(lo), "v"(hi)); return r; }
; __device__ __forceinline__ float silu_mul(float a, float b) { return a * b * __builtin_amdgcn_rcpf(1.0f + __builtin_amdgcn_exp2f(-a * LOG2E)); }
;     __device__ __forceinline__ void operator()(const f32x4 (&acc)[2][2][4][2], const Unit& u, int wr, int wc, int fr, int fq) const {
;     ...
;         for (int ai = 0; ai < 2; ++ai)
; #pragma unroll
;             for (int m = 0; m < 4; ++m) { const int row = row0 + ai * HALF + m * 16; const float rs = __shfl(ai ? rsl1 : rsl0, m * 16 + fr); bf16_t* rowp = O + (size_t)row * DFF + col0;
;                 const f32x4 a0 = acc[ai][0][m][0] * rs + ba0, a1 = acc[ai][0][m][1] * rs + ba1, b0 = acc[ai][1][m][0] * rs + bb0, b1 = acc[ai][1][m][1] * rs + bb1;
;                 u32x4 w; w.x = cvt_pk_bf16(silu_mul(a0[0], b0[0]), silu_mul(a0[1], b0[1])); w.y = cvt_pk_bf16(silu_mul(a0[2], b0[2]), silu_mul(a0[3], b0[3]));
;                 w.z = cvt_pk_bf16(silu_mul(a1[0], b1[0]), silu_mul(a1[1], b1[1])); w.w = cvt_pk_bf16(silu_mul(a1[2], b1[2]), silu_mul(a1[3], b1[3]));
;                 *(u32x4*)rowp = w; }
	v_pk_fma_f32 v[128:129], v[128:129], v[244:245], v[80:81] op_sel_hi:[1,0,1]
	v_pk_fma_f32 v[118:119], v[118:119], v[244:245], v[70:71] op_sel_hi:[1,0,1]
	v_pk_fma_f32 v[120:121], v[120:121], v[244:245], v[72:73] op_sel_hi:[1,0,1]
	v_pk_fma_f32 v[122:123], v[122:123], v[244:245], v[74:75] op_sel_hi:[1,0,1]
	v_pk_fma_f32 v[124:125], v[124:125], v[244:245], v[76:77] op_sel_hi:[1,0,1]
	v_pk_fma_f32 v[114:115], v[114:115], v[244:245], v[66:67] op_sel_hi:[1,0,1]
	v_pk_fma_f32 v[116:117], v[116:117], v[244:245], v[68:69] op_sel_hi:[1,0,1]
	v_pk_mul_f32 v[234:235], v[126:127], s[100:101] op_sel_hi:[1,0]
	v_pk_mul_f32 v[236:237], v[128:129], s[100:101] op_sel_hi:[1,0]
	v_exp_f32_e32 v234, v234
	v_exp_f32_e32 v235, v235
	v_exp_f32_e32 v236, v236
	v_exp_f32_e32 v237, v237
	v_pk_add_f32 v[234:235], v[234:235], 1.0 op_sel_hi:[1,0]
	v_pk_add_f32 v[236:237], v[236:237], 1.0 op_sel_hi:[1,0]
	v_rcp_f32_e32 v234, v234
	v_rcp_f32_e32 v235, v235
	v_rcp_f32_e32 v236, v236
	v_rcp_f32_e32 v237, v237
	v_pk_mul_f32 v[118:119], v[126:127], v[118:119]
	v_pk_mul_f32 v[120:121], v[128:129], v[120:121]
	v_pk_mul_f32 v[118:119], v[118:119], v[234:235]
	v_pk_mul_f32 v[120:121], v[120:121], v[236:237]
	v_cvt_pk_bf16_f32 v238, v118, v119
	v_cvt_pk_bf16_f32 v239, v120, v121
	v_pk_mul_f32 v[234:235], v[122:123], s[100:101] op_sel_hi:[1,0]
	v_pk_mul_f32 v[236:237], v[124:125], s[100:101] op_sel_hi:[1,0]
	v_exp_f32_e32 v234, v234
	v_exp_f32_e32 v235, v235
	v_exp_f32_e32 v236, v236
	v_exp_f32_e32 v237, v237
	v_pk_add_f32 v[234:235], v[234:235], 1.0 op_sel_hi:[1,0]
	v_pk_add_f32 v[236:237], v[236:237], 1.0 op_sel_hi:[1,0]
	v_rcp_f32_e32 v234, v234
	v_rcp_f32_e32 v235, v235
	v_rcp_f32_e32 v236, v236
	v_rcp_f32_e32 v237, v237
	v_pk_mul_f32 v[114:115], v[122:123], v[114:115]
	v_pk_mul_f32 v[116:117], v[124:125], v[116:117]
	v_pk_mul_f32 v[114:115], v[114:115], v[234:235]
	v_pk_mul_f32 v[116:117], v[116:117], v[236:237]
	v_cvt_pk_bf16_f32 v240, v114, v115
	v_cvt_pk_bf16_f32 v241, v116, v117
	global_store_dwordx4 v[132:133], v[238:241], off
	v_or_b32_e32 v115, 32, v180
	v_mad_i64_i32 v[116:117], s[2:3], v115, s46, v[162:163]
	v_lshl_add_u64 v[116:117], v[116:117], 0, v[164:165]
	v_pk_fma_f32 v[110:111], v[110:111], v[246:247], v[78:79] op_sel_hi:[1,0,1]
	v_pk_fma_f32 v[112:113], v[112:113], v[246:247], v[80:81] op_sel_hi:[1,0,1]
	v_pk_fma_f32 v[102:103], v[102:103], v[246:247], v[70:71] op_sel_hi:[1,0,1]
	v_pk_fma_f32 v[104:105], v[104:105], v[246:247], v[72:73] op_sel_hi:[1,0,1]
	v_pk_fma_f32 v[106:107], v[106:107], v[246:247], v[74:75] op_sel_hi:[1,0,1]
	v_pk_fma_f32 v[108:109], v[108:109], v[246:247], v[76:77] op_sel_hi:[1,0,1]
	v_pk_fma_f32 v[98:99], v[98:99], v[246:247], v[66:67] op_sel_hi:[1,0,1]
	v_pk_fma_f32 v[100:101], v[100:101], v[246:247], v[68:69] op_sel_hi:[1,0,1]
	v_pk_mul_f32 v[234:235], v[110:111], s[100:101] op_sel_hi:[1,0]
	v_pk_mul_f32 v[236:237], v[112:113], s[100:101] op_sel_hi:[1,0]
	v_exp_f32_e32 v234, v234
	v_exp_f32_e32 v235, v235
	v_exp_f32_e32 v236, v236
	v_exp_f32_e32 v237, v237
	v_pk_add_f32 v[234:235], v[234:235], 1.0 op_sel_hi:[1,0]
	v_pk_add_f32 v[236:237], v[236:237], 1.0 op_sel_hi:[1,0]
	v_rcp_f32_e32 v234, v234
	v_rcp_f32_e32 v235, v235
	v_rcp_f32_e32 v236, v236
	v_rcp_f32_e32 v237, v237
	v_pk_mul_f32 v[102:103], v[110:111], v[102:103]
	v_pk_mul_f32 v[104:105], v[112:113], v[104:105]
	v_pk_mul_f32 v[102:103], v[102:103], v[234:235]
	v_pk_mul_f32 v[104:105], v[104:105], v[236:237]
	v_cvt_pk_bf16_f32 v238, v102, v103
	v_cvt_pk_bf16_f32 v239, v104, v105
	v_pk_mul_f32 v[234:235], v[106:107], s[100:101] op_sel_hi:[1,0]
	v_pk_mul_f32 v[236:237], v[108:109], s[100:101] op_sel_hi:[1,0]
	v_exp_f32_e32 v234, v234
	v_exp_f32_e32 v235, v235
	v_exp_f32_e32 v236, v236
	v_exp_f32_e32 v237, v237
	v_pk_add_f32 v[234:235], v[234:235], 1.0 op_sel_hi:[1,0]
	v_pk_add_f32 v[236:237], v[236:237], 1.0 op_sel_hi:[1,0]
	v_rcp_f32_e32 v234, v234
	v_rcp_f32_e32 v235, v235
	v_rcp_f32_e32 v236, v236
	v_rcp_f32_e32 v237, v237
	v_pk_mul_f32 v[98:99], v[106:107], v[98:99]
	v_pk_mul_f32 v[100:101], v[108:109], v[100:101]
	v_pk_mul_f32 v[98:99], v[98:99], v[234:235]
	v_pk_mul_f32 v[100:101], v[100:101], v[236:237]
	v_cvt_pk_bf16_f32 v240, v98, v99
	v_cvt_pk_bf16_f32 v241, v100, v101
	global_store_dwordx4 v[116:117], v[238:241], off
	v_or_b32_e32 v99, 48, v180
	v_mad_i64_i32 v[100:101], s[2:3], v99, s46, v[162:163]
	v_lshl_add_u64 v[100:101], v[100:101], 0, v[164:165]
	v_pk_fma_f32 v[94:95], v[94:95], v[248:249], v[78:79] op_sel_hi:[1,0,1]
	v_pk_fma_f32 v[96:97], v[96:97], v[248:249], v[80:81] op_sel_hi:[1,0,1]
	v_pk_fma_f32 v[86:87], v[86:87], v[248:249], v[70:71] op_sel_hi:[1,0,1]
	v_pk_fma_f32 v[88:89], v[88:89], v[248:249], v[72:73] op_sel_hi:[1,0,1]
	v_pk_fma_f32 v[90:91], v[90:91], v[248:249], v[74:75] op_sel_hi:[1,0,1]
	v_pk_fma_f32 v[92:93], v[92:93], v[248:249], v[76:77] op_sel_hi:[1,0,1]
	v_pk_fma_f32 v[82:83], v[82:83], v[248:249], v[66:67] op_sel_hi:[1,0,1]
	v_pk_fma_f32 v[84:85], v[84:85], v[248:249], v[68:69] op_sel_hi:[1,0,1]
	v_pk_mul_f32 v[234:235], v[94:95], s[100:101] op_sel_hi:[1,0]
	v_pk_mul_f32 v[236:237], v[96:97], s[100:101] op_sel_hi:[1,0]
	v_exp_f32_e32 v234, v234
	v_exp_f32_e32 v235, v235
	v_exp_f32_e32 v236, v236
	v_exp_f32_e32 v237, v237
	v_pk_add_f32 v[234:235], v[234:235], 1.0 op_sel_hi:[1,0]
	v_pk_add_f32 v[236:237], v[236:237], 1.0 op_sel_hi:[1,0]
	v_rcp_f32_e32 v234, v234
	v_rcp_f32_e32 v235, v235
	v_rcp_f32_e32 v236, v236
	v_rcp_f32_e32 v237, v237
	v_pk_mul_f32 v[86:87], v[94:95], v[86:87]
	v_pk_mul_f32 v[88:89], v[96:97], v[88:89]
	v_pk_mul_f32 v[86:87], v[86:87], v[234:235]
	v_pk_mul_f32 v[88:89], v[88:89], v[236:237]
	v_cvt_pk_bf16_f32 v238, v86, v87
; __device__ __forceinline__ unsigned cvt_pk_bf16(float lo, float hi) { unsigned r; asm volatile("v_cvt_pk_bf16_f32 %0, %1, %2" : "=v"(r) : "v"(lo), "v"(hi)); return r; }
; __device__ __forceinline__ float row_rstd(const float* ss, int row) { return 1.0f / sqrtf(ss[row] * (1.0f / DM) + 1e-6f); }
; __device__ __forceinline__ float silu_mul(float a, float b) { return a * b * __builtin_amdgcn_rcpf(1.0f + __builtin_amdgcn_exp2f(-a * LOG2E)); }
;     __device__ __forceinline__ void operator()(const f32x4 (&acc)[2][2][4][2], const Unit& u, int wr, int wc, int fr, int fq) const {
;     ...
;         const float rsl0 = row_rstd(ss, u.pm * BM + wr * 64 + lane), rsl1 = row_rstd(ss, u.pm * BM + HALF + wr * 64 + lane);
;     ...
;         for (int ai = 0; ai < 2; ++ai)
; #pragma unroll
;             for (int m = 0; m < 4; ++m) { const int row = row0 + ai * HALF + m * 16; const float rs = __shfl(ai ? rsl1 : rsl0, m * 16 + fr); bf16_t* rowp = O + (size_t)row * DFF + col0;
;                 const f32x4 a0 = acc[ai][0][m][0] * rs + ba0, a1 = acc[ai][0][m][1] * rs + ba1, b0 = acc[ai][1][m][0] * rs + bb0, b1 = acc[ai][1][m][1] * rs + bb1;
;                 u32x4 w; w.x = cvt_pk_bf16(silu_mul(a0[0], b0[0]), silu_mul(a0[1], b0[1])); w.y = cvt_pk_bf16(silu_mul(a0[2], b0[2]), silu_mul(a0[3], b0[3]));
;                 w.z = cvt_pk_bf16(silu_mul(a1[0], b1[0]), silu_mul(a1[1], b1[1])); w.w = cvt_pk_bf16(silu_mul(a1[2], b1[2]), silu_mul(a1[3], b1[3]));
;                 *(u32x4*)rowp = w; }
	v_cvt_pk_bf16_f32 v239, v88, v89
	v_pk_mul_f32 v[234:235], v[90:91], s[100:101] op_sel_hi:[1,0]
	v_pk_mul_f32 v[236:237], v[92:93], s[100:101] op_sel_hi:[1,0]
	v_exp_f32_e32 v234, v234
	v_exp_f32_e32 v235, v235
	v_exp_f32_e32 v236, v236
	v_exp_f32_e32 v237, v237
	v_pk_add_f32 v[234:235], v[234:235], 1.0 op_sel_hi:[1,0]
	v_pk_add_f32 v[236:237], v[236:237], 1.0 op_sel_hi:[1,0]
	v_rcp_f32_e32 v234, v234
	v_rcp_f32_e32 v235, v235
	v_rcp_f32_e32 v236, v236
	v_rcp_f32_e32 v237, v237
	v_pk_mul_f32 v[82:83], v[90:91], v[82:83]
	v_pk_mul_f32 v[84:85], v[92:93], v[84:85]
	v_pk_mul_f32 v[82:83], v[82:83], v[234:235]
	v_pk_mul_f32 v[84:85], v[84:85], v[236:237]
	v_cvt_pk_bf16_f32 v240, v82, v83
	v_cvt_pk_bf16_f32 v241, v84, v85
	global_store_dwordx4 v[100:101], v[238:241], off
	s_nop 1
	v_div_scale_f32 v82, s[2:3], v181, v181, 1.0
	v_rcp_f32_e32 v84, v82
	v_add_u32_e32 v83, 0x80, v180
	v_fma_f32 v85, -v82, v84, 1.0
	v_fmac_f32_e32 v84, v85, v84
	v_div_scale_f32 v85, vcc, 1.0, v181, 1.0
	v_mul_f32_e32 v86, v85, v84
	v_fma_f32 v87, -v82, v86, v85
	v_fmac_f32_e32 v86, v87, v84
	v_fma_f32 v82, -v82, v86, v85
	v_div_fmas_f32 v82, v82, v84, v86
	v_div_fixup_f32 v82, v82, v181, 1.0
	ds_bpermute_b32 v242, v179, v82
	ds_bpermute_b32 v244, v179, v82 offset:64
	ds_bpermute_b32 v246, v179, v82 offset:128
	ds_bpermute_b32 v248, v179, v82 offset:192
	v_mad_i64_i32 v[86:87], s[2:3], v83, s46, v[162:163]
	v_lshl_add_u64 v[86:87], v[86:87], 0, v[164:165]
	s_and_b64 vcc, s[38:39], exec
	s_waitcnt lgkmcnt(0)
	v_pk_fma_f32 v[62:63], v[62:63], v[242:243], v[78:79] op_sel_hi:[1,0,1]
	v_pk_fma_f32 v[64:65], v[64:65], v[242:243], v[80:81] op_sel_hi:[1,0,1]
	v_pk_fma_f32 v[54:55], v[54:55], v[242:243], v[70:71] op_sel_hi:[1,0,1]
	v_pk_fma_f32 v[56:57], v[56:57], v[242:243], v[72:73] op_sel_hi:[1,0,1]
	v_pk_fma_f32 v[58:59], v[58:59], v[242:243], v[74:75] op_sel_hi:[1,0,1]
	v_pk_fma_f32 v[60:61], v[60:61], v[242:243], v[76:77] op_sel_hi:[1,0,1]
	v_pk_fma_f32 v[50:51], v[50:51], v[242:243], v[66:67] op_sel_hi:[1,0,1]
	v_pk_fma_f32 v[52:53], v[52:53], v[242:243], v[68:69] op_sel_hi:[1,0,1]
	v_pk_mul_f32 v[234:235], v[62:63], s[100:101] op_sel_hi:[1,0]
	v_pk_mul_f32 v[236:237], v[64:65], s[100:101] op_sel_hi:[1,0]
	v_exp_f32_e32 v234, v234
	v_exp_f32_e32 v235, v235
	v_exp_f32_e32 v236, v236
	v_exp_f32_e32 v237, v237
	v_pk_add_f32 v[234:235], v[234:235], 1.0 op_sel_hi:[1,0]
	v_pk_add_f32 v[236:237], v[236:237], 1.0 op_sel_hi:[1,0]
	v_rcp_f32_e32 v234, v234
	v_rcp_f32_e32 v235, v235
	v_rcp_f32_e32 v236, v236
	v_rcp_f32_e32 v237, v237
	v_pk_mul_f32 v[54:55], v[62:63], v[54:55]
	v_pk_mul_f32 v[56:57], v[64:65], v[56:57]
	v_pk_mul_f32 v[54:55], v[54:55], v[234:235]
	v_pk_mul_f32 v[56:57], v[56:57], v[236:237]
	v_cvt_pk_bf16_f32 v238, v54, v55
	v_cvt_pk_bf16_f32 v239, v56, v57
	v_pk_mul_f32 v[234:235], v[58:59], s[100:101] op_sel_hi:[1,0]
	v_pk_mul_f32 v[236:237], v[60:61], s[100:101] op_sel_hi:[1,0]
	v_exp_f32_e32 v234, v234
	v_exp_f32_e32 v235, v235
	v_exp_f32_e32 v236, v236
	v_exp_f32_e32 v237, v237
	v_pk_add_f32 v[234:235], v[234:235], 1.0 op_sel_hi:[1,0]
	v_pk_add_f32 v[236:237], v[236:237], 1.0 op_sel_hi:[1,0]
	v_rcp_f32_e32 v234, v234
	v_rcp_f32_e32 v235, v235
	v_rcp_f32_e32 v236, v236
	v_rcp_f32_e32 v237, v237
	v_pk_mul_f32 v[50:51], v[58:59], v[50:51]
	v_pk_mul_f32 v[52:53], v[60:61], v[52:53]
	v_pk_mul_f32 v[50:51], v[50:51], v[234:235]
	v_pk_mul_f32 v[52:53], v[52:53], v[236:237]
	v_cvt_pk_bf16_f32 v240, v50, v51
	v_cvt_pk_bf16_f32 v241, v52, v53
	global_store_dwordx4 v[86:87], v[238:241], off
	v_add_u32_e32 v51, 0x90, v180
	v_mad_i64_i32 v[52:53], s[2:3], v51, s46, v[162:163]
	v_lshl_add_u64 v[52:53], v[52:53], 0, v[164:165]
	v_pk_fma_f32 v[46:47], v[46:47], v[244:245], v[78:79] op_sel_hi:[1,0,1]
	v_pk_fma_f32 v[48:49], v[48:49], v[244:245], v[80:81] op_sel_hi:[1,0,1]
	v_pk_fma_f32 v[38:39], v[38:39], v[244:245], v[70:71] op_sel_hi:[1,0,1]
	v_pk_fma_f32 v[40:41], v[40:41], v[244:245], v[72:73] op_sel_hi:[1,0,1]
	v_pk_fma_f32 v[42:43], v[42:43], v[244:245], v[74:75] op_sel_hi:[1,0,1]
	v_pk_fma_f32 v[44:45], v[44:45], v[244:245], v[76:77] op_sel_hi:[1,0,1]
	v_pk_fma_f32 v[34:35], v[34:35], v[244:245], v[66:67] op_sel_hi:[1,0,1]
	v_pk_fma_f32 v[36:37], v[36:37], v[244:245], v[68:69] op_sel_hi:[1,0,1]
	v_pk_mul_f32 v[234:235], v[46:47], s[100:101] op_sel_hi:[1,0]
	v_pk_mul_f32 v[236:237], v[48:49], s[100:101] op_sel_hi:[1,0]
	v_exp_f32_e32 v234, v234
	v_exp_f32_e32 v235, v235
	v_exp_f32_e32 v236, v236
	v_exp_f32_e32 v237, v237
	v_pk_add_f32 v[234:235], v[234:235], 1.0 op_sel_hi:[1,0]
	v_pk_add_f32 v[236:237], v[236:237], 1.0 op_sel_hi:[1,0]
	v_rcp_f32_e32 v234, v234
	v_rcp_f32_e32 v235, v235
	v_rcp_f32_e32 v236, v236
	v_rcp_f32_e32 v237, v237
	v_pk_mul_f32 v[38:39], v[46:47], v[38:39]
	v_pk_mul_f32 v[40:41], v[48:49], v[40:41]
	v_pk_mul_f32 v[38:39], v[38:39], v[234:235]
	v_pk_mul_f32 v[40:41], v[40:41], v[236:237]
	v_cvt_pk_bf16_f32 v238, v38, v39
	v_cvt_pk_bf16_f32 v239, v40, v41
	v_pk_mul_f32 v[234:235], v[42:43], s[100:101] op_sel_hi:[1,0]
	v_pk_mul_f32 v[236:237], v[44:45], s[100:101] op_sel_hi:[1,0]
; __device__ __forceinline__ unsigned cvt_pk_bf16(float lo, float hi) { unsigned r; asm volatile("v_cvt_pk_bf16_f32 %0, %1, %2" : "=v"(r) : "v"(lo), "v"(hi)); return r; }
; __device__ __forceinline__ float silu_mul(float a, float b) { return a * b * __builtin_amdgcn_rcpf(1.0f + __builtin_amdgcn_exp2f(-a * LOG2E)); }
; #define PG8_BAR __builtin_amdgcn_s_barrier()
;     __device__ __forceinline__ void operator()(const f32x4 (&acc)[2][2][4][2], const Unit& u, int wr, int wc, int fr, int fq) const {
;     ...
;         for (int ai = 0; ai < 2; ++ai)
; #pragma unroll
;             for (int m = 0; m < 4; ++m) { const int row = row0 + ai * HALF + m * 16; const float rs = __shfl(ai ? rsl1 : rsl0, m * 16 + fr); bf16_t* rowp = O + (size_t)row * DFF + col0;
;                 const f32x4 a0 = acc[ai][0][m][0] * rs + ba0, a1 = acc[ai][0][m][1] * rs + ba1, b0 = acc[ai][1][m][0] * rs + bb0, b1 = acc[ai][1][m][1] * rs + bb1;
;                 u32x4 w; w.x = cvt_pk_bf16(silu_mul(a0[0], b0[0]), silu_mul(a0[1], b0[1])); w.y = cvt_pk_bf16(silu_mul(a0[2], b0[2]), silu_mul(a0[3], b0[3]));
;                 w.z = cvt_pk_bf16(silu_mul(a1[0], b1[0]), silu_mul(a1[1], b1[1])); w.w = cvt_pk_bf16(silu_mul(a1[2], b1[2]), silu_mul(a1[3], b1[3]));
;                 *(u32x4*)rowp = w; }
; template <class Epi, class Sched, bool ALIGN_EPI = false, bool SP2 = false>
; __device__ __forceinline__ void gemm_phase(LAS unsigned char* lds, const Gemm g, const Sched& S, const Epi& E) {
;     ...
;         if (!has_next) break;
; #pragma unroll
;         for (int a = 0; a < 2; ++a)
; #pragma unroll
;             for (int b = 0; b < 2; ++b)
; #pragma unroll
;                 for (int m = 0; m < 4; ++m)
; #pragma unroll
;                     for (int n = 0; n < 2; ++n) acc[a][b][m][n] = (f32x4){0.f, 0.f, 0.f, 0.f};
;         cur = nxt; cA = nA; cB = nB; ++ui;
;         if constexpr (ALIGN_EPI) { if (wr == 1) PG8_BAR; }
	v_exp_f32_e32 v234, v234
	v_exp_f32_e32 v235, v235
	v_exp_f32_e32 v236, v236
	v_exp_f32_e32 v237, v237
	v_pk_add_f32 v[234:235], v[234:235], 1.0 op_sel_hi:[1,0]
	v_pk_add_f32 v[236:237], v[236:237], 1.0 op_sel_hi:[1,0]
	v_rcp_f32_e32 v234, v234
	v_rcp_f32_e32 v235, v235
	v_rcp_f32_e32 v236, v236
	v_rcp_f32_e32 v237, v237
	v_pk_mul_f32 v[34:35], v[42:43], v[34:35]
	v_pk_mul_f32 v[36:37], v[44:45], v[36:37]
	v_pk_mul_f32 v[34:35], v[34:35], v[234:235]
	v_pk_mul_f32 v[36:37], v[36:37], v[236:237]
	v_cvt_pk_bf16_f32 v240, v34, v35
	v_cvt_pk_bf16_f32 v241, v36, v37
	global_store_dwordx4 v[52:53], v[238:241], off
	v_add_u32_e32 v35, 0xa0, v180
	v_mad_i64_i32 v[36:37], s[2:3], v35, s46, v[162:163]
	v_lshl_add_u64 v[36:37], v[36:37], 0, v[164:165]
	v_pk_fma_f32 v[30:31], v[30:31], v[246:247], v[78:79] op_sel_hi:[1,0,1]
	v_pk_fma_f32 v[32:33], v[32:33], v[246:247], v[80:81] op_sel_hi:[1,0,1]
	v_pk_fma_f32 v[22:23], v[22:23], v[246:247], v[70:71] op_sel_hi:[1,0,1]
	v_pk_fma_f32 v[24:25], v[24:25], v[246:247], v[72:73] op_sel_hi:[1,0,1]
	v_pk_fma_f32 v[26:27], v[26:27], v[246:247], v[74:75] op_sel_hi:[1,0,1]
	v_pk_fma_f32 v[28:29], v[28:29], v[246:247], v[76:77] op_sel_hi:[1,0,1]
	v_pk_fma_f32 v[18:19], v[18:19], v[246:247], v[66:67] op_sel_hi:[1,0,1]
	v_pk_fma_f32 v[20:21], v[20:21], v[246:247], v[68:69] op_sel_hi:[1,0,1]
	v_pk_mul_f32 v[234:235], v[30:31], s[100:101] op_sel_hi:[1,0]
	v_pk_mul_f32 v[236:237], v[32:33], s[100:101] op_sel_hi:[1,0]
	v_exp_f32_e32 v234, v234
	v_exp_f32_e32 v235, v235
	v_exp_f32_e32 v236, v236
	v_exp_f32_e32 v237, v237
	v_pk_add_f32 v[234:235], v[234:235], 1.0 op_sel_hi:[1,0]
	v_pk_add_f32 v[236:237], v[236:237], 1.0 op_sel_hi:[1,0]
	v_rcp_f32_e32 v234, v234
	v_rcp_f32_e32 v235, v235
	v_rcp_f32_e32 v236, v236
	v_rcp_f32_e32 v237, v237
	v_pk_mul_f32 v[22:23], v[30:31], v[22:23]
	v_pk_mul_f32 v[24:25], v[32:33], v[24:25]
	v_pk_mul_f32 v[22:23], v[22:23], v[234:235]
	v_pk_mul_f32 v[24:25], v[24:25], v[236:237]
	v_cvt_pk_bf16_f32 v238, v22, v23
	v_cvt_pk_bf16_f32 v239, v24, v25
	v_pk_mul_f32 v[234:235], v[26:27], s[100:101] op_sel_hi:[1,0]
	v_pk_mul_f32 v[236:237], v[28:29], s[100:101] op_sel_hi:[1,0]
	v_exp_f32_e32 v234, v234
	v_exp_f32_e32 v235, v235
	v_exp_f32_e32 v236, v236
	v_exp_f32_e32 v237, v237
	v_pk_add_f32 v[234:235], v[234:235], 1.0 op_sel_hi:[1,0]
	v_pk_add_f32 v[236:237], v[236:237], 1.0 op_sel_hi:[1,0]
	v_rcp_f32_e32 v234, v234
	v_rcp_f32_e32 v235, v235
	v_rcp_f32_e32 v236, v236
	v_rcp_f32_e32 v237, v237
	v_pk_mul_f32 v[18:19], v[26:27], v[18:19]
	v_pk_mul_f32 v[20:21], v[28:29], v[20:21]
	v_pk_mul_f32 v[18:19], v[18:19], v[234:235]
	v_pk_mul_f32 v[20:21], v[20:21], v[236:237]
	v_cvt_pk_bf16_f32 v240, v18, v19
	v_cvt_pk_bf16_f32 v241, v20, v21
	global_store_dwordx4 v[36:37], v[238:241], off
	v_add_u32_e32 v19, 0xb0, v180
	v_mad_i64_i32 v[20:21], s[2:3], v19, s46, v[162:163]
	v_lshl_add_u64 v[20:21], v[20:21], 0, v[164:165]
	s_mov_b64 s[2:3], -1
	v_pk_fma_f32 v[14:15], v[14:15], v[248:249], v[78:79] op_sel_hi:[1,0,1]
	v_pk_fma_f32 v[16:17], v[16:17], v[248:249], v[80:81] op_sel_hi:[1,0,1]
	v_pk_fma_f32 v[6:7], v[6:7], v[248:249], v[70:71] op_sel_hi:[1,0,1]
	v_pk_fma_f32 v[8:9], v[8:9], v[248:249], v[72:73] op_sel_hi:[1,0,1]
	v_pk_fma_f32 v[10:11], v[10:11], v[248:249], v[74:75] op_sel_hi:[1,0,1]
	v_pk_fma_f32 v[12:13], v[12:13], v[248:249], v[76:77] op_sel_hi:[1,0,1]
	v_pk_fma_f32 v[2:3], v[2:3], v[248:249], v[66:67] op_sel_hi:[1,0,1]
	v_pk_fma_f32 v[4:5], v[4:5], v[248:249], v[68:69] op_sel_hi:[1,0,1]
	v_pk_mul_f32 v[234:235], v[14:15], s[100:101] op_sel_hi:[1,0]
	v_pk_mul_f32 v[236:237], v[16:17], s[100:101] op_sel_hi:[1,0]
	v_exp_f32_e32 v234, v234
	v_exp_f32_e32 v235, v235
	v_exp_f32_e32 v236, v236
	v_exp_f32_e32 v237, v237
	v_pk_add_f32 v[234:235], v[234:235], 1.0 op_sel_hi:[1,0]
	v_pk_add_f32 v[236:237], v[236:237], 1.0 op_sel_hi:[1,0]
	v_rcp_f32_e32 v234, v234
	v_rcp_f32_e32 v235, v235
	v_rcp_f32_e32 v236, v236
	v_rcp_f32_e32 v237, v237
	v_pk_mul_f32 v[6:7], v[14:15], v[6:7]
	v_pk_mul_f32 v[8:9], v[16:17], v[8:9]
	v_pk_mul_f32 v[6:7], v[6:7], v[234:235]
	v_pk_mul_f32 v[8:9], v[8:9], v[236:237]
	v_cvt_pk_bf16_f32 v238, v6, v7
	v_cvt_pk_bf16_f32 v239, v8, v9
	v_pk_mul_f32 v[234:235], v[10:11], s[100:101] op_sel_hi:[1,0]
	v_pk_mul_f32 v[236:237], v[12:13], s[100:101] op_sel_hi:[1,0]
	v_exp_f32_e32 v234, v234
	v_exp_f32_e32 v235, v235
	v_exp_f32_e32 v236, v236
	v_exp_f32_e32 v237, v237
	v_pk_add_f32 v[234:235], v[234:235], 1.0 op_sel_hi:[1,0]
	v_pk_add_f32 v[236:237], v[236:237], 1.0 op_sel_hi:[1,0]
	v_rcp_f32_e32 v234, v234
	v_rcp_f32_e32 v235, v235
	v_rcp_f32_e32 v236, v236
	v_rcp_f32_e32 v237, v237
	v_pk_mul_f32 v[2:3], v[10:11], v[2:3]
	v_pk_mul_f32 v[4:5], v[12:13], v[4:5]
	v_pk_mul_f32 v[2:3], v[2:3], v[234:235]
	v_pk_mul_f32 v[4:5], v[4:5], v[236:237]
	v_cvt_pk_bf16_f32 v240, v2, v3
	v_cvt_pk_bf16_f32 v241, v4, v5
	global_store_dwordx4 v[20:21], v[238:241], off
	s_cbranch_vccz .LBB0_1818
	s_andn2_b64 vcc, exec, s[4:5]
	s_cbranch_vccnz .LBB0_1817
	s_barrier
	s_branch .LBB0_1817

; #define PG8_STAGE(bufoff, gbase, voff) do { _Pragma("unroll") for (int _i = 0; _i < 2; ++_i) \
;         __builtin_amdgcn_global_load_lds((const unsigned*)((const char*)(gbase) + (voff)[_i]), (LAS unsigned*)(lds + (bufoff) + ldsw + _i * 8192), 16, 0, 0); } while (0)
; #define PG8_LDA(dst, b, h) do { _Pragma("unroll") for (int m = 0; m < 4; ++m) _Pragma("unroll") for (int k = 0; k < 2; ++k) dst[m][k] = *(const LAS bf16x8*)(lds + PG8_SA(b, h) + aoff + m * 2048 + k * 1024); } while (0)
; #define PG8_LDB(dst, b, h) do { _Pragma("unroll") for (int n = 0; n < 2; ++n) _Pragma("unroll") for (int k = 0; k < 2; ++k) dst[n][k] = *(const LAS bf16x8*)(lds + PG8_SB(b, h) + boff + n * 2048 + k * 1024); } while (0)
; #define PG8_MMA(ai, bj, At, Bt) do { __builtin_amdgcn_s_setprio(1); _Pragma("unroll") for (int m = 0; m < 4; ++m) _Pragma("unroll") for (int n = 0; n < 2; ++n) _Pragma("unroll") for (int k = 0; k < 2; ++k) \
;         acc[ai][bj][m][n] = __builtin_amdgcn_mfma_f32_16x16x32_bf16(Bt[n][k], At[m][k], acc[ai][bj][m][n], 0, 0, 0); __builtin_amdgcn_s_setprio(0); } while (0)
; #define PG8_WAIT_V(n) asm volatile("s_waitcnt vmcnt(" #n ")" ::: "memory")
; #define PG8_WAIT_L(n) asm volatile("s_waitcnt lgkmcnt(" #n ")" ::: "memory")
; template <class Epi, class Sched, bool ALIGN_EPI = false, bool SP2 = false>
; __device__ __forceinline__ void gemm_phase(LAS unsigned char* lds, const Gemm g, const Sched& S, const Epi& E) {
;     ...
;         for (int t = 0; t < nt; t += 2) {
;             const bool last = (t == nt - 2);
;             const char* a1 = cA + (size_t)(t + 1) * kstep;
;             const char* a2 = last ? nA : cA + (size_t)(t + 2) * kstep; const char* b2 = last ? nB : cB + (size_t)(t + 2) * kstep;
;             const char* a3 = a2 + kstep; const char* b3 = b2 + kstep;
;             if (last && has_next) S.a_ready(nxt);
;             if constexpr (SP2) {
;             PG8_LDB(B0, 0, 0); PG8_LDB(B1, 0, 1); PG8_SCHED; PG8_LDA(At, 0, 0); PG8_STAGE(PG8_SA(1, 1), a1 + hstep, voffA);
;             PG8_WAIT_V(8); PG8_WAIT_L(0); PG8_BAR; PG8_MMA(0, 0, At, B0); PG8_MMA(0, 1, At, B1); PG8_BAR; PG8_SCHED;
;             PG8_LDA(At, 0, 1); PG8_STAGE(PG8_SB(0, 0), b2, voffB); PG8_STAGE(PG8_SB(0, 1), b2 + hstepB, voffB); PG8_STAGE(PG8_SA(0, 0), a2, voffA);
;             PG8_WAIT_V(8); PG8_WAIT_L(0); PG8_BAR; PG8_MMA(1, 0, At, B0); PG8_MMA(1, 1, At, B1); PG8_BAR; PG8_SCHED;
.LBB0_2916:
	ds_read_b128 v[66:69], v173
	ds_read_b128 v[70:73], v173 offset:1024
	ds_read_b128 v[74:77], v173 offset:2048
	ds_read_b128 v[78:81], v173 offset:3072
	ds_read_b128 v[162:165], v174
	ds_read_b128 v[180:183], v174 offset:1024
	ds_read_b128 v[184:187], v174 offset:2048
	ds_read_b128 v[188:191], v174 offset:3072
	s_add_u32 s20, s18, 0xfff80080
	s_addc_u32 s21, s19, -1
	s_cmp_eq_u32 s50, 28
	s_cselect_b32 s23, s13, s21
	s_cselect_b32 s22, s46, s20
	s_cselect_b32 s21, s11, s49
	s_cselect_b32 s20, s47, s48
	s_add_i32 m0, s28, 0xc000
	ds_read_b128 v[192:195], v175
	ds_read_b128 v[196:199], v175 offset:1024
	ds_read_b128 v[200:203], v175 offset:2048
	ds_read_b128 v[204:207], v175 offset:3072
	ds_read_b128 v[208:211], v175 offset:4096
	ds_read_b128 v[212:215], v175 offset:5120
	ds_read_b128 v[216:219], v175 offset:6144
	ds_read_b128 v[220:223], v175 offset:7168
	global_load_lds_dwordx4 v156, s[18:19]
	s_add_i32 m0, s28, 0xe000
	s_nop 0
	global_load_lds_dwordx4 v154, s[18:19]
	s_waitcnt vmcnt(8)
	s_waitcnt lgkmcnt(0)
	s_barrier
	s_waitcnt lgkmcnt(0)
	v_mfma_f32_16x16x32_bf16 v[142:145], v[66:69], v[192:195], v[142:145]
	v_mfma_f32_16x16x32_bf16 v[138:141], v[74:77], v[192:195], v[138:141]
	v_mfma_f32_16x16x32_bf16 v[126:129], v[66:69], v[200:203], v[126:129]
	v_mfma_f32_16x16x32_bf16 v[122:125], v[74:77], v[200:203], v[122:125]
	v_mfma_f32_16x16x32_bf16 v[110:113], v[66:69], v[208:211], v[110:113]
	v_mfma_f32_16x16x32_bf16 v[106:109], v[74:77], v[208:211], v[106:109]
	v_mfma_f32_16x16x32_bf16 v[94:97], v[66:69], v[216:219], v[94:97]
	v_mfma_f32_16x16x32_bf16 v[90:93], v[74:77], v[216:219], v[90:93]
	v_mfma_f32_16x16x32_bf16 v[142:145], v[70:73], v[196:199], v[142:145]
	v_mfma_f32_16x16x32_bf16 v[138:141], v[78:81], v[196:199], v[138:141]
	v_mfma_f32_16x16x32_bf16 v[126:129], v[70:73], v[204:207], v[126:129]
	v_mfma_f32_16x16x32_bf16 v[122:125], v[78:81], v[204:207], v[122:125]
	v_mfma_f32_16x16x32_bf16 v[110:113], v[70:73], v[212:215], v[110:113]
	v_mfma_f32_16x16x32_bf16 v[106:109], v[78:81], v[212:215], v[106:109]
	v_mfma_f32_16x16x32_bf16 v[94:97], v[70:73], v[220:223], v[94:97]
	v_mfma_f32_16x16x32_bf16 v[90:93], v[78:81], v[220:223], v[90:93]
	v_mfma_f32_16x16x32_bf16 v[134:137], v[162:165], v[192:195], v[134:137]
	v_mfma_f32_16x16x32_bf16 v[130:133], v[184:187], v[192:195], v[130:133]
	v_mfma_f32_16x16x32_bf16 v[118:121], v[162:165], v[200:203], v[118:121]
	v_mfma_f32_16x16x32_bf16 v[114:117], v[184:187], v[200:203], v[114:117]
	v_mfma_f32_16x16x32_bf16 v[102:105], v[162:165], v[208:211], v[102:105]
	v_mfma_f32_16x16x32_bf16 v[98:101], v[184:187], v[208:211], v[98:101]
	v_mfma_f32_16x16x32_bf16 v[86:89], v[162:165], v[216:219], v[86:89]
	v_mfma_f32_16x16x32_bf16 v[82:85], v[184:187], v[216:219], v[82:85]
	v_mfma_f32_16x16x32_bf16 v[134:137], v[180:183], v[196:199], v[134:137]
	v_mfma_f32_16x16x32_bf16 v[130:133], v[188:191], v[196:199], v[130:133]
	v_mfma_f32_16x16x32_bf16 v[118:121], v[180:183], v[204:207], v[118:121]
	v_mfma_f32_16x16x32_bf16 v[114:117], v[188:191], v[204:207], v[114:117]
	v_mfma_f32_16x16x32_bf16 v[102:105], v[180:183], v[212:215], v[102:105]
	v_mfma_f32_16x16x32_bf16 v[98:101], v[188:191], v[212:215], v[98:101]
	v_mfma_f32_16x16x32_bf16 v[86:89], v[180:183], v[220:223], v[86:89]
	v_mfma_f32_16x16x32_bf16 v[82:85], v[188:191], v[220:223], v[82:85]
	s_barrier
	s_add_i32 s51, s41, s25
	s_mov_b32 m0, s51
	ds_read_b128 v[192:195], v175 offset:16384
	ds_read_b128 v[196:199], v175 offset:17408
	ds_read_b128 v[200:203], v175 offset:18432
	ds_read_b128 v[204:207], v175 offset:19456
	ds_read_b128 v[208:211], v175 offset:20480
	ds_read_b128 v[212:215], v175 offset:21504
	ds_read_b128 v[216:219], v175 offset:22528
	ds_read_b128 v[220:223], v175 offset:23552
	global_load_lds_dwordx4 v150, s[20:21]
	s_add_i32 m0, s51, 0x2000
	s_add_u32 s52, s20, 0x80000
	v_lshl_add_u64 v[224:225], s[20:21], 0, v[146:147]
	s_addc_u32 s53, s21, 0
	s_add_i32 s51, s42, s25
	global_load_lds_dwordx4 v146, s[20:21]
	s_mov_b32 m0, s51
	v_lshl_add_u64 v[228:229], s[22:23], 0, v[148:149]
	global_load_lds_dwordx4 v150, s[52:53]
	s_add_i32 m0, s51, 0x2000
	s_nop 0
	global_load_lds_dwordx4 v146, s[52:53]
	v_lshl_add_u64 v[226:227], s[22:23], 0, v[152:153]
	s_mov_b32 m0, s28
	s_nop 0
	global_load_lds_dwordx4 v152, s[22:23]
	s_mov_b32 m0, s29
	s_nop 0
	global_load_lds_dwordx4 v148, s[22:23]
	s_waitcnt vmcnt(8)
	s_waitcnt lgkmcnt(0)
	s_barrier
	s_waitcnt lgkmcnt(0)
	v_mfma_f32_16x16x32_bf16 v[62:65], v[66:69], v[192:195], v[62:65]
	v_mfma_f32_16x16x32_bf16 v[58:61], v[74:77], v[192:195], v[58:61]
	v_mfma_f32_16x16x32_bf16 v[46:49], v[66:69], v[200:203], v[46:49]
	v_mfma_f32_16x16x32_bf16 v[42:45], v[74:77], v[200:203], v[42:45]
	v_mfma_f32_16x16x32_bf16 v[30:33], v[66:69], v[208:211], v[30:33]
	v_mfma_f32_16x16x32_bf16 v[26:29], v[74:77], v[208:211], v[26:29]
	v_mfma_f32_16x16x32_bf16 v[14:17], v[66:69], v[216:219], v[14:17]
	v_mfma_f32_16x16x32_bf16 v[10:13], v[74:77], v[216:219], v[10:13]
	v_mfma_f32_16x16x32_bf16 v[62:65], v[70:73], v[196:199], v[62:65]
	v_mfma_f32_16x16x32_bf16 v[58:61], v[78:81], v[196:199], v[58:61]
	v_mfma_f32_16x16x32_bf16 v[46:49], v[70:73], v[204:207], v[46:49]
	v_mfma_f32_16x16x32_bf16 v[42:45], v[78:81], v[204:207], v[42:45]
	v_mfma_f32_16x16x32_bf16 v[30:33], v[70:73], v[212:215], v[30:33]
	v_mfma_f32_16x16x32_bf16 v[26:29], v[78:81], v[212:215], v[26:29]
	v_mfma_f32_16x16x32_bf16 v[14:17], v[70:73], v[220:223], v[14:17]
	v_mfma_f32_16x16x32_bf16 v[10:13], v[78:81], v[220:223], v[10:13]
	v_mfma_f32_16x16x32_bf16 v[54:57], v[162:165], v[192:195], v[54:57]
	v_mfma_f32_16x16x32_bf16 v[50:53], v[184:187], v[192:195], v[50:53]
	v_mfma_f32_16x16x32_bf16 v[38:41], v[162:165], v[200:203], v[38:41]
	v_mfma_f32_16x16x32_bf16 v[34:37], v[184:187], v[200:203], v[34:37]
	v_mfma_f32_16x16x32_bf16 v[22:25], v[162:165], v[208:211], v[22:25]
	v_mfma_f32_16x16x32_bf16 v[18:21], v[184:187], v[208:211], v[18:21]
	v_mfma_f32_16x16x32_bf16 v[6:9], v[162:165], v[216:219], v[6:9]
	v_mfma_f32_16x16x32_bf16 v[2:5], v[184:187], v[216:219], v[2:5]
	v_mfma_f32_16x16x32_bf16 v[54:57], v[180:183], v[196:199], v[54:57]
	v_mfma_f32_16x16x32_bf16 v[50:53], v[188:191], v[196:199], v[50:53]
	v_mfma_f32_16x16x32_bf16 v[38:41], v[180:183], v[204:207], v[38:41]
	v_mfma_f32_16x16x32_bf16 v[34:37], v[188:191], v[204:207], v[34:37]
	v_mfma_f32_16x16x32_bf16 v[22:25], v[180:183], v[212:215], v[22:25]
	v_mfma_f32_16x16x32_bf16 v[18:21], v[188:191], v[212:215], v[18:21]
	v_mfma_f32_16x16x32_bf16 v[6:9], v[180:183], v[220:223], v[6:9]
	v_mfma_f32_16x16x32_bf16 v[2:5], v[188:191], v[220:223], v[2:5]
	s_barrier
; #define PG8_STAGE(bufoff, gbase, voff) do { _Pragma("unroll") for (int _i = 0; _i < 2; ++_i) \
;         __builtin_amdgcn_global_load_lds((const unsigned*)((const char*)(gbase) + (voff)[_i]), (LAS unsigned*)(lds + (bufoff) + ldsw + _i * 8192), 16, 0, 0); } while (0)
; #define PG8_BAR __builtin_amdgcn_s_barrier()
; template <class Epi, class Sched, bool ALIGN_EPI = false, bool SP2 = false>
; __device__ __forceinline__ void gemm_phase(LAS unsigned char* lds, const Gemm g, const Sched& S, const Epi& E) {
;     ...
;             PG8_LDB(B0, 1, 0); PG8_LDB(B1, 1, 1); PG8_SCHED; PG8_LDA(At, 1, 0); PG8_STAGE(PG8_SA(0, 1), a2 + hstep, voffA);
;             PG8_WAIT_V(8); PG8_WAIT_L(0); PG8_BAR; PG8_MMA(0, 0, At, B0); PG8_MMA(0, 1, At, B1); PG8_BAR; PG8_SCHED;
;             PG8_LDA(At, 1, 1); PG8_STAGE(PG8_SB(1, 0), b3, voffB); PG8_STAGE(PG8_SB(1, 1), b3 + hstepB, voffB); PG8_STAGE(PG8_SA(1, 0), a3, voffA);
;             PG8_WAIT_V(8); PG8_WAIT_L(0); PG8_BAR; PG8_MMA(1, 0, At, B0); PG8_MMA(1, 1, At, B1); PG8_BAR; PG8_SCHED;
;             } else {
;             PG8_LDB(B0, 0, 0); PG8_SCHED; PG8_LDA(At, 0, 0); PG8_STAGE(PG8_SA(1, 1), a1 + hstep, voffA);
;             PG8_WAIT_L(8); PG8_BAR; PG8_WAIT_L(0); PG8_MMA(0, 0, At, B0); PG8_BAR; PG8_SCHED;
;             PG8_LDB(B1, 0, 1); PG8_STAGE(PG8_SB(0, 0), b2, voffB);
;             PG8_BAR; PG8_WAIT_L(0); PG8_MMA(0, 1, At, B1); PG8_BAR;
;             PG8_LDA(At, 0, 1); PG8_STAGE(PG8_SA(0, 0), a2, voffA);
;             PG8_BAR; PG8_WAIT_L(0); PG8_MMA(1, 0, At, B0); PG8_BAR; PG8_SCHED;
;             PG8_STAGE(PG8_SB(0, 1), b2 + hstepB, voffB);
;             PG8_WAIT_V(6); PG8_BAR; PG8_MMA(1, 1, At, B1); PG8_BAR;
;             PG8_LDB(B0, 1, 0); PG8_SCHED; PG8_LDA(At, 1, 0); PG8_STAGE(PG8_SA(0, 1), a2 + hstep, voffA);
;             PG8_WAIT_L(8); PG8_BAR; PG8_WAIT_L(0); PG8_MMA(0, 0, At, B0); PG8_BAR; PG8_SCHED;
;             PG8_LDB(B1, 1, 1); PG8_STAGE(PG8_SB(1, 0), b3, voffB);
;             PG8_BAR; PG8_WAIT_L(0); PG8_MMA(0, 1, At, B1); PG8_BAR;
;             PG8_LDA(At, 1, 1); PG8_STAGE(PG8_SA(1, 0), a3, voffA);
;             PG8_BAR; PG8_WAIT_L(0); PG8_MMA(1, 0, At, B0); PG8_BAR; PG8_SCHED;
;             PG8_STAGE(PG8_SB(1, 1), b3 + hstepB, voffB);
;             PG8_WAIT_V(6); PG8_BAR; PG8_MMA(1, 1, At, B1); PG8_BAR;
;             }
;         }
;         if constexpr (ALIGN_EPI) { if (wr == 0) PG8_BAR; }
	s_add_i32 s51, 0, 0x18000
	s_add_i32 s52, 0, 0x1c000
	v_add_u32_e32 v78, s51, v169
	v_add_u32_e32 v168, s52, v169
	ds_read_b128 v[66:69], v78
	ds_read_b128 v[70:73], v78 offset:1024
	ds_read_b128 v[74:77], v78 offset:2048
	ds_read_b128 v[78:81], v78 offset:3072
	ds_read_b128 v[162:165], v168
	ds_read_b128 v[180:183], v168 offset:1024
	ds_read_b128 v[184:187], v168 offset:2048
	ds_read_b128 v[188:191], v168 offset:3072
	s_add_u32 s22, s22, 0x80000
	s_addc_u32 s23, s23, 0
	s_mov_b32 m0, s30
	ds_read_b128 v[192:195], v175 offset:32768
	ds_read_b128 v[196:199], v175 offset:33792
	ds_read_b128 v[200:203], v175 offset:34816
	ds_read_b128 v[204:207], v175 offset:35840
	ds_read_b128 v[208:211], v175 offset:36864
	ds_read_b128 v[212:215], v175 offset:37888
	ds_read_b128 v[216:219], v175 offset:38912
	ds_read_b128 v[220:223], v175 offset:39936
	global_load_lds_dwordx4 v152, s[22:23]
	s_mov_b32 m0, s31
	s_nop 0
	global_load_lds_dwordx4 v148, s[22:23]
	s_waitcnt vmcnt(8)
	s_waitcnt lgkmcnt(0)
	s_barrier
	s_waitcnt lgkmcnt(0)
	v_mfma_f32_16x16x32_bf16 v[142:145], v[66:69], v[192:195], v[142:145]
	v_mfma_f32_16x16x32_bf16 v[138:141], v[74:77], v[192:195], v[138:141]
	v_mfma_f32_16x16x32_bf16 v[126:129], v[66:69], v[200:203], v[126:129]
	v_mfma_f32_16x16x32_bf16 v[122:125], v[74:77], v[200:203], v[122:125]
	v_mfma_f32_16x16x32_bf16 v[110:113], v[66:69], v[208:211], v[110:113]
	v_mfma_f32_16x16x32_bf16 v[106:109], v[74:77], v[208:211], v[106:109]
	v_mfma_f32_16x16x32_bf16 v[94:97], v[66:69], v[216:219], v[94:97]
	v_mfma_f32_16x16x32_bf16 v[90:93], v[74:77], v[216:219], v[90:93]
	v_mfma_f32_16x16x32_bf16 v[142:145], v[70:73], v[196:199], v[142:145]
	v_mfma_f32_16x16x32_bf16 v[138:141], v[78:81], v[196:199], v[138:141]
	v_mfma_f32_16x16x32_bf16 v[126:129], v[70:73], v[204:207], v[126:129]
	v_mfma_f32_16x16x32_bf16 v[122:125], v[78:81], v[204:207], v[122:125]
	v_mfma_f32_16x16x32_bf16 v[110:113], v[70:73], v[212:215], v[110:113]
	v_mfma_f32_16x16x32_bf16 v[106:109], v[78:81], v[212:215], v[106:109]
	v_mfma_f32_16x16x32_bf16 v[94:97], v[70:73], v[220:223], v[94:97]
	v_mfma_f32_16x16x32_bf16 v[90:93], v[78:81], v[220:223], v[90:93]
	v_mfma_f32_16x16x32_bf16 v[134:137], v[162:165], v[192:195], v[134:137]
	v_mfma_f32_16x16x32_bf16 v[130:133], v[184:187], v[192:195], v[130:133]
	v_mfma_f32_16x16x32_bf16 v[118:121], v[162:165], v[200:203], v[118:121]
	v_mfma_f32_16x16x32_bf16 v[114:117], v[184:187], v[200:203], v[114:117]
	v_mfma_f32_16x16x32_bf16 v[102:105], v[162:165], v[208:211], v[102:105]
	v_mfma_f32_16x16x32_bf16 v[98:101], v[184:187], v[208:211], v[98:101]
	v_mfma_f32_16x16x32_bf16 v[86:89], v[162:165], v[216:219], v[86:89]
	v_mfma_f32_16x16x32_bf16 v[82:85], v[184:187], v[216:219], v[82:85]
	v_mfma_f32_16x16x32_bf16 v[134:137], v[180:183], v[196:199], v[134:137]
	v_mfma_f32_16x16x32_bf16 v[130:133], v[188:191], v[196:199], v[130:133]
	v_mfma_f32_16x16x32_bf16 v[118:121], v[180:183], v[204:207], v[118:121]
	v_mfma_f32_16x16x32_bf16 v[114:117], v[188:191], v[204:207], v[114:117]
	v_mfma_f32_16x16x32_bf16 v[102:105], v[180:183], v[212:215], v[102:105]
	v_mfma_f32_16x16x32_bf16 v[98:101], v[188:191], v[212:215], v[98:101]
	v_mfma_f32_16x16x32_bf16 v[86:89], v[180:183], v[220:223], v[86:89]
	v_mfma_f32_16x16x32_bf16 v[82:85], v[188:191], v[220:223], v[82:85]
	s_barrier
	s_add_u32 s98, s20, 0x80
	s_addc_u32 s99, s21, 0
	s_add_i32 s22, s51, s25
	s_mov_b32 m0, s22
	ds_read_b128 v[192:195], v175 offset:49152
	ds_read_b128 v[196:199], v175 offset:50176
	ds_read_b128 v[200:203], v175 offset:51200
	ds_read_b128 v[204:207], v175 offset:52224
	ds_read_b128 v[208:211], v175 offset:53248
	ds_read_b128 v[212:215], v175 offset:54272
	ds_read_b128 v[216:219], v175 offset:55296
	ds_read_b128 v[220:223], v175 offset:56320
	global_load_lds_dwordx4 v150, s[98:99]
	s_add_i32 m0, s22, 0x2000
	s_add_u32 s20, s20, 0x80080
	v_lshl_add_u64 v[166:167], v[224:225], 0, s[6:7]
	s_addc_u32 s21, s21, 0
	s_add_i32 s22, s52, s25
	global_load_lds_dwordx4 v[166:167], off
	s_mov_b32 m0, s22
	s_nop 0
	global_load_lds_dwordx4 v150, s[20:21]
	s_add_i32 m0, s22, 0x2000
	s_nop 0
	global_load_lds_dwordx4 v146, s[20:21]
	v_lshl_add_u64 v[166:167], v[226:227], 0, s[6:7]
	s_mov_b32 m0, s39
	s_nop 0
	global_load_lds_dwordx4 v[166:167], off
	v_lshl_add_u64 v[166:167], v[228:229], 0, s[6:7]
	s_mov_b32 m0, s40
	s_nop 0
	global_load_lds_dwordx4 v[166:167], off
	s_waitcnt vmcnt(8)
	s_waitcnt lgkmcnt(0)
	s_barrier
	s_waitcnt lgkmcnt(0)
	v_mfma_f32_16x16x32_bf16 v[62:65], v[66:69], v[192:195], v[62:65]
	v_mfma_f32_16x16x32_bf16 v[58:61], v[74:77], v[192:195], v[58:61]
	v_mfma_f32_16x16x32_bf16 v[46:49], v[66:69], v[200:203], v[46:49]
	v_mfma_f32_16x16x32_bf16 v[42:45], v[74:77], v[200:203], v[42:45]
	v_mfma_f32_16x16x32_bf16 v[30:33], v[66:69], v[208:211], v[30:33]
	v_mfma_f32_16x16x32_bf16 v[26:29], v[74:77], v[208:211], v[26:29]
	v_mfma_f32_16x16x32_bf16 v[14:17], v[66:69], v[216:219], v[14:17]
	v_mfma_f32_16x16x32_bf16 v[10:13], v[74:77], v[216:219], v[10:13]
	v_mfma_f32_16x16x32_bf16 v[62:65], v[70:73], v[196:199], v[62:65]
	v_mfma_f32_16x16x32_bf16 v[58:61], v[78:81], v[196:199], v[58:61]
	v_mfma_f32_16x16x32_bf16 v[46:49], v[70:73], v[204:207], v[46:49]
	v_mfma_f32_16x16x32_bf16 v[42:45], v[78:81], v[204:207], v[42:45]
	v_mfma_f32_16x16x32_bf16 v[30:33], v[70:73], v[212:215], v[30:33]
	v_mfma_f32_16x16x32_bf16 v[26:29], v[78:81], v[212:215], v[26:29]
	v_mfma_f32_16x16x32_bf16 v[14:17], v[70:73], v[220:223], v[14:17]
	v_mfma_f32_16x16x32_bf16 v[10:13], v[78:81], v[220:223], v[10:13]
	v_mfma_f32_16x16x32_bf16 v[54:57], v[162:165], v[192:195], v[54:57]
	v_mfma_f32_16x16x32_bf16 v[50:53], v[184:187], v[192:195], v[50:53]
	v_mfma_f32_16x16x32_bf16 v[38:41], v[162:165], v[200:203], v[38:41]
	v_mfma_f32_16x16x32_bf16 v[34:37], v[184:187], v[200:203], v[34:37]
	v_mfma_f32_16x16x32_bf16 v[22:25], v[162:165], v[208:211], v[22:25]
	v_mfma_f32_16x16x32_bf16 v[18:21], v[184:187], v[208:211], v[18:21]
	v_mfma_f32_16x16x32_bf16 v[6:9], v[162:165], v[216:219], v[6:9]
	v_mfma_f32_16x16x32_bf16 v[2:5], v[184:187], v[216:219], v[2:5]
	v_mfma_f32_16x16x32_bf16 v[54:57], v[180:183], v[196:199], v[54:57]
	v_mfma_f32_16x16x32_bf16 v[50:53], v[188:191], v[196:199], v[50:53]
	v_mfma_f32_16x16x32_bf16 v[38:41], v[180:183], v[204:207], v[38:41]
	v_mfma_f32_16x16x32_bf16 v[34:37], v[188:191], v[204:207], v[34:37]
	v_mfma_f32_16x16x32_bf16 v[22:25], v[180:183], v[212:215], v[22:25]
	v_mfma_f32_16x16x32_bf16 v[18:21], v[188:191], v[212:215], v[18:21]
	v_mfma_f32_16x16x32_bf16 v[6:9], v[180:183], v[220:223], v[6:9]
	v_mfma_f32_16x16x32_bf16 v[2:5], v[188:191], v[220:223], v[2:5]
	s_barrier
	s_add_i32 s50, s50, 2
	s_add_u32 s48, s48, 0x100
	s_addc_u32 s49, s49, 0
	s_add_u32 s18, s18, 0x100
	s_addc_u32 s19, s19, 0
	s_cmp_lt_u32 s50, 30
	s_cbranch_scc1 .LBB0_2916
	s_setprio 0
	s_mov_b64 s[48:49], s[64:65]
	s_cmpk_gt_i32 s2, 0x7f
	s_mov_b64 s[18:19], 0xb000
	s_mov_b64 s[50:51], s[66:67]
	s_cbranch_scc1 .LBB0_2921
	s_ashr_i32 s11, s2, 5
	s_mul_hi_i32 s19, s11, 0x2c00
	s_mul_i32 s18, s11, 0x2c00
; __device__ __forceinline__ unsigned cvt_pk_bf16(float lo, float hi) { unsigned r; asm volatile("v_cvt_pk_bf16_f32 %0, %1, %2" : "=v"(r) : "v"(lo), "v"(hi)); return r; }
; __device__ __forceinline__ float row_rstd(const float* ss, int row) { return 1.0f / sqrtf(ss[row] * (1.0f / DM) + 1e-6f); }
; __device__ __forceinline__ float silu_mul(float a, float b) { return a * b * __builtin_amdgcn_rcpf(1.0f + __builtin_amdgcn_exp2f(-a * LOG2E)); }
; #define PG8_BAR __builtin_amdgcn_s_barrier()
;     __device__ __forceinline__ void operator()(const f32x4 (&acc)[2][2][4][2], const Unit& u, int wr, int wc, int fr, int fq) const {
;         const int row0 = u.pm * BM + wr * 64 + fr, col0 = u.pn * HALF + wc * 32 + 8 * fq;
;         const int s = (u.pm < ML / BM) ? (u.pm >> 5) : 4;
;         const float* bp = bias + (size_t)s * BIAS_N + u.pn * BM + wc * 32 + 8 * fq;
;         const f32x4 ba0 = *(const f32x4*)bp, ba1 = *(const f32x4*)(bp + 4), bb0 = *(const f32x4*)(bp + HALF), bb1 = *(const f32x4*)(bp + HALF + 4);
;         const int lane = fq * 16 + fr;
;         const float rsl0 = row_rstd(ss, u.pm * BM + wr * 64 + lane), rsl1 = row_rstd(ss, u.pm * BM + HALF + wr * 64 + lane);
; #pragma unroll
;         for (int ai = 0; ai < 2; ++ai)
; #pragma unroll
;             for (int m = 0; m < 4; ++m) { const int row = row0 + ai * HALF + m * 16; const float rs = __shfl(ai ? rsl1 : rsl0, m * 16 + fr); bf16_t* rowp = O + (size_t)row * DFF + col0;
;                 const f32x4 a0 = acc[ai][0][m][0] * rs + ba0, a1 = acc[ai][0][m][1] * rs + ba1, b0 = acc[ai][1][m][0] * rs + bb0, b1 = acc[ai][1][m][1] * rs + bb1;
;                 u32x4 w; w.x = cvt_pk_bf16(silu_mul(a0[0], b0[0]), silu_mul(a0[1], b0[1])); w.y = cvt_pk_bf16(silu_mul(a0[2], b0[2]), silu_mul(a0[3], b0[3]));
;                 w.z = cvt_pk_bf16(silu_mul(a1[0], b1[0]), silu_mul(a1[1], b1[1])); w.w = cvt_pk_bf16(silu_mul(a1[2], b1[2]), silu_mul(a1[3], b1[3]));
;                 *(u32x4*)rowp = w; }
; template <class Epi, class Sched, bool ALIGN_EPI = false, bool SP2 = false>
; __device__ __forceinline__ void gemm_phase(LAS unsigned char* lds, const Gemm g, const Sched& S, const Epi& E) {
;     ...
;         if constexpr (ALIGN_EPI) { if (wr == 0) PG8_BAR; }
;         if constexpr (!Epi::AFTER_DRAIN) { E(acc, cur, wr, wc, fr, fq); S.done(cur); }
.LBB0_2921:
	s_lshl_b32 s2, s2, 8
	s_add_i32 s11, s2, s34
	s_lshl_b64 s[18:19], s[18:19], 2
	s_add_u32 s13, s35, s18
	s_addc_u32 s18, s38, s19
	s_lshl_b32 s2, s3, 8
	v_lshl_or_b32 v164, s3, 7, v172
	s_ashr_i32 s3, s2, 31
	s_lshl_b64 s[2:3], s[2:3], 2
	s_add_u32 s2, s13, s2
	s_addc_u32 s3, s18, s3
	v_or_b32_e32 v162, s11, v170
	s_add_u32 s2, s2, s44
	v_ashrrev_i32_e32 v163, 31, v162
	s_addc_u32 s3, s3, 0
	v_lshl_add_u64 v[162:163], v[162:163], 2, s[0:1]
	v_mov_b32_e32 v74, v234
	v_mov_b32_e32 v75, v235
	v_mov_b32_e32 v76, v236
	v_mov_b32_e32 v77, v237
	v_mov_b32_e32 v78, v238
	v_mov_b32_e32 v79, v239
	v_mov_b32_e32 v80, v240
	v_mov_b32_e32 v81, v241
	v_mov_b32_e32 v66, v242
	v_mov_b32_e32 v67, v243
	v_mov_b32_e32 v68, v244
	v_mov_b32_e32 v69, v245
	v_mov_b32_e32 v70, v246
	v_mov_b32_e32 v71, v247
	v_mov_b32_e32 v72, v248
	v_mov_b32_e32 v73, v249
	v_or_b32_e32 v180, s11, v1
	v_mov_b32_e32 v162, v250
	s_waitcnt vmcnt(0)
	v_fmamk_f32 v162, v162, 0x3a000000, v177
	v_cmp_gt_f32_e32 vcc, s45, v162
	v_mul_f32_e32 v163, 0x4f800000, v162
	s_nop 0
	v_cndmask_b32_e32 v162, v162, v163, vcc
	v_sqrt_f32_e32 v163, v162
	s_nop 0
	v_add_u32_e32 v165, -1, v163
	v_fma_f32 v166, -v165, v163, v162
	v_cmp_ge_f32_e64 s[2:3], 0, v166
	v_add_u32_e32 v166, 1, v163
	s_nop 0
	v_cndmask_b32_e64 v165, v163, v165, s[2:3]
	v_fma_f32 v163, -v166, v163, v162
	v_cmp_lt_f32_e64 s[2:3], 0, v163
	s_nop 1
	v_cndmask_b32_e64 v163, v165, v166, s[2:3]
	v_mul_f32_e32 v165, 0x37800000, v163
	v_cndmask_b32_e32 v163, v163, v165, vcc
	v_cmp_class_f32_e32 vcc, v162, v178
	s_nop 1
	v_cndmask_b32_e32 v166, v163, v162, vcc
	v_add_u32_e32 v162, s11, v171
	v_ashrrev_i32_e32 v163, 31, v162
	v_lshl_add_u64 v[162:163], v[162:163], 2, s[0:1]
	v_mov_b32_e32 v162, v251
	v_fmamk_f32 v162, v162, 0x3a000000, v177
	v_cmp_gt_f32_e32 vcc, s45, v162
	v_mul_f32_e32 v163, 0x4f800000, v162
	s_nop 0
	v_cndmask_b32_e32 v162, v162, v163, vcc
	v_sqrt_f32_e32 v163, v162
	s_nop 0
	v_add_u32_e32 v165, -1, v163
	v_fma_f32 v167, -v165, v163, v162
	v_cmp_ge_f32_e64 s[2:3], 0, v167
	v_add_u32_e32 v167, 1, v163
	s_nop 0
	v_cndmask_b32_e64 v165, v163, v165, s[2:3]
	v_fma_f32 v163, -v167, v163, v162
	v_cmp_lt_f32_e64 s[2:3], 0, v163
	s_nop 1
	v_cndmask_b32_e64 v163, v165, v167, s[2:3]
	v_mul_f32_e32 v165, 0x37800000, v163
	v_cndmask_b32_e32 v163, v163, v165, vcc
	v_cmp_class_f32_e32 vcc, v162, v178
	v_ashrrev_i32_e32 v165, 31, v164
	v_lshlrev_b64 v[164:165], 1, v[164:165]
	v_cndmask_b32_e32 v181, v163, v162, vcc
	v_div_scale_f32 v162, s[2:3], v166, v166, 1.0
	v_rcp_f32_e32 v163, v162
	s_nop 0
	v_fma_f32 v167, -v162, v163, 1.0
	v_fmac_f32_e32 v163, v167, v163
	v_div_scale_f32 v167, vcc, 1.0, v166, 1.0
	v_mul_f32_e32 v168, v167, v163
	v_fma_f32 v182, -v162, v168, v167
	v_fmac_f32_e32 v168, v182, v163
	v_fma_f32 v162, -v162, v168, v167
	v_div_fmas_f32 v162, v162, v163, v168
	v_div_fixup_f32 v182, v162, v166, 1.0
	s_andn2_b64 vcc, exec, s[8:9]
	s_cbranch_vccnz .Lalign_2919
	s_barrier
.Lalign_2919:
	s_mov_b32 s100, 0xbfb8aa3b
	ds_bpermute_b32 v242, v179, v182
	ds_bpermute_b32 v244, v179, v182 offset:64
	ds_bpermute_b32 v246, v179, v182 offset:128
	ds_bpermute_b32 v248, v179, v182 offset:192
	v_mov_b64_e32 v[162:163], s[96:97]
	v_mad_i64_i32 v[166:167], s[2:3], v180, s43, v[162:163]
	v_lshl_add_u64 v[166:167], v[166:167], 0, v[164:165]
	s_waitcnt lgkmcnt(0)
	v_pk_fma_f32 v[142:143], v[142:143], v[242:243], v[78:79] op_sel_hi:[1,0,1]
	v_pk_fma_f32 v[144:145], v[144:145], v[242:243], v[80:81] op_sel_hi:[1,0,1]
	v_pk_fma_f32 v[134:135], v[134:135], v[242:243], v[70:71] op_sel_hi:[1,0,1]
	v_pk_fma_f32 v[136:137], v[136:137], v[242:243], v[72:73] op_sel_hi:[1,0,1]
	v_pk_fma_f32 v[138:139], v[138:139], v[242:243], v[74:75] op_sel_hi:[1,0,1]
	v_pk_fma_f32 v[140:141], v[140:141], v[242:243], v[76:77] op_sel_hi:[1,0,1]
	v_pk_fma_f32 v[130:131], v[130:131], v[242:243], v[66:67] op_sel_hi:[1,0,1]
	v_pk_fma_f32 v[132:133], v[132:133], v[242:243], v[68:69] op_sel_hi:[1,0,1]
	v_pk_mul_f32 v[234:235], v[142:143], s[100:101] op_sel_hi:[1,0]
	v_pk_mul_f32 v[236:237], v[144:145], s[100:101] op_sel_hi:[1,0]
	v_exp_f32_e32 v234, v234
	v_exp_f32_e32 v235, v235
	v_exp_f32_e32 v236, v236
	v_exp_f32_e32 v237, v237
	v_pk_add_f32 v[234:235], v[234:235], 1.0 op_sel_hi:[1,0]
	v_pk_add_f32 v[236:237], v[236:237], 1.0 op_sel_hi:[1,0]
	v_rcp_f32_e32 v234, v234
	v_rcp_f32_e32 v235, v235
	v_rcp_f32_e32 v236, v236
	v_rcp_f32_e32 v237, v237
	v_pk_mul_f32 v[134:135], v[142:143], v[134:135]
	v_pk_mul_f32 v[136:137], v[144:145], v[136:137]
	v_pk_mul_f32 v[134:135], v[134:135], v[234:235]
	v_pk_mul_f32 v[136:137], v[136:137], v[236:237]
	v_cvt_pk_bf16_f32 v238, v134, v135
	v_cvt_pk_bf16_f32 v239, v136, v137
	v_pk_mul_f32 v[234:235], v[138:139], s[100:101] op_sel_hi:[1,0]
	v_pk_mul_f32 v[236:237], v[140:141], s[100:101] op_sel_hi:[1,0]
	v_exp_f32_e32 v234, v234
	v_exp_f32_e32 v235, v235
	v_exp_f32_e32 v236, v236
	v_exp_f32_e32 v237, v237
	v_pk_add_f32 v[234:235], v[234:235], 1.0 op_sel_hi:[1,0]
	v_pk_add_f32 v[236:237], v[236:237], 1.0 op_sel_hi:[1,0]
	v_rcp_f32_e32 v234, v234
	v_rcp_f32_e32 v235, v235
	v_rcp_f32_e32 v236, v236
	v_rcp_f32_e32 v237, v237
	v_pk_mul_f32 v[130:131], v[138:139], v[130:131]
	v_pk_mul_f32 v[132:133], v[140:141], v[132:133]
	v_pk_mul_f32 v[130:131], v[130:131], v[234:235]
	v_pk_mul_f32 v[132:133], v[132:133], v[236:237]
	v_cvt_pk_bf16_f32 v240, v130, v131
	v_cvt_pk_bf16_f32 v241, v132, v133
	global_store_dwordx4 v[166:167], v[238:241], off
	v_or_b32_e32 v131, 16, v180
	v_mad_i64_i32 v[132:133], s[2:3], v131, s43, v[162:163]
	v_lshl_add_u64 v[132:133], v[132:133], 0, v[164:165]
	v_pk_fma_f32 v[126:127], v[126:127], v[244:245], v[78:79] op_sel_hi:[1,0,1]
; __device__ __forceinline__ unsigned cvt_pk_bf16(float lo, float hi) { unsigned r; asm volatile("v_cvt_pk_bf16_f32 %0, %1, %2" : "=v"(r) : "v"(lo), "v"(hi)); return r; }
; __device__ __forceinline__ float silu_mul(float a, float b) { return a * b * __builtin_amdgcn_rcpf(1.0f + __builtin_amdgcn_exp2f(-a * LOG2E)); }
;     __device__ __forceinline__ void operator()(const f32x4 (&acc)[2][2][4][2], const Unit& u, int wr, int wc, int fr, int fq) const {
;     ...
;         for (int ai = 0; ai < 2; ++ai)
; #pragma unroll
;             for (int m = 0; m < 4; ++m) { const int row = row0 + ai * HALF + m * 16; const float rs = __shfl(ai ? rsl1 : rsl0, m * 16 + fr); bf16_t* rowp = O + (size_t)row * DFF + col0;
;                 const f32x4 a0 = acc[ai][0][m][0] * rs + ba0, a1 = acc[ai][0][m][1] * rs + ba1, b0 = acc[ai][1][m][0] * rs + bb0, b1 = acc[ai][1][m][1] * rs + bb1;
;                 u32x4 w; w.x = cvt_pk_bf16(silu_mul(a0[0], b0[0]), silu_mul(a0[1], b0[1])); w.y = cvt_pk_bf16(silu_mul(a0[2], b0[2]), silu_mul(a0[3], b0[3]));
;                 w.z = cvt_pk_bf16(silu_mul(a1[0], b1[0]), silu_mul(a1[1], b1[1])); w.w = cvt_pk_bf16(silu_mul(a1[2], b1[2]), silu_mul(a1[3], b1[3]));
;                 *(u32x4*)rowp = w; }
	v_pk_fma_f32 v[128:129], v[128:129], v[244:245], v[80:81] op_sel_hi:[1,0,1]
	v_pk_fma_f32 v[118:119], v[118:119], v[244:245], v[70:71] op_sel_hi:[1,0,1]
	v_pk_fma_f32 v[120:121], v[120:121], v[244:245], v[72:73] op_sel_hi:[1,0,1]
	v_pk_fma_f32 v[122:123], v[122:123], v[244:245], v[74:75] op_sel_hi:[1,0,1]
	v_pk_fma_f32 v[124:125], v[124:125], v[244:245], v[76:77] op_sel_hi:[1,0,1]
	v_pk_fma_f32 v[114:115], v[114:115], v[244:245], v[66:67] op_sel_hi:[1,0,1]
	v_pk_fma_f32 v[116:117], v[116:117], v[244:245], v[68:69] op_sel_hi:[1,0,1]
	v_pk_mul_f32 v[234:235], v[126:127], s[100:101] op_sel_hi:[1,0]
	v_pk_mul_f32 v[236:237], v[128:129], s[100:101] op_sel_hi:[1,0]
	v_exp_f32_e32 v234, v234
	v_exp_f32_e32 v235, v235
	v_exp_f32_e32 v236, v236
	v_exp_f32_e32 v237, v237
	v_pk_add_f32 v[234:235], v[234:235], 1.0 op_sel_hi:[1,0]
	v_pk_add_f32 v[236:237], v[236:237], 1.0 op_sel_hi:[1,0]
	v_rcp_f32_e32 v234, v234
	v_rcp_f32_e32 v235, v235
	v_rcp_f32_e32 v236, v236
	v_rcp_f32_e32 v237, v237
	v_pk_mul_f32 v[118:119], v[126:127], v[118:119]
	v_pk_mul_f32 v[120:121], v[128:129], v[120:121]
	v_pk_mul_f32 v[118:119], v[118:119], v[234:235]
	v_pk_mul_f32 v[120:121], v[120:121], v[236:237]
	v_cvt_pk_bf16_f32 v238, v118, v119
	v_cvt_pk_bf16_f32 v239, v120, v121
	v_pk_mul_f32 v[234:235], v[122:123], s[100:101] op_sel_hi:[1,0]
	v_pk_mul_f32 v[236:237], v[124:125], s[100:101] op_sel_hi:[1,0]
	v_exp_f32_e32 v234, v234
	v_exp_f32_e32 v235, v235
	v_exp_f32_e32 v236, v236
	v_exp_f32_e32 v237, v237
	v_pk_add_f32 v[234:235], v[234:235], 1.0 op_sel_hi:[1,0]
	v_pk_add_f32 v[236:237], v[236:237], 1.0 op_sel_hi:[1,0]
	v_rcp_f32_e32 v234, v234
	v_rcp_f32_e32 v235, v235
	v_rcp_f32_e32 v236, v236
	v_rcp_f32_e32 v237, v237
	v_pk_mul_f32 v[114:115], v[122:123], v[114:115]
	v_pk_mul_f32 v[116:117], v[124:125], v[116:117]
	v_pk_mul_f32 v[114:115], v[114:115], v[234:235]
	v_pk_mul_f32 v[116:117], v[116:117], v[236:237]
	v_cvt_pk_bf16_f32 v240, v114, v115
	v_cvt_pk_bf16_f32 v241, v116, v117
	global_store_dwordx4 v[132:133], v[238:241], off
	v_or_b32_e32 v115, 32, v180
	v_mad_i64_i32 v[116:117], s[2:3], v115, s43, v[162:163]
	v_lshl_add_u64 v[116:117], v[116:117], 0, v[164:165]
	v_pk_fma_f32 v[110:111], v[110:111], v[246:247], v[78:79] op_sel_hi:[1,0,1]
	v_pk_fma_f32 v[112:113], v[112:113], v[246:247], v[80:81] op_sel_hi:[1,0,1]
	v_pk_fma_f32 v[102:103], v[102:103], v[246:247], v[70:71] op_sel_hi:[1,0,1]
	v_pk_fma_f32 v[104:105], v[104:105], v[246:247], v[72:73] op_sel_hi:[1,0,1]
	v_pk_fma_f32 v[106:107], v[106:107], v[246:247], v[74:75] op_sel_hi:[1,0,1]
	v_pk_fma_f32 v[108:109], v[108:109], v[246:247], v[76:77] op_sel_hi:[1,0,1]
	v_pk_fma_f32 v[98:99], v[98:99], v[246:247], v[66:67] op_sel_hi:[1,0,1]
	v_pk_fma_f32 v[100:101], v[100:101], v[246:247], v[68:69] op_sel_hi:[1,0,1]
	v_pk_mul_f32 v[234:235], v[110:111], s[100:101] op_sel_hi:[1,0]
	v_pk_mul_f32 v[236:237], v[112:113], s[100:101] op_sel_hi:[1,0]
	v_exp_f32_e32 v234, v234
	v_exp_f32_e32 v235, v235
	v_exp_f32_e32 v236, v236
	v_exp_f32_e32 v237, v237
	v_pk_add_f32 v[234:235], v[234:235], 1.0 op_sel_hi:[1,0]
	v_pk_add_f32 v[236:237], v[236:237], 1.0 op_sel_hi:[1,0]
	v_rcp_f32_e32 v234, v234
	v_rcp_f32_e32 v235, v235
	v_rcp_f32_e32 v236, v236
	v_rcp_f32_e32 v237, v237
	v_pk_mul_f32 v[102:103], v[110:111], v[102:103]
	v_pk_mul_f32 v[104:105], v[112:113], v[104:105]
	v_pk_mul_f32 v[102:103], v[102:103], v[234:235]
	v_pk_mul_f32 v[104:105], v[104:105], v[236:237]
	v_cvt_pk_bf16_f32 v238, v102, v103
	v_cvt_pk_bf16_f32 v239, v104, v105
	v_pk_mul_f32 v[234:235], v[106:107], s[100:101] op_sel_hi:[1,0]
	v_pk_mul_f32 v[236:237], v[108:109], s[100:101] op_sel_hi:[1,0]
	v_exp_f32_e32 v234, v234
	v_exp_f32_e32 v235, v235
	v_exp_f32_e32 v236, v236
	v_exp_f32_e32 v237, v237
	v_pk_add_f32 v[234:235], v[234:235], 1.0 op_sel_hi:[1,0]
	v_pk_add_f32 v[236:237], v[236:237], 1.0 op_sel_hi:[1,0]
	v_rcp_f32_e32 v234, v234
	v_rcp_f32_e32 v235, v235
	v_rcp_f32_e32 v236, v236
	v_rcp_f32_e32 v237, v237
	v_pk_mul_f32 v[98:99], v[106:107], v[98:99]
	v_pk_mul_f32 v[100:101], v[108:109], v[100:101]
	v_pk_mul_f32 v[98:99], v[98:99], v[234:235]
	v_pk_mul_f32 v[100:101], v[100:101], v[236:237]
	v_cvt_pk_bf16_f32 v240, v98, v99
	v_cvt_pk_bf16_f32 v241, v100, v101
	global_store_dwordx4 v[116:117], v[238:241], off
	v_or_b32_e32 v99, 48, v180
	v_mad_i64_i32 v[100:101], s[2:3], v99, s43, v[162:163]
	v_lshl_add_u64 v[100:101], v[100:101], 0, v[164:165]
	v_pk_fma_f32 v[94:95], v[94:95], v[248:249], v[78:79] op_sel_hi:[1,0,1]
	v_pk_fma_f32 v[96:97], v[96:97], v[248:249], v[80:81] op_sel_hi:[1,0,1]
	v_pk_fma_f32 v[86:87], v[86:87], v[248:249], v[70:71] op_sel_hi:[1,0,1]
	v_pk_fma_f32 v[88:89], v[88:89], v[248:249], v[72:73] op_sel_hi:[1,0,1]
	v_pk_fma_f32 v[90:91], v[90:91], v[248:249], v[74:75] op_sel_hi:[1,0,1]
	v_pk_fma_f32 v[92:93], v[92:93], v[248:249], v[76:77] op_sel_hi:[1,0,1]
	v_pk_fma_f32 v[82:83], v[82:83], v[248:249], v[66:67] op_sel_hi:[1,0,1]
	v_pk_fma_f32 v[84:85], v[84:85], v[248:249], v[68:69] op_sel_hi:[1,0,1]
	v_pk_mul_f32 v[234:235], v[94:95], s[100:101] op_sel_hi:[1,0]
	v_pk_mul_f32 v[236:237], v[96:97], s[100:101] op_sel_hi:[1,0]
	v_exp_f32_e32 v234, v234
	v_exp_f32_e32 v235, v235
	v_exp_f32_e32 v236, v236
	v_exp_f32_e32 v237, v237
	v_pk_add_f32 v[234:235], v[234:235], 1.0 op_sel_hi:[1,0]
	v_pk_add_f32 v[236:237], v[236:237], 1.0 op_sel_hi:[1,0]
	v_rcp_f32_e32 v234, v234
	v_rcp_f32_e32 v235, v235
	v_rcp_f32_e32 v236, v236
	v_rcp_f32_e32 v237, v237
	v_pk_mul_f32 v[86:87], v[94:95], v[86:87]
	v_pk_mul_f32 v[88:89], v[96:97], v[88:89]
	v_pk_mul_f32 v[86:87], v[86:87], v[234:235]
	v_pk_mul_f32 v[88:89], v[88:89], v[236:237]
	v_cvt_pk_bf16_f32 v238, v86, v87
; __device__ __forceinline__ unsigned cvt_pk_bf16(float lo, float hi) { unsigned r; asm volatile("v_cvt_pk_bf16_f32 %0, %1, %2" : "=v"(r) : "v"(lo), "v"(hi)); return r; }
; __device__ __forceinline__ float row_rstd(const float* ss, int row) { return 1.0f / sqrtf(ss[row] * (1.0f / DM) + 1e-6f); }
; __device__ __forceinline__ float silu_mul(float a, float b) { return a * b * __builtin_amdgcn_rcpf(1.0f + __builtin_amdgcn_exp2f(-a * LOG2E)); }
;     __device__ __forceinline__ void operator()(const f32x4 (&acc)[2][2][4][2], const Unit& u, int wr, int wc, int fr, int fq) const {
;     ...
;         const float rsl0 = row_rstd(ss, u.pm * BM + wr * 64 + lane), rsl1 = row_rstd(ss, u.pm * BM + HALF + wr * 64 + lane);
;     ...
;         for (int ai = 0; ai < 2; ++ai)
; #pragma unroll
;             for (int m = 0; m < 4; ++m) { const int row = row0 + ai * HALF + m * 16; const float rs = __shfl(ai ? rsl1 : rsl0, m * 16 + fr); bf16_t* rowp = O + (size_t)row * DFF + col0;
;                 const f32x4 a0 = acc[ai][0][m][0] * rs + ba0, a1 = acc[ai][0][m][1] * rs + ba1, b0 = acc[ai][1][m][0] * rs + bb0, b1 = acc[ai][1][m][1] * rs + bb1;
;                 u32x4 w; w.x = cvt_pk_bf16(silu_mul(a0[0], b0[0]), silu_mul(a0[1], b0[1])); w.y = cvt_pk_bf16(silu_mul(a0[2], b0[2]), silu_mul(a0[3], b0[3]));
;                 w.z = cvt_pk_bf16(silu_mul(a1[0], b1[0]), silu_mul(a1[1], b1[1])); w.w = cvt_pk_bf16(silu_mul(a1[2], b1[2]), silu_mul(a1[3], b1[3]));
;                 *(u32x4*)rowp = w; }
	v_cvt_pk_bf16_f32 v239, v88, v89
	v_pk_mul_f32 v[234:235], v[90:91], s[100:101] op_sel_hi:[1,0]
	v_pk_mul_f32 v[236:237], v[92:93], s[100:101] op_sel_hi:[1,0]
	v_exp_f32_e32 v234, v234
	v_exp_f32_e32 v235, v235
	v_exp_f32_e32 v236, v236
	v_exp_f32_e32 v237, v237
	v_pk_add_f32 v[234:235], v[234:235], 1.0 op_sel_hi:[1,0]
	v_pk_add_f32 v[236:237], v[236:237], 1.0 op_sel_hi:[1,0]
	v_rcp_f32_e32 v234, v234
	v_rcp_f32_e32 v235, v235
	v_rcp_f32_e32 v236, v236
	v_rcp_f32_e32 v237, v237
	v_pk_mul_f32 v[82:83], v[90:91], v[82:83]
	v_pk_mul_f32 v[84:85], v[92:93], v[84:85]
	v_pk_mul_f32 v[82:83], v[82:83], v[234:235]
	v_pk_mul_f32 v[84:85], v[84:85], v[236:237]
	v_cvt_pk_bf16_f32 v240, v82, v83
	v_cvt_pk_bf16_f32 v241, v84, v85
	global_store_dwordx4 v[100:101], v[238:241], off
	s_nop 1
	v_div_scale_f32 v82, s[2:3], v181, v181, 1.0
	v_rcp_f32_e32 v84, v82
	v_add_u32_e32 v83, 0x80, v180
	v_fma_f32 v85, -v82, v84, 1.0
	v_fmac_f32_e32 v84, v85, v84
	v_div_scale_f32 v85, vcc, 1.0, v181, 1.0
	v_mul_f32_e32 v86, v85, v84
	v_fma_f32 v87, -v82, v86, v85
	v_fmac_f32_e32 v86, v87, v84
	v_fma_f32 v82, -v82, v86, v85
	v_div_fmas_f32 v82, v82, v84, v86
	v_div_fixup_f32 v82, v82, v181, 1.0
	ds_bpermute_b32 v242, v179, v82
	ds_bpermute_b32 v244, v179, v82 offset:64
	ds_bpermute_b32 v246, v179, v82 offset:128
	ds_bpermute_b32 v248, v179, v82 offset:192
	v_mad_i64_i32 v[86:87], s[2:3], v83, s43, v[162:163]
	v_lshl_add_u64 v[86:87], v[86:87], 0, v[164:165]
	s_and_b64 vcc, s[36:37], exec
	s_waitcnt lgkmcnt(0)
	v_pk_fma_f32 v[62:63], v[62:63], v[242:243], v[78:79] op_sel_hi:[1,0,1]
	v_pk_fma_f32 v[64:65], v[64:65], v[242:243], v[80:81] op_sel_hi:[1,0,1]
	v_pk_fma_f32 v[54:55], v[54:55], v[242:243], v[70:71] op_sel_hi:[1,0,1]
	v_pk_fma_f32 v[56:57], v[56:57], v[242:243], v[72:73] op_sel_hi:[1,0,1]
	v_pk_fma_f32 v[58:59], v[58:59], v[242:243], v[74:75] op_sel_hi:[1,0,1]
	v_pk_fma_f32 v[60:61], v[60:61], v[242:243], v[76:77] op_sel_hi:[1,0,1]
	v_pk_fma_f32 v[50:51], v[50:51], v[242:243], v[66:67] op_sel_hi:[1,0,1]
	v_pk_fma_f32 v[52:53], v[52:53], v[242:243], v[68:69] op_sel_hi:[1,0,1]
	v_pk_mul_f32 v[234:235], v[62:63], s[100:101] op_sel_hi:[1,0]
	v_pk_mul_f32 v[236:237], v[64:65], s[100:101] op_sel_hi:[1,0]
	v_exp_f32_e32 v234, v234
	v_exp_f32_e32 v235, v235
	v_exp_f32_e32 v236, v236
	v_exp_f32_e32 v237, v237
	v_pk_add_f32 v[234:235], v[234:235], 1.0 op_sel_hi:[1,0]
	v_pk_add_f32 v[236:237], v[236:237], 1.0 op_sel_hi:[1,0]
	v_rcp_f32_e32 v234, v234
	v_rcp_f32_e32 v235, v235
	v_rcp_f32_e32 v236, v236
	v_rcp_f32_e32 v237, v237
	v_pk_mul_f32 v[54:55], v[62:63], v[54:55]
	v_pk_mul_f32 v[56:57], v[64:65], v[56:57]
	v_pk_mul_f32 v[54:55], v[54:55], v[234:235]
	v_pk_mul_f32 v[56:57], v[56:57], v[236:237]
	v_cvt_pk_bf16_f32 v238, v54, v55
	v_cvt_pk_bf16_f32 v239, v56, v57
	v_pk_mul_f32 v[234:235], v[58:59], s[100:101] op_sel_hi:[1,0]
	v_pk_mul_f32 v[236:237], v[60:61], s[100:101] op_sel_hi:[1,0]
	v_exp_f32_e32 v234, v234
	v_exp_f32_e32 v235, v235
	v_exp_f32_e32 v236, v236
	v_exp_f32_e32 v237, v237
	v_pk_add_f32 v[234:235], v[234:235], 1.0 op_sel_hi:[1,0]
	v_pk_add_f32 v[236:237], v[236:237], 1.0 op_sel_hi:[1,0]
	v_rcp_f32_e32 v234, v234
	v_rcp_f32_e32 v235, v235
	v_rcp_f32_e32 v236, v236
	v_rcp_f32_e32 v237, v237
	v_pk_mul_f32 v[50:51], v[58:59], v[50:51]
	v_pk_mul_f32 v[52:53], v[60:61], v[52:53]
	v_pk_mul_f32 v[50:51], v[50:51], v[234:235]
	v_pk_mul_f32 v[52:53], v[52:53], v[236:237]
	v_cvt_pk_bf16_f32 v240, v50, v51
	v_cvt_pk_bf16_f32 v241, v52, v53
	global_store_dwordx4 v[86:87], v[238:241], off
	v_add_u32_e32 v51, 0x90, v180
	v_mad_i64_i32 v[52:53], s[2:3], v51, s43, v[162:163]
	v_lshl_add_u64 v[52:53], v[52:53], 0, v[164:165]
	v_pk_fma_f32 v[46:47], v[46:47], v[244:245], v[78:79] op_sel_hi:[1,0,1]
	v_pk_fma_f32 v[48:49], v[48:49], v[244:245], v[80:81] op_sel_hi:[1,0,1]
	v_pk_fma_f32 v[38:39], v[38:39], v[244:245], v[70:71] op_sel_hi:[1,0,1]
	v_pk_fma_f32 v[40:41], v[40:41], v[244:245], v[72:73] op_sel_hi:[1,0,1]
	v_pk_fma_f32 v[42:43], v[42:43], v[244:245], v[74:75] op_sel_hi:[1,0,1]
	v_pk_fma_f32 v[44:45], v[44:45], v[244:245], v[76:77] op_sel_hi:[1,0,1]
	v_pk_fma_f32 v[34:35], v[34:35], v[244:245], v[66:67] op_sel_hi:[1,0,1]
	v_pk_fma_f32 v[36:37], v[36:37], v[244:245], v[68:69] op_sel_hi:[1,0,1]
	v_pk_mul_f32 v[234:235], v[46:47], s[100:101] op_sel_hi:[1,0]
	v_pk_mul_f32 v[236:237], v[48:49], s[100:101] op_sel_hi:[1,0]
	v_exp_f32_e32 v234, v234
	v_exp_f32_e32 v235, v235
	v_exp_f32_e32 v236, v236
	v_exp_f32_e32 v237, v237
	v_pk_add_f32 v[234:235], v[234:235], 1.0 op_sel_hi:[1,0]
	v_pk_add_f32 v[236:237], v[236:237], 1.0 op_sel_hi:[1,0]
	v_rcp_f32_e32 v234, v234
	v_rcp_f32_e32 v235, v235
	v_rcp_f32_e32 v236, v236
	v_rcp_f32_e32 v237, v237
	v_pk_mul_f32 v[38:39], v[46:47], v[38:39]
	v_pk_mul_f32 v[40:41], v[48:49], v[40:41]
	v_pk_mul_f32 v[38:39], v[38:39], v[234:235]
	v_pk_mul_f32 v[40:41], v[40:41], v[236:237]
	v_cvt_pk_bf16_f32 v238, v38, v39
	v_cvt_pk_bf16_f32 v239, v40, v41
	v_pk_mul_f32 v[234:235], v[42:43], s[100:101] op_sel_hi:[1,0]
	v_pk_mul_f32 v[236:237], v[44:45], s[100:101] op_sel_hi:[1,0]
; __device__ __forceinline__ unsigned cvt_pk_bf16(float lo, float hi) { unsigned r; asm volatile("v_cvt_pk_bf16_f32 %0, %1, %2" : "=v"(r) : "v"(lo), "v"(hi)); return r; }
; __device__ __forceinline__ float silu_mul(float a, float b) { return a * b * __builtin_amdgcn_rcpf(1.0f + __builtin_amdgcn_exp2f(-a * LOG2E)); }
; #define PG8_BAR __builtin_amdgcn_s_barrier()
;     __device__ __forceinline__ void operator()(const f32x4 (&acc)[2][2][4][2], const Unit& u, int wr, int wc, int fr, int fq) const {
;     ...
;         for (int ai = 0; ai < 2; ++ai)
; #pragma unroll
;             for (int m = 0; m < 4; ++m) { const int row = row0 + ai * HALF + m * 16; const float rs = __shfl(ai ? rsl1 : rsl0, m * 16 + fr); bf16_t* rowp = O + (size_t)row * DFF + col0;
;                 const f32x4 a0 = acc[ai][0][m][0] * rs + ba0, a1 = acc[ai][0][m][1] * rs + ba1, b0 = acc[ai][1][m][0] * rs + bb0, b1 = acc[ai][1][m][1] * rs + bb1;
;                 u32x4 w; w.x = cvt_pk_bf16(silu_mul(a0[0], b0[0]), silu_mul(a0[1], b0[1])); w.y = cvt_pk_bf16(silu_mul(a0[2], b0[2]), silu_mul(a0[3], b0[3]));
;                 w.z = cvt_pk_bf16(silu_mul(a1[0], b1[0]), silu_mul(a1[1], b1[1])); w.w = cvt_pk_bf16(silu_mul(a1[2], b1[2]), silu_mul(a1[3], b1[3]));
;                 *(u32x4*)rowp = w; }
; template <class Epi, class Sched, bool ALIGN_EPI = false, bool SP2 = false>
; __device__ __forceinline__ void gemm_phase(LAS unsigned char* lds, const Gemm g, const Sched& S, const Epi& E) {
;     ...
;         if (!has_next) break;
; #pragma unroll
;         for (int a = 0; a < 2; ++a)
; #pragma unroll
;             for (int b = 0; b < 2; ++b)
; #pragma unroll
;                 for (int m = 0; m < 4; ++m)
; #pragma unroll
;                     for (int n = 0; n < 2; ++n) acc[a][b][m][n] = (f32x4){0.f, 0.f, 0.f, 0.f};
;         cur = nxt; cA = nA; cB = nB; ++ui;
;         if constexpr (ALIGN_EPI) { if (wr == 1) PG8_BAR; }
	v_exp_f32_e32 v234, v234
	v_exp_f32_e32 v235, v235
	v_exp_f32_e32 v236, v236
	v_exp_f32_e32 v237, v237
	v_pk_add_f32 v[234:235], v[234:235], 1.0 op_sel_hi:[1,0]
	v_pk_add_f32 v[236:237], v[236:237], 1.0 op_sel_hi:[1,0]
	v_rcp_f32_e32 v234, v234
	v_rcp_f32_e32 v235, v235
	v_rcp_f32_e32 v236, v236
	v_rcp_f32_e32 v237, v237
	v_pk_mul_f32 v[34:35], v[42:43], v[34:35]
	v_pk_mul_f32 v[36:37], v[44:45], v[36:37]
	v_pk_mul_f32 v[34:35], v[34:35], v[234:235]
	v_pk_mul_f32 v[36:37], v[36:37], v[236:237]
	v_cvt_pk_bf16_f32 v240, v34, v35
	v_cvt_pk_bf16_f32 v241, v36, v37
	global_store_dwordx4 v[52:53], v[238:241], off
	v_add_u32_e32 v35, 0xa0, v180
	v_mad_i64_i32 v[36:37], s[2:3], v35, s43, v[162:163]
	v_lshl_add_u64 v[36:37], v[36:37], 0, v[164:165]
	v_pk_fma_f32 v[30:31], v[30:31], v[246:247], v[78:79] op_sel_hi:[1,0,1]
	v_pk_fma_f32 v[32:33], v[32:33], v[246:247], v[80:81] op_sel_hi:[1,0,1]
	v_pk_fma_f32 v[22:23], v[22:23], v[246:247], v[70:71] op_sel_hi:[1,0,1]
	v_pk_fma_f32 v[24:25], v[24:25], v[246:247], v[72:73] op_sel_hi:[1,0,1]
	v_pk_fma_f32 v[26:27], v[26:27], v[246:247], v[74:75] op_sel_hi:[1,0,1]
	v_pk_fma_f32 v[28:29], v[28:29], v[246:247], v[76:77] op_sel_hi:[1,0,1]
	v_pk_fma_f32 v[18:19], v[18:19], v[246:247], v[66:67] op_sel_hi:[1,0,1]
	v_pk_fma_f32 v[20:21], v[20:21], v[246:247], v[68:69] op_sel_hi:[1,0,1]
	v_pk_mul_f32 v[234:235], v[30:31], s[100:101] op_sel_hi:[1,0]
	v_pk_mul_f32 v[236:237], v[32:33], s[100:101] op_sel_hi:[1,0]
	v_exp_f32_e32 v234, v234
	v_exp_f32_e32 v235, v235
	v_exp_f32_e32 v236, v236
	v_exp_f32_e32 v237, v237
	v_pk_add_f32 v[234:235], v[234:235], 1.0 op_sel_hi:[1,0]
	v_pk_add_f32 v[236:237], v[236:237], 1.0 op_sel_hi:[1,0]
	v_rcp_f32_e32 v234, v234
	v_rcp_f32_e32 v235, v235
	v_rcp_f32_e32 v236, v236
	v_rcp_f32_e32 v237, v237
	v_pk_mul_f32 v[22:23], v[30:31], v[22:23]
	v_pk_mul_f32 v[24:25], v[32:33], v[24:25]
	v_pk_mul_f32 v[22:23], v[22:23], v[234:235]
	v_pk_mul_f32 v[24:25], v[24:25], v[236:237]
	v_cvt_pk_bf16_f32 v238, v22, v23
	v_cvt_pk_bf16_f32 v239, v24, v25
	v_pk_mul_f32 v[234:235], v[26:27], s[100:101] op_sel_hi:[1,0]
	v_pk_mul_f32 v[236:237], v[28:29], s[100:101] op_sel_hi:[1,0]
	v_exp_f32_e32 v234, v234
	v_exp_f32_e32 v235, v235
	v_exp_f32_e32 v236, v236
	v_exp_f32_e32 v237, v237
	v_pk_add_f32 v[234:235], v[234:235], 1.0 op_sel_hi:[1,0]
	v_pk_add_f32 v[236:237], v[236:237], 1.0 op_sel_hi:[1,0]
	v_rcp_f32_e32 v234, v234
	v_rcp_f32_e32 v235, v235
	v_rcp_f32_e32 v236, v236
	v_rcp_f32_e32 v237, v237
	v_pk_mul_f32 v[18:19], v[26:27], v[18:19]
	v_pk_mul_f32 v[20:21], v[28:29], v[20:21]
	v_pk_mul_f32 v[18:19], v[18:19], v[234:235]
	v_pk_mul_f32 v[20:21], v[20:21], v[236:237]
	v_cvt_pk_bf16_f32 v240, v18, v19
	v_cvt_pk_bf16_f32 v241, v20, v21
	global_store_dwordx4 v[36:37], v[238:241], off
	v_add_u32_e32 v19, 0xb0, v180
	v_mad_i64_i32 v[20:21], s[2:3], v19, s43, v[162:163]
	v_lshl_add_u64 v[20:21], v[20:21], 0, v[164:165]
	s_mov_b64 s[2:3], -1
	v_pk_fma_f32 v[14:15], v[14:15], v[248:249], v[78:79] op_sel_hi:[1,0,1]
	v_pk_fma_f32 v[16:17], v[16:17], v[248:249], v[80:81] op_sel_hi:[1,0,1]
	v_pk_fma_f32 v[6:7], v[6:7], v[248:249], v[70:71] op_sel_hi:[1,0,1]
	v_pk_fma_f32 v[8:9], v[8:9], v[248:249], v[72:73] op_sel_hi:[1,0,1]
	v_pk_fma_f32 v[10:11], v[10:11], v[248:249], v[74:75] op_sel_hi:[1,0,1]
	v_pk_fma_f32 v[12:13], v[12:13], v[248:249], v[76:77] op_sel_hi:[1,0,1]
	v_pk_fma_f32 v[2:3], v[2:3], v[248:249], v[66:67] op_sel_hi:[1,0,1]
	v_pk_fma_f32 v[4:5], v[4:5], v[248:249], v[68:69] op_sel_hi:[1,0,1]
	v_pk_mul_f32 v[234:235], v[14:15], s[100:101] op_sel_hi:[1,0]
	v_pk_mul_f32 v[236:237], v[16:17], s[100:101] op_sel_hi:[1,0]
	v_exp_f32_e32 v234, v234
	v_exp_f32_e32 v235, v235
	v_exp_f32_e32 v236, v236
	v_exp_f32_e32 v237, v237
	v_pk_add_f32 v[234:235], v[234:235], 1.0 op_sel_hi:[1,0]
	v_pk_add_f32 v[236:237], v[236:237], 1.0 op_sel_hi:[1,0]
	v_rcp_f32_e32 v234, v234
	v_rcp_f32_e32 v235, v235
	v_rcp_f32_e32 v236, v236
	v_rcp_f32_e32 v237, v237
	v_pk_mul_f32 v[6:7], v[14:15], v[6:7]
	v_pk_mul_f32 v[8:9], v[16:17], v[8:9]
	v_pk_mul_f32 v[6:7], v[6:7], v[234:235]
	v_pk_mul_f32 v[8:9], v[8:9], v[236:237]
	v_cvt_pk_bf16_f32 v238, v6, v7
	v_cvt_pk_bf16_f32 v239, v8, v9
	v_pk_mul_f32 v[234:235], v[10:11], s[100:101] op_sel_hi:[1,0]
	v_pk_mul_f32 v[236:237], v[12:13], s[100:101] op_sel_hi:[1,0]
	v_exp_f32_e32 v234, v234
	v_exp_f32_e32 v235, v235
	v_exp_f32_e32 v236, v236
	v_exp_f32_e32 v237, v237
	v_pk_add_f32 v[234:235], v[234:235], 1.0 op_sel_hi:[1,0]
	v_pk_add_f32 v[236:237], v[236:237], 1.0 op_sel_hi:[1,0]
	v_rcp_f32_e32 v234, v234
	v_rcp_f32_e32 v235, v235
	v_rcp_f32_e32 v236, v236
	v_rcp_f32_e32 v237, v237
	v_pk_mul_f32 v[2:3], v[10:11], v[2:3]
	v_pk_mul_f32 v[4:5], v[12:13], v[4:5]
	v_pk_mul_f32 v[2:3], v[2:3], v[234:235]
	v_pk_mul_f32 v[4:5], v[4:5], v[236:237]
	v_cvt_pk_bf16_f32 v240, v2, v3
	v_cvt_pk_bf16_f32 v241, v4, v5
	global_store_dwordx4 v[20:21], v[238:241], off
	s_cbranch_vccz .LBB0_2912
	s_andn2_b64 vcc, exec, s[4:5]
	s_cbranch_vccnz .LBB0_2911
	s_barrier
	s_branch .LBB0_2911
